# GEMM k-loops: A operand triple-buffered in registers (A(k+3) loaded at end of step k: two k-steps of latency tolerance instead of one), single vmcnt wait per step
# speedup vs baseline: 1.0051x; 1.0051x over previous
.LBB0_215:
	s_mul_hi_i32 s0, s8, 0x2aaaaaab
	s_lshr_b32 s1, s0, 31
	s_ashr_i32 s0, s0, 5
	s_add_i32 s0, s0, s1
	s_lshl_b32 s1, s0, 3
	s_sub_i32 s2, 17, s1
	s_min_u32 s2, s2, 8
	v_cvt_f32_ubyte0_e32 v0, s2
	v_rcp_iflag_f32_e32 v0, v0
	s_sub_i32 s5, 0, s2
	s_mulk_i32 s0, 0xff40
	s_add_i32 s3, s0, s8
	v_mul_f32_e32 v0, 0x4f7ffffe, v0
	v_cvt_u32_f32_e32 v0, v0
	s_abs_i32 s4, s3
	s_ashr_i32 s0, s3, 31
	v_mov_b32_e32 v181, v179
	v_readfirstlane_b32 s6, v0
	s_mul_i32 s5, s5, s6
	s_mul_hi_u32 s5, s6, s5
	s_add_i32 s6, s6, s5
	s_mul_hi_u32 s5, s4, s6
	s_mul_i32 s6, s5, s2
	s_sub_i32 s4, s4, s6
	s_add_i32 s6, s5, 1
	s_sub_i32 s7, s4, s2
	s_cmp_ge_u32 s4, s2
	s_cselect_b32 s5, s6, s5
	s_cselect_b32 s4, s7, s4
	s_add_i32 s6, s5, 1
	s_cmp_ge_u32 s4, s2
	s_cselect_b32 s4, s6, s5
	s_xor_b32 s4, s4, s0
	s_sub_i32 s0, s4, s0
	s_mul_i32 s2, s2, s0
	s_sub_i32 s2, s3, s2
	s_add_i32 s1, s1, s11
	s_add_i32 s2, s1, s2
	v_ashrrev_i32_e32 v233, 6, v181
	v_lshlrev_b32_e32 v0, 1, v233
	v_lshl_add_u32 v0, s2, 3, v0
	v_ashrrev_i32_e32 v1, 31, v0
	v_bfe_u32 v183, v181, 5, 1
	v_lshlrev_b64 v[0:1], 16, v[0:1]
	v_and_b32_e32 v231, 31, v181
	v_lshl_add_u64 v[0:1], s[64:65], 0, v[0:1]
	v_lshlrev_b32_e32 v176, 9, v183
	s_ashr_i32 s1, s0, 31
	v_lshl_add_u64 v[0:1], v[0:1], 0, v[176:177]
	v_lshlrev_b32_e32 v176, 4, v231
	v_ashrrev_i32_e32 v12, 2, v181
	s_lshl_b64 s[4:5], s[0:1], 18
	v_lshl_add_u64 v[184:185], v[0:1], 0, v[176:177]
	s_add_u32 s4, s9, s4
	v_lshlrev_b32_e32 v0, 5, v12
	s_addc_u32 s5, s10, s5
	v_ashrrev_i32_e32 v1, 31, v0
	v_lshlrev_b32_e32 v2, 4, v181
	v_lshl_add_u64 v[0:1], v[0:1], 1, s[4:5]
	v_and_b32_e32 v176, 48, v2
	v_lshl_add_u64 v[186:187], v[0:1], 0, v[176:177]
	s_movk_i32 s1, 0x2000
	v_add_co_u32_e32 v8, vcc, s1, v186
	v_mul_u32_u24_e32 v10, 40, v231
	s_nop 0
	v_addc_co_u32_e32 v9, vcc, 0, v187, vcc
	v_lshlrev_b32_e32 v11, 4, v183
	v_lshl_add_u32 v235, v10, 1, v11
	v_add_co_u32_e32 v10, vcc, s41, v184
	s_movk_i32 s3, 0x50
	s_nop 0
	v_addc_co_u32_e32 v11, vcc, 0, v185, vcc
	v_and_b32_e32 v232, 63, v181
	v_lshlrev_b32_e32 v234, 3, v181
	v_bfe_u32 v197, v181, 4, 2
	v_lshlrev_b32_e32 v197, 1, v197
	v_mov_b32_e32 v176, 0x78
	v_lshrrev_b32_e32 v197, v197, v176
	v_and_b32_e32 v197, 3, v197
	v_and_b32_e32 v196, 3, v181
	v_xor_b32_e32 v197, v197, v196
	v_lshlrev_b32_e32 v197, 4, v197
	v_and_b32_e32 v188, 0xffffffcf, v186
	v_or_b32_e32 v188, v188, v197
	v_mov_b32_e32 v189, v187
	v_lshrrev_b32_e32 v176, 6, v181
	v_lshlrev_b32_e32 v197, 11, v176
	v_lshlrev_b32_e32 v176, 10, v176
	v_lshl_add_u64 v[188:189], v[188:189], 0, v[176:177]
	v_readfirstlane_b32 vcc_lo, v197
	v_bfe_u32 v197, v181, 4, 1
	v_lshlrev_b32_e32 v176, 9, v183
	v_lshl_add_u32 v176, v197, 8, v176
	v_lshl_add_u64 v[184:185], v[184:185], 0, v[176:177]
	v_mov_b32_e32 v176, s41
	v_lshl_add_u64 v[186:187], v[184:185], 0, v[176:177]
	v_mov_b32_e32 v176, 0x78
	v_bfe_u32 v197, v181, 2, 2
	v_lshlrev_b32_e32 v197, 1, v197
	v_lshrrev_b32_e32 v197, v197, v176
	v_and_b32_e32 v197, 3, v197
	v_bfe_u32 v196, v181, 4, 2
	v_xor_b32_e32 v197, v197, v196
	v_lshlrev_b32_e32 v197, 4, v197
	v_and_b32_e32 v196, 15, v181
	v_lshl_add_u32 v196, v196, 6, v197
	s_mov_b32 s96, 0
	s_mov_b32 m0, vcc_lo
	v_lshl_add_u64 v[198:199], v[188:189], 0, s[96:97]
	global_load_lds_dwordx4 v[198:199], off
	global_load_lds_dwordx4 v[198:199], off offset:1024
	s_mov_b32 s96, 0
	v_lshl_add_u64 v[198:199], v[184:185], 0, s[96:97]
	v_lshl_add_u64 v[200:201], v[186:187], 0, s[96:97]
	global_load_dwordx4 v[128:131], v[198:199], off
	global_load_dwordx4 v[132:135], v[198:199], off offset:256
	global_load_dwordx4 v[136:139], v[200:201], off
	global_load_dwordx4 v[140:143], v[200:201], off offset:256
	s_movk_i32 s96, 0x800
	v_lshl_add_u64 v[198:199], v[184:185], 0, s[96:97]
	v_lshl_add_u64 v[200:201], v[186:187], 0, s[96:97]
	global_load_dwordx4 v[144:147], v[198:199], off
	global_load_dwordx4 v[148:151], v[198:199], off offset:256
	global_load_dwordx4 v[152:155], v[200:201], off
	global_load_dwordx4 v[156:159], v[200:201], off offset:256
	s_movk_i32 s96, 0x2000
	s_add_i32 m0, vcc_lo, 8192
	v_lshl_add_u64 v[198:199], v[188:189], 0, s[96:97]
	global_load_lds_dwordx4 v[198:199], off
	global_load_lds_dwordx4 v[198:199], off offset:1024
	s_movk_i32 s96, 0x1000
	v_lshl_add_u64 v[198:199], v[184:185], 0, s[96:97]
	v_lshl_add_u64 v[200:201], v[186:187], 0, s[96:97]
	global_load_dwordx4 v[160:163], v[198:199], off
	global_load_dwordx4 v[164:167], v[198:199], off offset:256
	global_load_dwordx4 v[168:171], v[200:201], off
	global_load_dwordx4 v[172:175], v[200:201], off offset:256
	v_mov_b32_e32 v0, 0
	v_mov_b32_e32 v1, 0
	v_mov_b32_e32 v2, 0
	v_mov_b32_e32 v3, 0
	v_mov_b32_e32 v4, 0
	v_mov_b32_e32 v5, 0
	v_mov_b32_e32 v6, 0
	v_mov_b32_e32 v7, 0
	v_mov_b32_e32 v8, 0
	v_mov_b32_e32 v9, 0
	v_mov_b32_e32 v10, 0
	v_mov_b32_e32 v11, 0
	v_mov_b32_e32 v12, 0
	v_mov_b32_e32 v13, 0
	v_mov_b32_e32 v14, 0
	v_mov_b32_e32 v15, 0
	v_mov_b32_e32 v16, 0
	v_mov_b32_e32 v17, 0
	v_mov_b32_e32 v18, 0
	v_mov_b32_e32 v19, 0
	v_mov_b32_e32 v20, 0
	v_mov_b32_e32 v21, 0
	v_mov_b32_e32 v22, 0
	v_mov_b32_e32 v23, 0
	v_mov_b32_e32 v24, 0
	v_mov_b32_e32 v25, 0
	v_mov_b32_e32 v26, 0
	v_mov_b32_e32 v27, 0
	v_mov_b32_e32 v28, 0
	v_mov_b32_e32 v29, 0
	v_mov_b32_e32 v30, 0
	v_mov_b32_e32 v31, 0
	v_mov_b32_e32 v32, 0
	v_mov_b32_e32 v33, 0
	v_mov_b32_e32 v34, 0
	v_mov_b32_e32 v35, 0
	v_mov_b32_e32 v36, 0
	v_mov_b32_e32 v37, 0
	v_mov_b32_e32 v38, 0
	v_mov_b32_e32 v39, 0
	v_mov_b32_e32 v40, 0
	v_mov_b32_e32 v41, 0
	v_mov_b32_e32 v42, 0
	v_mov_b32_e32 v43, 0
	v_mov_b32_e32 v44, 0
	v_mov_b32_e32 v45, 0
	v_mov_b32_e32 v46, 0
	v_mov_b32_e32 v47, 0
	v_mov_b32_e32 v48, 0
	v_mov_b32_e32 v49, 0
	v_mov_b32_e32 v50, 0
	v_mov_b32_e32 v51, 0
	v_mov_b32_e32 v52, 0
	v_mov_b32_e32 v53, 0
	v_mov_b32_e32 v54, 0
	v_mov_b32_e32 v55, 0
	v_mov_b32_e32 v56, 0
	v_mov_b32_e32 v57, 0
	v_mov_b32_e32 v58, 0
	v_mov_b32_e32 v59, 0
	v_mov_b32_e32 v60, 0
	v_mov_b32_e32 v61, 0
	v_mov_b32_e32 v62, 0
	v_mov_b32_e32 v63, 0
	v_mov_b32_e32 v64, 0
	v_mov_b32_e32 v65, 0
	v_mov_b32_e32 v66, 0
	v_mov_b32_e32 v67, 0
	v_mov_b32_e32 v68, 0
	v_mov_b32_e32 v69, 0
	v_mov_b32_e32 v70, 0
	v_mov_b32_e32 v71, 0
	v_mov_b32_e32 v72, 0
	v_mov_b32_e32 v73, 0
	v_mov_b32_e32 v74, 0
	v_mov_b32_e32 v75, 0
	v_mov_b32_e32 v76, 0
	v_mov_b32_e32 v77, 0
	v_mov_b32_e32 v78, 0
	v_mov_b32_e32 v79, 0
	v_mov_b32_e32 v80, 0
	v_mov_b32_e32 v81, 0
	v_mov_b32_e32 v82, 0
	v_mov_b32_e32 v83, 0
	v_mov_b32_e32 v84, 0
	v_mov_b32_e32 v85, 0
	v_mov_b32_e32 v86, 0
	v_mov_b32_e32 v87, 0
	v_mov_b32_e32 v88, 0
	v_mov_b32_e32 v89, 0
	v_mov_b32_e32 v90, 0
	v_mov_b32_e32 v91, 0
	v_mov_b32_e32 v92, 0
	v_mov_b32_e32 v93, 0
	v_mov_b32_e32 v94, 0
	v_mov_b32_e32 v95, 0
	v_mov_b32_e32 v96, 0
	v_mov_b32_e32 v97, 0
	v_mov_b32_e32 v98, 0
	v_mov_b32_e32 v99, 0
	v_mov_b32_e32 v100, 0
	v_mov_b32_e32 v101, 0
	v_mov_b32_e32 v102, 0
	v_mov_b32_e32 v103, 0
	v_mov_b32_e32 v104, 0
	v_mov_b32_e32 v105, 0
	v_mov_b32_e32 v106, 0
	v_mov_b32_e32 v107, 0
	v_mov_b32_e32 v108, 0
	v_mov_b32_e32 v109, 0
	v_mov_b32_e32 v110, 0
	v_mov_b32_e32 v111, 0
	v_mov_b32_e32 v112, 0
	v_mov_b32_e32 v113, 0
	v_mov_b32_e32 v114, 0
	v_mov_b32_e32 v115, 0
	v_mov_b32_e32 v116, 0
	v_mov_b32_e32 v117, 0
	v_mov_b32_e32 v118, 0
	v_mov_b32_e32 v119, 0
	v_mov_b32_e32 v120, 0
	v_mov_b32_e32 v121, 0
	v_mov_b32_e32 v122, 0
	v_mov_b32_e32 v123, 0
	v_mov_b32_e32 v124, 0
	v_mov_b32_e32 v125, 0
	v_mov_b32_e32 v126, 0
	v_mov_b32_e32 v127, 0
	s_mov_b32 s1, 0
	s_waitcnt vmcnt(10)
	s_barrier
.Lg16_proj_k:
	s_add_i32 s3, s1, 2
	s_lshl_b32 s96, s3, 13
	s_add_i32 m0, vcc_lo, 16384
	v_lshl_add_u64 v[198:199], v[188:189], 0, s[96:97]
	global_load_lds_dwordx4 v[198:199], off
	global_load_lds_dwordx4 v[198:199], off offset:1024
	ds_read_b128 v[236:239], v196 offset:0
	ds_read_b128 v[240:243], v196 offset:1024
	ds_read_b128 v[244:247], v196 offset:2048
	ds_read_b128 v[248:251], v196 offset:3072
	s_add_i32 s3, s1, 3
	s_min_u32 s3, s3, 31
	s_lshl_b32 s96, s3, 11
	v_lshl_add_u64 v[198:199], v[184:185], 0, s[96:97]
	v_lshl_add_u64 v[200:201], v[186:187], 0, s[96:97]
	s_waitcnt lgkmcnt(3)
	v_mfma_f32_16x16x32_bf16 v[16:19], v[128:131], v[236:239], v[16:19]
	v_mfma_f32_16x16x32_bf16 v[24:27], v[132:135], v[236:239], v[24:27]
	v_mfma_f32_16x16x32_bf16 v[0:3], v[136:139], v[236:239], v[0:3]
	v_mfma_f32_16x16x32_bf16 v[8:11], v[140:143], v[236:239], v[8:11]
	ds_read_b128 v[236:239], v196 offset:4096
	s_waitcnt lgkmcnt(3)
	v_mfma_f32_16x16x32_bf16 v[20:23], v[128:131], v[240:243], v[20:23]
	v_mfma_f32_16x16x32_bf16 v[28:31], v[132:135], v[240:243], v[28:31]
	v_mfma_f32_16x16x32_bf16 v[4:7], v[136:139], v[240:243], v[4:7]
	v_mfma_f32_16x16x32_bf16 v[12:15], v[140:143], v[240:243], v[12:15]
	ds_read_b128 v[240:243], v196 offset:5120
	s_waitcnt lgkmcnt(3)
	v_mfma_f32_16x16x32_bf16 v[112:115], v[128:131], v[244:247], v[112:115]
	v_mfma_f32_16x16x32_bf16 v[120:123], v[132:135], v[244:247], v[120:123]
	v_mfma_f32_16x16x32_bf16 v[96:99], v[136:139], v[244:247], v[96:99]
	v_mfma_f32_16x16x32_bf16 v[104:107], v[140:143], v[244:247], v[104:107]
	ds_read_b128 v[244:247], v196 offset:6144
	s_waitcnt lgkmcnt(3)
	v_mfma_f32_16x16x32_bf16 v[116:119], v[128:131], v[248:251], v[116:119]
	v_mfma_f32_16x16x32_bf16 v[124:127], v[132:135], v[248:251], v[124:127]
	v_mfma_f32_16x16x32_bf16 v[100:103], v[136:139], v[248:251], v[100:103]
	v_mfma_f32_16x16x32_bf16 v[108:111], v[140:143], v[248:251], v[108:111]
	ds_read_b128 v[248:251], v196 offset:7168
	s_waitcnt lgkmcnt(3)
	v_mfma_f32_16x16x32_bf16 v[80:83], v[128:131], v[236:239], v[80:83]
	v_mfma_f32_16x16x32_bf16 v[88:91], v[132:135], v[236:239], v[88:91]
	v_mfma_f32_16x16x32_bf16 v[48:51], v[136:139], v[236:239], v[48:51]
	v_mfma_f32_16x16x32_bf16 v[56:59], v[140:143], v[236:239], v[56:59]
	s_waitcnt lgkmcnt(2)
	v_mfma_f32_16x16x32_bf16 v[84:87], v[128:131], v[240:243], v[84:87]
	v_mfma_f32_16x16x32_bf16 v[92:95], v[132:135], v[240:243], v[92:95]
	v_mfma_f32_16x16x32_bf16 v[52:55], v[136:139], v[240:243], v[52:55]
	v_mfma_f32_16x16x32_bf16 v[60:63], v[140:143], v[240:243], v[60:63]
	s_waitcnt lgkmcnt(1)
	v_mfma_f32_16x16x32_bf16 v[64:67], v[128:131], v[244:247], v[64:67]
	v_mfma_f32_16x16x32_bf16 v[72:75], v[132:135], v[244:247], v[72:75]
	v_mfma_f32_16x16x32_bf16 v[32:35], v[136:139], v[244:247], v[32:35]
	v_mfma_f32_16x16x32_bf16 v[40:43], v[140:143], v[244:247], v[40:43]
	s_waitcnt lgkmcnt(0)
	v_mfma_f32_16x16x32_bf16 v[68:71], v[128:131], v[248:251], v[68:71]
	v_mfma_f32_16x16x32_bf16 v[76:79], v[132:135], v[248:251], v[76:79]
	v_mfma_f32_16x16x32_bf16 v[36:39], v[136:139], v[248:251], v[36:39]
	v_mfma_f32_16x16x32_bf16 v[44:47], v[140:143], v[248:251], v[44:47]
	global_load_dwordx4 v[128:131], v[198:199], off
	global_load_dwordx4 v[132:135], v[198:199], off offset:256
	global_load_dwordx4 v[136:139], v[200:201], off
	global_load_dwordx4 v[140:143], v[200:201], off offset:256
	s_waitcnt vmcnt(10)
	s_barrier
	s_add_i32 s3, s1, 3
	s_lshl_b32 s96, s3, 13
	s_mov_b32 m0, vcc_lo
	v_lshl_add_u64 v[198:199], v[188:189], 0, s[96:97]
	global_load_lds_dwordx4 v[198:199], off
	global_load_lds_dwordx4 v[198:199], off offset:1024
	ds_read_b128 v[236:239], v196 offset:8192
	ds_read_b128 v[240:243], v196 offset:9216
	ds_read_b128 v[244:247], v196 offset:10240
	ds_read_b128 v[248:251], v196 offset:11264
	s_add_i32 s3, s1, 4
	s_min_u32 s3, s3, 31
	s_lshl_b32 s96, s3, 11
	v_lshl_add_u64 v[198:199], v[184:185], 0, s[96:97]
	v_lshl_add_u64 v[200:201], v[186:187], 0, s[96:97]
	s_waitcnt lgkmcnt(3)
	v_mfma_f32_16x16x32_bf16 v[16:19], v[144:147], v[236:239], v[16:19]
	v_mfma_f32_16x16x32_bf16 v[24:27], v[148:151], v[236:239], v[24:27]
	v_mfma_f32_16x16x32_bf16 v[0:3], v[152:155], v[236:239], v[0:3]
	v_mfma_f32_16x16x32_bf16 v[8:11], v[156:159], v[236:239], v[8:11]
	ds_read_b128 v[236:239], v196 offset:12288
	s_waitcnt lgkmcnt(3)
	v_mfma_f32_16x16x32_bf16 v[20:23], v[144:147], v[240:243], v[20:23]
	v_mfma_f32_16x16x32_bf16 v[28:31], v[148:151], v[240:243], v[28:31]
	v_mfma_f32_16x16x32_bf16 v[4:7], v[152:155], v[240:243], v[4:7]
	v_mfma_f32_16x16x32_bf16 v[12:15], v[156:159], v[240:243], v[12:15]
	ds_read_b128 v[240:243], v196 offset:13312
	s_waitcnt lgkmcnt(3)
	v_mfma_f32_16x16x32_bf16 v[112:115], v[144:147], v[244:247], v[112:115]
	v_mfma_f32_16x16x32_bf16 v[120:123], v[148:151], v[244:247], v[120:123]
	v_mfma_f32_16x16x32_bf16 v[96:99], v[152:155], v[244:247], v[96:99]
	v_mfma_f32_16x16x32_bf16 v[104:107], v[156:159], v[244:247], v[104:107]
	ds_read_b128 v[244:247], v196 offset:14336
	s_waitcnt lgkmcnt(3)
	v_mfma_f32_16x16x32_bf16 v[116:119], v[144:147], v[248:251], v[116:119]
	v_mfma_f32_16x16x32_bf16 v[124:127], v[148:151], v[248:251], v[124:127]
	v_mfma_f32_16x16x32_bf16 v[100:103], v[152:155], v[248:251], v[100:103]
	v_mfma_f32_16x16x32_bf16 v[108:111], v[156:159], v[248:251], v[108:111]
	ds_read_b128 v[248:251], v196 offset:15360
	s_waitcnt lgkmcnt(3)
	v_mfma_f32_16x16x32_bf16 v[80:83], v[144:147], v[236:239], v[80:83]
	v_mfma_f32_16x16x32_bf16 v[88:91], v[148:151], v[236:239], v[88:91]
	v_mfma_f32_16x16x32_bf16 v[48:51], v[152:155], v[236:239], v[48:51]
	v_mfma_f32_16x16x32_bf16 v[56:59], v[156:159], v[236:239], v[56:59]
	s_waitcnt lgkmcnt(2)
	v_mfma_f32_16x16x32_bf16 v[84:87], v[144:147], v[240:243], v[84:87]
	v_mfma_f32_16x16x32_bf16 v[92:95], v[148:151], v[240:243], v[92:95]
	v_mfma_f32_16x16x32_bf16 v[52:55], v[152:155], v[240:243], v[52:55]
	v_mfma_f32_16x16x32_bf16 v[60:63], v[156:159], v[240:243], v[60:63]
	s_waitcnt lgkmcnt(1)
	v_mfma_f32_16x16x32_bf16 v[64:67], v[144:147], v[244:247], v[64:67]
	v_mfma_f32_16x16x32_bf16 v[72:75], v[148:151], v[244:247], v[72:75]
	v_mfma_f32_16x16x32_bf16 v[32:35], v[152:155], v[244:247], v[32:35]
	v_mfma_f32_16x16x32_bf16 v[40:43], v[156:159], v[244:247], v[40:43]
	s_waitcnt lgkmcnt(0)
	v_mfma_f32_16x16x32_bf16 v[68:71], v[144:147], v[248:251], v[68:71]
	v_mfma_f32_16x16x32_bf16 v[76:79], v[148:151], v[248:251], v[76:79]
	v_mfma_f32_16x16x32_bf16 v[36:39], v[152:155], v[248:251], v[36:39]
	v_mfma_f32_16x16x32_bf16 v[44:47], v[156:159], v[248:251], v[44:47]
	global_load_dwordx4 v[144:147], v[198:199], off
	global_load_dwordx4 v[148:151], v[198:199], off offset:256
	global_load_dwordx4 v[152:155], v[200:201], off
	global_load_dwordx4 v[156:159], v[200:201], off offset:256
	s_waitcnt vmcnt(10)
	s_barrier
	s_add_i32 s3, s1, 4
	s_lshl_b32 s96, s3, 13
	s_add_i32 m0, vcc_lo, 8192
	v_lshl_add_u64 v[198:199], v[188:189], 0, s[96:97]
	global_load_lds_dwordx4 v[198:199], off
	global_load_lds_dwordx4 v[198:199], off offset:1024
	ds_read_b128 v[236:239], v196 offset:16384
	ds_read_b128 v[240:243], v196 offset:17408
	ds_read_b128 v[244:247], v196 offset:18432
	ds_read_b128 v[248:251], v196 offset:19456
	s_add_i32 s3, s1, 5
	s_min_u32 s3, s3, 31
	s_lshl_b32 s96, s3, 11
	v_lshl_add_u64 v[198:199], v[184:185], 0, s[96:97]
	v_lshl_add_u64 v[200:201], v[186:187], 0, s[96:97]
	s_waitcnt lgkmcnt(3)
	v_mfma_f32_16x16x32_bf16 v[16:19], v[160:163], v[236:239], v[16:19]
	v_mfma_f32_16x16x32_bf16 v[24:27], v[164:167], v[236:239], v[24:27]
	v_mfma_f32_16x16x32_bf16 v[0:3], v[168:171], v[236:239], v[0:3]
	v_mfma_f32_16x16x32_bf16 v[8:11], v[172:175], v[236:239], v[8:11]
	ds_read_b128 v[236:239], v196 offset:20480
	s_waitcnt lgkmcnt(3)
	v_mfma_f32_16x16x32_bf16 v[20:23], v[160:163], v[240:243], v[20:23]
	v_mfma_f32_16x16x32_bf16 v[28:31], v[164:167], v[240:243], v[28:31]
	v_mfma_f32_16x16x32_bf16 v[4:7], v[168:171], v[240:243], v[4:7]
	v_mfma_f32_16x16x32_bf16 v[12:15], v[172:175], v[240:243], v[12:15]
	ds_read_b128 v[240:243], v196 offset:21504
	s_waitcnt lgkmcnt(3)
	v_mfma_f32_16x16x32_bf16 v[112:115], v[160:163], v[244:247], v[112:115]
	v_mfma_f32_16x16x32_bf16 v[120:123], v[164:167], v[244:247], v[120:123]
	v_mfma_f32_16x16x32_bf16 v[96:99], v[168:171], v[244:247], v[96:99]
	v_mfma_f32_16x16x32_bf16 v[104:107], v[172:175], v[244:247], v[104:107]
	ds_read_b128 v[244:247], v196 offset:22528
	s_waitcnt lgkmcnt(3)
	v_mfma_f32_16x16x32_bf16 v[116:119], v[160:163], v[248:251], v[116:119]
	v_mfma_f32_16x16x32_bf16 v[124:127], v[164:167], v[248:251], v[124:127]
	v_mfma_f32_16x16x32_bf16 v[100:103], v[168:171], v[248:251], v[100:103]
	v_mfma_f32_16x16x32_bf16 v[108:111], v[172:175], v[248:251], v[108:111]
	ds_read_b128 v[248:251], v196 offset:23552
	s_waitcnt lgkmcnt(3)
	v_mfma_f32_16x16x32_bf16 v[80:83], v[160:163], v[236:239], v[80:83]
	v_mfma_f32_16x16x32_bf16 v[88:91], v[164:167], v[236:239], v[88:91]
	v_mfma_f32_16x16x32_bf16 v[48:51], v[168:171], v[236:239], v[48:51]
	v_mfma_f32_16x16x32_bf16 v[56:59], v[172:175], v[236:239], v[56:59]
	s_waitcnt lgkmcnt(2)
	v_mfma_f32_16x16x32_bf16 v[84:87], v[160:163], v[240:243], v[84:87]
	v_mfma_f32_16x16x32_bf16 v[92:95], v[164:167], v[240:243], v[92:95]
	v_mfma_f32_16x16x32_bf16 v[52:55], v[168:171], v[240:243], v[52:55]
	v_mfma_f32_16x16x32_bf16 v[60:63], v[172:175], v[240:243], v[60:63]
	s_waitcnt lgkmcnt(1)
	v_mfma_f32_16x16x32_bf16 v[64:67], v[160:163], v[244:247], v[64:67]
	v_mfma_f32_16x16x32_bf16 v[72:75], v[164:167], v[244:247], v[72:75]
	v_mfma_f32_16x16x32_bf16 v[32:35], v[168:171], v[244:247], v[32:35]
	v_mfma_f32_16x16x32_bf16 v[40:43], v[172:175], v[244:247], v[40:43]
	s_waitcnt lgkmcnt(0)
	v_mfma_f32_16x16x32_bf16 v[68:71], v[160:163], v[248:251], v[68:71]
	v_mfma_f32_16x16x32_bf16 v[76:79], v[164:167], v[248:251], v[76:79]
	v_mfma_f32_16x16x32_bf16 v[36:39], v[168:171], v[248:251], v[36:39]
	v_mfma_f32_16x16x32_bf16 v[44:47], v[172:175], v[248:251], v[44:47]
	global_load_dwordx4 v[160:163], v[198:199], off
	global_load_dwordx4 v[164:167], v[198:199], off offset:256
	global_load_dwordx4 v[168:171], v[200:201], off
	global_load_dwordx4 v[172:175], v[200:201], off offset:256
	s_waitcnt vmcnt(10)
	s_barrier
	s_add_i32 s3, s1, 5
	s_lshl_b32 s96, s3, 13
	s_add_i32 m0, vcc_lo, 16384
	v_lshl_add_u64 v[198:199], v[188:189], 0, s[96:97]
	global_load_lds_dwordx4 v[198:199], off
	global_load_lds_dwordx4 v[198:199], off offset:1024
	ds_read_b128 v[236:239], v196 offset:0
	ds_read_b128 v[240:243], v196 offset:1024
	ds_read_b128 v[244:247], v196 offset:2048
	ds_read_b128 v[248:251], v196 offset:3072
	s_add_i32 s3, s1, 6
	s_min_u32 s3, s3, 31
	s_lshl_b32 s96, s3, 11
	v_lshl_add_u64 v[198:199], v[184:185], 0, s[96:97]
	v_lshl_add_u64 v[200:201], v[186:187], 0, s[96:97]
	s_waitcnt lgkmcnt(3)
	v_mfma_f32_16x16x32_bf16 v[16:19], v[128:131], v[236:239], v[16:19]
	v_mfma_f32_16x16x32_bf16 v[24:27], v[132:135], v[236:239], v[24:27]
	v_mfma_f32_16x16x32_bf16 v[0:3], v[136:139], v[236:239], v[0:3]
	v_mfma_f32_16x16x32_bf16 v[8:11], v[140:143], v[236:239], v[8:11]
	ds_read_b128 v[236:239], v196 offset:4096
	s_waitcnt lgkmcnt(3)
	v_mfma_f32_16x16x32_bf16 v[20:23], v[128:131], v[240:243], v[20:23]
	v_mfma_f32_16x16x32_bf16 v[28:31], v[132:135], v[240:243], v[28:31]
	v_mfma_f32_16x16x32_bf16 v[4:7], v[136:139], v[240:243], v[4:7]
	v_mfma_f32_16x16x32_bf16 v[12:15], v[140:143], v[240:243], v[12:15]
	ds_read_b128 v[240:243], v196 offset:5120
	s_waitcnt lgkmcnt(3)
	v_mfma_f32_16x16x32_bf16 v[112:115], v[128:131], v[244:247], v[112:115]
	v_mfma_f32_16x16x32_bf16 v[120:123], v[132:135], v[244:247], v[120:123]
	v_mfma_f32_16x16x32_bf16 v[96:99], v[136:139], v[244:247], v[96:99]
	v_mfma_f32_16x16x32_bf16 v[104:107], v[140:143], v[244:247], v[104:107]
	ds_read_b128 v[244:247], v196 offset:6144
	s_waitcnt lgkmcnt(3)
	v_mfma_f32_16x16x32_bf16 v[116:119], v[128:131], v[248:251], v[116:119]
	v_mfma_f32_16x16x32_bf16 v[124:127], v[132:135], v[248:251], v[124:127]
	v_mfma_f32_16x16x32_bf16 v[100:103], v[136:139], v[248:251], v[100:103]
	v_mfma_f32_16x16x32_bf16 v[108:111], v[140:143], v[248:251], v[108:111]
	ds_read_b128 v[248:251], v196 offset:7168
	s_waitcnt lgkmcnt(3)
	v_mfma_f32_16x16x32_bf16 v[80:83], v[128:131], v[236:239], v[80:83]
	v_mfma_f32_16x16x32_bf16 v[88:91], v[132:135], v[236:239], v[88:91]
	v_mfma_f32_16x16x32_bf16 v[48:51], v[136:139], v[236:239], v[48:51]
	v_mfma_f32_16x16x32_bf16 v[56:59], v[140:143], v[236:239], v[56:59]
	s_waitcnt lgkmcnt(2)
	v_mfma_f32_16x16x32_bf16 v[84:87], v[128:131], v[240:243], v[84:87]
	v_mfma_f32_16x16x32_bf16 v[92:95], v[132:135], v[240:243], v[92:95]
	v_mfma_f32_16x16x32_bf16 v[52:55], v[136:139], v[240:243], v[52:55]
	v_mfma_f32_16x16x32_bf16 v[60:63], v[140:143], v[240:243], v[60:63]
	s_waitcnt lgkmcnt(1)
	v_mfma_f32_16x16x32_bf16 v[64:67], v[128:131], v[244:247], v[64:67]
	v_mfma_f32_16x16x32_bf16 v[72:75], v[132:135], v[244:247], v[72:75]
	v_mfma_f32_16x16x32_bf16 v[32:35], v[136:139], v[244:247], v[32:35]
	v_mfma_f32_16x16x32_bf16 v[40:43], v[140:143], v[244:247], v[40:43]
	s_waitcnt lgkmcnt(0)
	v_mfma_f32_16x16x32_bf16 v[68:71], v[128:131], v[248:251], v[68:71]
	v_mfma_f32_16x16x32_bf16 v[76:79], v[132:135], v[248:251], v[76:79]
	v_mfma_f32_16x16x32_bf16 v[36:39], v[136:139], v[248:251], v[36:39]
	v_mfma_f32_16x16x32_bf16 v[44:47], v[140:143], v[248:251], v[44:47]
	global_load_dwordx4 v[128:131], v[198:199], off
	global_load_dwordx4 v[132:135], v[198:199], off offset:256
	global_load_dwordx4 v[136:139], v[200:201], off
	global_load_dwordx4 v[140:143], v[200:201], off offset:256
	s_waitcnt vmcnt(10)
	s_barrier
	s_add_i32 s3, s1, 6
	s_lshl_b32 s96, s3, 13
	s_mov_b32 m0, vcc_lo
	v_lshl_add_u64 v[198:199], v[188:189], 0, s[96:97]
	global_load_lds_dwordx4 v[198:199], off
	global_load_lds_dwordx4 v[198:199], off offset:1024
	ds_read_b128 v[236:239], v196 offset:8192
	ds_read_b128 v[240:243], v196 offset:9216
	ds_read_b128 v[244:247], v196 offset:10240
	ds_read_b128 v[248:251], v196 offset:11264
	s_add_i32 s3, s1, 7
	s_min_u32 s3, s3, 31
	s_lshl_b32 s96, s3, 11
	v_lshl_add_u64 v[198:199], v[184:185], 0, s[96:97]
	v_lshl_add_u64 v[200:201], v[186:187], 0, s[96:97]
	s_waitcnt lgkmcnt(3)
	v_mfma_f32_16x16x32_bf16 v[16:19], v[144:147], v[236:239], v[16:19]
	v_mfma_f32_16x16x32_bf16 v[24:27], v[148:151], v[236:239], v[24:27]
	v_mfma_f32_16x16x32_bf16 v[0:3], v[152:155], v[236:239], v[0:3]
	v_mfma_f32_16x16x32_bf16 v[8:11], v[156:159], v[236:239], v[8:11]
	ds_read_b128 v[236:239], v196 offset:12288
	s_waitcnt lgkmcnt(3)
	v_mfma_f32_16x16x32_bf16 v[20:23], v[144:147], v[240:243], v[20:23]
	v_mfma_f32_16x16x32_bf16 v[28:31], v[148:151], v[240:243], v[28:31]
	v_mfma_f32_16x16x32_bf16 v[4:7], v[152:155], v[240:243], v[4:7]
	v_mfma_f32_16x16x32_bf16 v[12:15], v[156:159], v[240:243], v[12:15]
	ds_read_b128 v[240:243], v196 offset:13312
	s_waitcnt lgkmcnt(3)
	v_mfma_f32_16x16x32_bf16 v[112:115], v[144:147], v[244:247], v[112:115]
	v_mfma_f32_16x16x32_bf16 v[120:123], v[148:151], v[244:247], v[120:123]
	v_mfma_f32_16x16x32_bf16 v[96:99], v[152:155], v[244:247], v[96:99]
	v_mfma_f32_16x16x32_bf16 v[104:107], v[156:159], v[244:247], v[104:107]
	ds_read_b128 v[244:247], v196 offset:14336
	s_waitcnt lgkmcnt(3)
	v_mfma_f32_16x16x32_bf16 v[116:119], v[144:147], v[248:251], v[116:119]
	v_mfma_f32_16x16x32_bf16 v[124:127], v[148:151], v[248:251], v[124:127]
	v_mfma_f32_16x16x32_bf16 v[100:103], v[152:155], v[248:251], v[100:103]
	v_mfma_f32_16x16x32_bf16 v[108:111], v[156:159], v[248:251], v[108:111]
	ds_read_b128 v[248:251], v196 offset:15360
	s_waitcnt lgkmcnt(3)
	v_mfma_f32_16x16x32_bf16 v[80:83], v[144:147], v[236:239], v[80:83]
	v_mfma_f32_16x16x32_bf16 v[88:91], v[148:151], v[236:239], v[88:91]
	v_mfma_f32_16x16x32_bf16 v[48:51], v[152:155], v[236:239], v[48:51]
	v_mfma_f32_16x16x32_bf16 v[56:59], v[156:159], v[236:239], v[56:59]
	s_waitcnt lgkmcnt(2)
	v_mfma_f32_16x16x32_bf16 v[84:87], v[144:147], v[240:243], v[84:87]
	v_mfma_f32_16x16x32_bf16 v[92:95], v[148:151], v[240:243], v[92:95]
	v_mfma_f32_16x16x32_bf16 v[52:55], v[152:155], v[240:243], v[52:55]
	v_mfma_f32_16x16x32_bf16 v[60:63], v[156:159], v[240:243], v[60:63]
	s_waitcnt lgkmcnt(1)
	v_mfma_f32_16x16x32_bf16 v[64:67], v[144:147], v[244:247], v[64:67]
	v_mfma_f32_16x16x32_bf16 v[72:75], v[148:151], v[244:247], v[72:75]
	v_mfma_f32_16x16x32_bf16 v[32:35], v[152:155], v[244:247], v[32:35]
	v_mfma_f32_16x16x32_bf16 v[40:43], v[156:159], v[244:247], v[40:43]
	s_waitcnt lgkmcnt(0)
	v_mfma_f32_16x16x32_bf16 v[68:71], v[144:147], v[248:251], v[68:71]
	v_mfma_f32_16x16x32_bf16 v[76:79], v[148:151], v[248:251], v[76:79]
	v_mfma_f32_16x16x32_bf16 v[36:39], v[152:155], v[248:251], v[36:39]
	v_mfma_f32_16x16x32_bf16 v[44:47], v[156:159], v[248:251], v[44:47]
	global_load_dwordx4 v[144:147], v[198:199], off
	global_load_dwordx4 v[148:151], v[198:199], off offset:256
	global_load_dwordx4 v[152:155], v[200:201], off
	global_load_dwordx4 v[156:159], v[200:201], off offset:256
	s_waitcnt vmcnt(10)
	s_barrier
	s_add_i32 s3, s1, 7
	s_lshl_b32 s96, s3, 13
	s_add_i32 m0, vcc_lo, 8192
	v_lshl_add_u64 v[198:199], v[188:189], 0, s[96:97]
	global_load_lds_dwordx4 v[198:199], off
	global_load_lds_dwordx4 v[198:199], off offset:1024
	ds_read_b128 v[236:239], v196 offset:16384
	ds_read_b128 v[240:243], v196 offset:17408
	ds_read_b128 v[244:247], v196 offset:18432
	ds_read_b128 v[248:251], v196 offset:19456
	s_add_i32 s3, s1, 8
	s_min_u32 s3, s3, 31
	s_lshl_b32 s96, s3, 11
	v_lshl_add_u64 v[198:199], v[184:185], 0, s[96:97]
	v_lshl_add_u64 v[200:201], v[186:187], 0, s[96:97]
	s_waitcnt lgkmcnt(3)
	v_mfma_f32_16x16x32_bf16 v[16:19], v[160:163], v[236:239], v[16:19]
	v_mfma_f32_16x16x32_bf16 v[24:27], v[164:167], v[236:239], v[24:27]
	v_mfma_f32_16x16x32_bf16 v[0:3], v[168:171], v[236:239], v[0:3]
	v_mfma_f32_16x16x32_bf16 v[8:11], v[172:175], v[236:239], v[8:11]
	ds_read_b128 v[236:239], v196 offset:20480
	s_waitcnt lgkmcnt(3)
	v_mfma_f32_16x16x32_bf16 v[20:23], v[160:163], v[240:243], v[20:23]
	v_mfma_f32_16x16x32_bf16 v[28:31], v[164:167], v[240:243], v[28:31]
	v_mfma_f32_16x16x32_bf16 v[4:7], v[168:171], v[240:243], v[4:7]
	v_mfma_f32_16x16x32_bf16 v[12:15], v[172:175], v[240:243], v[12:15]
	ds_read_b128 v[240:243], v196 offset:21504
	s_waitcnt lgkmcnt(3)
	v_mfma_f32_16x16x32_bf16 v[112:115], v[160:163], v[244:247], v[112:115]
	v_mfma_f32_16x16x32_bf16 v[120:123], v[164:167], v[244:247], v[120:123]
	v_mfma_f32_16x16x32_bf16 v[96:99], v[168:171], v[244:247], v[96:99]
	v_mfma_f32_16x16x32_bf16 v[104:107], v[172:175], v[244:247], v[104:107]
	ds_read_b128 v[244:247], v196 offset:22528
	s_waitcnt lgkmcnt(3)
	v_mfma_f32_16x16x32_bf16 v[116:119], v[160:163], v[248:251], v[116:119]
	v_mfma_f32_16x16x32_bf16 v[124:127], v[164:167], v[248:251], v[124:127]
	v_mfma_f32_16x16x32_bf16 v[100:103], v[168:171], v[248:251], v[100:103]
	v_mfma_f32_16x16x32_bf16 v[108:111], v[172:175], v[248:251], v[108:111]
	ds_read_b128 v[248:251], v196 offset:23552
	s_waitcnt lgkmcnt(3)
	v_mfma_f32_16x16x32_bf16 v[80:83], v[160:163], v[236:239], v[80:83]
	v_mfma_f32_16x16x32_bf16 v[88:91], v[164:167], v[236:239], v[88:91]
	v_mfma_f32_16x16x32_bf16 v[48:51], v[168:171], v[236:239], v[48:51]
	v_mfma_f32_16x16x32_bf16 v[56:59], v[172:175], v[236:239], v[56:59]
	s_waitcnt lgkmcnt(2)
	v_mfma_f32_16x16x32_bf16 v[84:87], v[160:163], v[240:243], v[84:87]
	v_mfma_f32_16x16x32_bf16 v[92:95], v[164:167], v[240:243], v[92:95]
	v_mfma_f32_16x16x32_bf16 v[52:55], v[168:171], v[240:243], v[52:55]
	v_mfma_f32_16x16x32_bf16 v[60:63], v[172:175], v[240:243], v[60:63]
	s_waitcnt lgkmcnt(1)
	v_mfma_f32_16x16x32_bf16 v[64:67], v[160:163], v[244:247], v[64:67]
	v_mfma_f32_16x16x32_bf16 v[72:75], v[164:167], v[244:247], v[72:75]
	v_mfma_f32_16x16x32_bf16 v[32:35], v[168:171], v[244:247], v[32:35]
	v_mfma_f32_16x16x32_bf16 v[40:43], v[172:175], v[244:247], v[40:43]
	s_waitcnt lgkmcnt(0)
	v_mfma_f32_16x16x32_bf16 v[68:71], v[160:163], v[248:251], v[68:71]
	v_mfma_f32_16x16x32_bf16 v[76:79], v[164:167], v[248:251], v[76:79]
	v_mfma_f32_16x16x32_bf16 v[36:39], v[168:171], v[248:251], v[36:39]
	v_mfma_f32_16x16x32_bf16 v[44:47], v[172:175], v[248:251], v[44:47]
	global_load_dwordx4 v[160:163], v[198:199], off
	global_load_dwordx4 v[164:167], v[198:199], off offset:256
	global_load_dwordx4 v[168:171], v[200:201], off
	global_load_dwordx4 v[172:175], v[200:201], off offset:256
	s_waitcnt vmcnt(10)
	s_barrier
	s_add_i32 s1, s1, 6
	s_cmp_lt_u32 s1, 30
	s_cbranch_scc1 .Lg16_proj_k
	ds_read_b128 v[236:239], v196 offset:0
	ds_read_b128 v[240:243], v196 offset:1024
	ds_read_b128 v[244:247], v196 offset:2048
	ds_read_b128 v[248:251], v196 offset:3072
	s_waitcnt lgkmcnt(3)
	v_mfma_f32_16x16x32_bf16 v[16:19], v[128:131], v[236:239], v[16:19]
	v_mfma_f32_16x16x32_bf16 v[24:27], v[132:135], v[236:239], v[24:27]
	v_mfma_f32_16x16x32_bf16 v[0:3], v[136:139], v[236:239], v[0:3]
	v_mfma_f32_16x16x32_bf16 v[8:11], v[140:143], v[236:239], v[8:11]
	ds_read_b128 v[236:239], v196 offset:4096
	s_waitcnt lgkmcnt(3)
	v_mfma_f32_16x16x32_bf16 v[20:23], v[128:131], v[240:243], v[20:23]
	v_mfma_f32_16x16x32_bf16 v[28:31], v[132:135], v[240:243], v[28:31]
	v_mfma_f32_16x16x32_bf16 v[4:7], v[136:139], v[240:243], v[4:7]
	v_mfma_f32_16x16x32_bf16 v[12:15], v[140:143], v[240:243], v[12:15]
	ds_read_b128 v[240:243], v196 offset:5120
	s_waitcnt lgkmcnt(3)
	v_mfma_f32_16x16x32_bf16 v[112:115], v[128:131], v[244:247], v[112:115]
	v_mfma_f32_16x16x32_bf16 v[120:123], v[132:135], v[244:247], v[120:123]
	v_mfma_f32_16x16x32_bf16 v[96:99], v[136:139], v[244:247], v[96:99]
	v_mfma_f32_16x16x32_bf16 v[104:107], v[140:143], v[244:247], v[104:107]
	ds_read_b128 v[244:247], v196 offset:6144
	s_waitcnt lgkmcnt(3)
	v_mfma_f32_16x16x32_bf16 v[116:119], v[128:131], v[248:251], v[116:119]
	v_mfma_f32_16x16x32_bf16 v[124:127], v[132:135], v[248:251], v[124:127]
	v_mfma_f32_16x16x32_bf16 v[100:103], v[136:139], v[248:251], v[100:103]
	v_mfma_f32_16x16x32_bf16 v[108:111], v[140:143], v[248:251], v[108:111]
	ds_read_b128 v[248:251], v196 offset:7168
	s_waitcnt lgkmcnt(3)
	v_mfma_f32_16x16x32_bf16 v[80:83], v[128:131], v[236:239], v[80:83]
	v_mfma_f32_16x16x32_bf16 v[88:91], v[132:135], v[236:239], v[88:91]
	v_mfma_f32_16x16x32_bf16 v[48:51], v[136:139], v[236:239], v[48:51]
	v_mfma_f32_16x16x32_bf16 v[56:59], v[140:143], v[236:239], v[56:59]
	s_waitcnt lgkmcnt(2)
	v_mfma_f32_16x16x32_bf16 v[84:87], v[128:131], v[240:243], v[84:87]
	v_mfma_f32_16x16x32_bf16 v[92:95], v[132:135], v[240:243], v[92:95]
	v_mfma_f32_16x16x32_bf16 v[52:55], v[136:139], v[240:243], v[52:55]
	v_mfma_f32_16x16x32_bf16 v[60:63], v[140:143], v[240:243], v[60:63]
	s_waitcnt lgkmcnt(1)
	v_mfma_f32_16x16x32_bf16 v[64:67], v[128:131], v[244:247], v[64:67]
	v_mfma_f32_16x16x32_bf16 v[72:75], v[132:135], v[244:247], v[72:75]
	v_mfma_f32_16x16x32_bf16 v[32:35], v[136:139], v[244:247], v[32:35]
	v_mfma_f32_16x16x32_bf16 v[40:43], v[140:143], v[244:247], v[40:43]
	s_waitcnt lgkmcnt(0)
	v_mfma_f32_16x16x32_bf16 v[68:71], v[128:131], v[248:251], v[68:71]
	v_mfma_f32_16x16x32_bf16 v[76:79], v[132:135], v[248:251], v[76:79]
	v_mfma_f32_16x16x32_bf16 v[36:39], v[136:139], v[248:251], v[36:39]
	v_mfma_f32_16x16x32_bf16 v[44:47], v[140:143], v[248:251], v[44:47]
	s_waitcnt vmcnt(4)
	s_barrier
	ds_read_b128 v[236:239], v196 offset:8192
	ds_read_b128 v[240:243], v196 offset:9216
	ds_read_b128 v[244:247], v196 offset:10240
	ds_read_b128 v[248:251], v196 offset:11264
	s_waitcnt lgkmcnt(3)
	v_mfma_f32_16x16x32_bf16 v[16:19], v[144:147], v[236:239], v[16:19]
	v_mfma_f32_16x16x32_bf16 v[24:27], v[148:151], v[236:239], v[24:27]
	v_mfma_f32_16x16x32_bf16 v[0:3], v[152:155], v[236:239], v[0:3]
	v_mfma_f32_16x16x32_bf16 v[8:11], v[156:159], v[236:239], v[8:11]
	ds_read_b128 v[236:239], v196 offset:12288
	s_waitcnt lgkmcnt(3)
	v_mfma_f32_16x16x32_bf16 v[20:23], v[144:147], v[240:243], v[20:23]
	v_mfma_f32_16x16x32_bf16 v[28:31], v[148:151], v[240:243], v[28:31]
	v_mfma_f32_16x16x32_bf16 v[4:7], v[152:155], v[240:243], v[4:7]
	v_mfma_f32_16x16x32_bf16 v[12:15], v[156:159], v[240:243], v[12:15]
	ds_read_b128 v[240:243], v196 offset:13312
	s_waitcnt lgkmcnt(3)
	v_mfma_f32_16x16x32_bf16 v[112:115], v[144:147], v[244:247], v[112:115]
	v_mfma_f32_16x16x32_bf16 v[120:123], v[148:151], v[244:247], v[120:123]
	v_mfma_f32_16x16x32_bf16 v[96:99], v[152:155], v[244:247], v[96:99]
	v_mfma_f32_16x16x32_bf16 v[104:107], v[156:159], v[244:247], v[104:107]
	ds_read_b128 v[244:247], v196 offset:14336
	s_waitcnt lgkmcnt(3)
	v_mfma_f32_16x16x32_bf16 v[116:119], v[144:147], v[248:251], v[116:119]
	v_mfma_f32_16x16x32_bf16 v[124:127], v[148:151], v[248:251], v[124:127]
	v_mfma_f32_16x16x32_bf16 v[100:103], v[152:155], v[248:251], v[100:103]
	v_mfma_f32_16x16x32_bf16 v[108:111], v[156:159], v[248:251], v[108:111]
	ds_read_b128 v[248:251], v196 offset:15360
	v_permlane16_swap_b32_e32 v16, v20
	v_permlane16_swap_b32_e32 v17, v21
	v_permlane16_swap_b32_e32 v18, v22
	v_permlane16_swap_b32_e32 v19, v23
	v_permlane16_swap_b32_e32 v24, v28
	v_permlane16_swap_b32_e32 v25, v29
	v_permlane16_swap_b32_e32 v26, v30
	v_permlane16_swap_b32_e32 v27, v31
	v_permlane16_swap_b32_e32 v0, v4
	v_permlane16_swap_b32_e32 v1, v5
	v_permlane16_swap_b32_e32 v2, v6
	v_permlane16_swap_b32_e32 v3, v7
	v_permlane16_swap_b32_e32 v8, v12
	v_permlane16_swap_b32_e32 v9, v13
	v_permlane16_swap_b32_e32 v10, v14
	v_permlane16_swap_b32_e32 v11, v15
	v_permlane32_swap_b32_e32 v16, v20
	v_permlane32_swap_b32_e32 v17, v21
	v_permlane32_swap_b32_e32 v18, v22
	v_permlane32_swap_b32_e32 v19, v23
	v_permlane32_swap_b32_e32 v24, v28
	v_permlane32_swap_b32_e32 v25, v29
	v_permlane32_swap_b32_e32 v26, v30
	v_permlane32_swap_b32_e32 v27, v31
	v_permlane32_swap_b32_e32 v0, v4
	v_permlane32_swap_b32_e32 v1, v5
	v_permlane32_swap_b32_e32 v2, v6
	v_permlane32_swap_b32_e32 v3, v7
	v_permlane32_swap_b32_e32 v8, v12
	v_permlane32_swap_b32_e32 v9, v13
	v_permlane32_swap_b32_e32 v10, v14
	v_permlane32_swap_b32_e32 v11, v15
	s_waitcnt lgkmcnt(3)
	v_mfma_f32_16x16x32_bf16 v[80:83], v[144:147], v[236:239], v[80:83]
	v_mfma_f32_16x16x32_bf16 v[88:91], v[148:151], v[236:239], v[88:91]
	v_mfma_f32_16x16x32_bf16 v[48:51], v[152:155], v[236:239], v[48:51]
	v_mfma_f32_16x16x32_bf16 v[56:59], v[156:159], v[236:239], v[56:59]
	s_waitcnt lgkmcnt(2)
	v_mfma_f32_16x16x32_bf16 v[84:87], v[144:147], v[240:243], v[84:87]
	v_mfma_f32_16x16x32_bf16 v[92:95], v[148:151], v[240:243], v[92:95]
	v_mfma_f32_16x16x32_bf16 v[52:55], v[152:155], v[240:243], v[52:55]
	v_mfma_f32_16x16x32_bf16 v[60:63], v[156:159], v[240:243], v[60:63]
	v_permlane16_swap_b32_e32 v112, v116
	v_permlane16_swap_b32_e32 v113, v117
	v_permlane16_swap_b32_e32 v114, v118
	v_permlane16_swap_b32_e32 v115, v119
	v_permlane16_swap_b32_e32 v120, v124
	v_permlane16_swap_b32_e32 v121, v125
	v_permlane16_swap_b32_e32 v122, v126
	v_permlane16_swap_b32_e32 v123, v127
	v_permlane16_swap_b32_e32 v96, v100
	v_permlane16_swap_b32_e32 v97, v101
	v_permlane16_swap_b32_e32 v98, v102
	v_permlane16_swap_b32_e32 v99, v103
	v_permlane16_swap_b32_e32 v104, v108
	v_permlane16_swap_b32_e32 v105, v109
	v_permlane16_swap_b32_e32 v106, v110
	v_permlane16_swap_b32_e32 v107, v111
	v_permlane32_swap_b32_e32 v112, v116
	v_permlane32_swap_b32_e32 v113, v117
	v_permlane32_swap_b32_e32 v114, v118
	v_permlane32_swap_b32_e32 v115, v119
	v_permlane32_swap_b32_e32 v120, v124
	v_permlane32_swap_b32_e32 v121, v125
	v_permlane32_swap_b32_e32 v122, v126
	v_permlane32_swap_b32_e32 v123, v127
	v_permlane32_swap_b32_e32 v96, v100
	v_permlane32_swap_b32_e32 v97, v101
	v_permlane32_swap_b32_e32 v98, v102
	v_permlane32_swap_b32_e32 v99, v103
	v_permlane32_swap_b32_e32 v104, v108
	v_permlane32_swap_b32_e32 v105, v109
	v_permlane32_swap_b32_e32 v106, v110
	v_permlane32_swap_b32_e32 v107, v111
	s_waitcnt lgkmcnt(1)
	v_mfma_f32_16x16x32_bf16 v[64:67], v[144:147], v[244:247], v[64:67]
	v_mfma_f32_16x16x32_bf16 v[72:75], v[148:151], v[244:247], v[72:75]
	v_mfma_f32_16x16x32_bf16 v[32:35], v[152:155], v[244:247], v[32:35]
	v_mfma_f32_16x16x32_bf16 v[40:43], v[156:159], v[244:247], v[40:43]
	s_waitcnt lgkmcnt(0)
	v_mfma_f32_16x16x32_bf16 v[68:71], v[144:147], v[248:251], v[68:71]
	v_mfma_f32_16x16x32_bf16 v[76:79], v[148:151], v[248:251], v[76:79]
	v_mfma_f32_16x16x32_bf16 v[36:39], v[152:155], v[248:251], v[36:39]
	v_mfma_f32_16x16x32_bf16 v[44:47], v[156:159], v[248:251], v[44:47]
	v_permlane16_swap_b32_e32 v80, v84
	v_permlane16_swap_b32_e32 v81, v85
	v_permlane16_swap_b32_e32 v82, v86
	v_permlane16_swap_b32_e32 v83, v87
	v_permlane16_swap_b32_e32 v88, v92
	v_permlane16_swap_b32_e32 v89, v93
	v_permlane16_swap_b32_e32 v90, v94
	v_permlane16_swap_b32_e32 v91, v95
	v_permlane16_swap_b32_e32 v48, v52
	v_permlane16_swap_b32_e32 v49, v53
	v_permlane16_swap_b32_e32 v50, v54
	v_permlane16_swap_b32_e32 v51, v55
	v_permlane16_swap_b32_e32 v56, v60
	v_permlane16_swap_b32_e32 v57, v61
	v_permlane16_swap_b32_e32 v58, v62
	v_permlane16_swap_b32_e32 v59, v63
	v_permlane32_swap_b32_e32 v80, v84
	v_permlane32_swap_b32_e32 v81, v85
	v_permlane32_swap_b32_e32 v82, v86
	v_permlane32_swap_b32_e32 v83, v87
	v_permlane32_swap_b32_e32 v88, v92
	v_permlane32_swap_b32_e32 v89, v93
	v_permlane32_swap_b32_e32 v90, v94
	v_permlane32_swap_b32_e32 v91, v95
	v_permlane32_swap_b32_e32 v48, v52
	v_permlane32_swap_b32_e32 v49, v53
	v_permlane32_swap_b32_e32 v50, v54
	v_permlane32_swap_b32_e32 v51, v55
	v_permlane32_swap_b32_e32 v56, v60
	v_permlane32_swap_b32_e32 v57, v61
	v_permlane32_swap_b32_e32 v58, v62
	v_permlane32_swap_b32_e32 v59, v63
	s_barrier
	s_nop 7
	v_permlane16_swap_b32_e32 v64, v68
	v_permlane16_swap_b32_e32 v65, v69
	v_permlane16_swap_b32_e32 v66, v70
	v_permlane16_swap_b32_e32 v67, v71
	v_permlane16_swap_b32_e32 v72, v76
	v_permlane16_swap_b32_e32 v73, v77
	v_permlane16_swap_b32_e32 v74, v78
	v_permlane16_swap_b32_e32 v75, v79
	v_permlane16_swap_b32_e32 v32, v36
	v_permlane16_swap_b32_e32 v33, v37
	v_permlane16_swap_b32_e32 v34, v38
	v_permlane16_swap_b32_e32 v35, v39
	v_permlane16_swap_b32_e32 v40, v44
	v_permlane16_swap_b32_e32 v41, v45
	v_permlane16_swap_b32_e32 v42, v46
	v_permlane16_swap_b32_e32 v43, v47
	v_permlane32_swap_b32_e32 v64, v68
	v_permlane32_swap_b32_e32 v65, v69
	v_permlane32_swap_b32_e32 v66, v70
	v_permlane32_swap_b32_e32 v67, v71
	v_permlane32_swap_b32_e32 v72, v76
	v_permlane32_swap_b32_e32 v73, v77
	v_permlane32_swap_b32_e32 v74, v78
	v_permlane32_swap_b32_e32 v75, v79
	v_permlane32_swap_b32_e32 v32, v36
	v_permlane32_swap_b32_e32 v33, v37
	v_permlane32_swap_b32_e32 v34, v38
	v_permlane32_swap_b32_e32 v35, v39
	v_permlane32_swap_b32_e32 v40, v44
	v_permlane32_swap_b32_e32 v41, v45
	v_permlane32_swap_b32_e32 v42, v46
	v_permlane32_swap_b32_e32 v43, v47
	s_waitcnt vmcnt(0)
	s_lshl_b32 s12, s2, 8
	s_cmp_eq_u32 s0, 23
	s_mov_b64 s[2:3], -1
	s_cbranch_scc1 .LBB0_347
	s_movk_i32 s1, 0x2400
	s_waitcnt vmcnt(6)
	v_and_b32_e32 v130, 0xffffffc0, v181
	s_cmp_gt_i32 s0, 10
	v_mul_lo_u32 v129, v233, s1
	v_and_b32_e32 v128, 56, v234
	v_add_u32_e32 v131, s12, v130
	s_cselect_b64 s[2:3], -1, 0
	s_cmp_gt_u32 s0, 19
	v_mul_u32_u24_e32 v130, 0x120, v183
	s_waitcnt vmcnt(0)
	v_lshl_or_b32 v132, v128, 1, v129
	v_lshl_or_b32 v128, s0, 7, v128
	s_cselect_b64 s[0:1], -1, 0
	v_lshl_add_u32 v129, v130, 1, v129
	v_lshl_or_b32 v130, v231, 1, v129
	v_cvt_pk_bf16_f32 v112, v112, s0
	ds_write_b16 v130, v112 offset:64
	v_cvt_pk_bf16_f32 v112, v17, s0
	v_cvt_pk_bf16_f32 v96, v96, s0
	ds_write_b16 v130, v112 offset:144
	v_cvt_pk_bf16_f32 v112, v113, s0
	ds_write_b16 v130, v96 offset:4672
	v_cvt_pk_bf16_f32 v96, v1, s0
	ds_write_b16 v130, v112 offset:208
	v_cvt_pk_bf16_f32 v112, v18, s0
	ds_write_b16 v130, v96 offset:4752
	v_cvt_pk_bf16_f32 v96, v97, s0
	ds_write_b16 v130, v112 offset:288
	v_cvt_pk_bf16_f32 v112, v114, s0
	ds_write_b16 v130, v96 offset:4816
	v_cvt_pk_bf16_f32 v96, v2, s0
	ds_write_b16 v130, v112 offset:352
	v_cvt_pk_bf16_f32 v112, v19, s0
	ds_write_b16 v130, v96 offset:4896
	v_cvt_pk_bf16_f32 v96, v98, s0
	ds_write_b16 v130, v112 offset:432
	v_cvt_pk_bf16_f32 v112, v115, s0
	ds_write_b16 v130, v96 offset:4960
	v_cvt_pk_bf16_f32 v96, v3, s0
	ds_write_b16 v130, v112 offset:496
	v_cvt_pk_bf16_f32 v112, v20, s0
	ds_write_b16 v130, v96 offset:5040
	v_cvt_pk_bf16_f32 v96, v99, s0
	ds_write_b16 v130, v112 offset:1152
	v_cvt_pk_bf16_f32 v112, v116, s0
	ds_write_b16 v130, v96 offset:5104
	v_cvt_pk_bf16_f32 v96, v4, s0
	ds_write_b16 v130, v112 offset:1216
	v_cvt_pk_bf16_f32 v112, v21, s0
	ds_write_b16 v130, v96 offset:5760
	v_cvt_pk_bf16_f32 v96, v100, s0
	ds_write_b16 v130, v112 offset:1296
	v_cvt_pk_bf16_f32 v112, v117, s0
	ds_write_b16 v130, v96 offset:5824
	v_cvt_pk_bf16_f32 v96, v5, s0
	ds_write_b16 v130, v112 offset:1360
	v_cvt_pk_bf16_f32 v112, v22, s0
	ds_write_b16 v130, v96 offset:5904
	v_cvt_pk_bf16_f32 v96, v101, s0
	ds_write_b16 v130, v112 offset:1440
	v_cvt_pk_bf16_f32 v112, v118, s0
	ds_write_b16 v130, v96 offset:5968
	v_cvt_pk_bf16_f32 v96, v6, s0
	ds_write_b16 v130, v112 offset:1504
	v_cvt_pk_bf16_f32 v112, v23, s0
	ds_write_b16 v130, v96 offset:6048
	v_cvt_pk_bf16_f32 v96, v102, s0
	ds_write_b16 v130, v112 offset:1584
	v_cvt_pk_bf16_f32 v112, v119, s0
	ds_write_b16 v130, v96 offset:6112
	v_cvt_pk_bf16_f32 v96, v7, s0
	ds_write_b16 v130, v112 offset:1648
	v_cvt_pk_bf16_f32 v112, v24, s0
	ds_write_b16 v130, v96 offset:6192
	v_cvt_pk_bf16_f32 v96, v103, s0
	ds_write_b16 v130, v112 offset:2304
	v_cvt_pk_bf16_f32 v112, v120, s0
	ds_write_b16 v130, v96 offset:6256
	v_cvt_pk_bf16_f32 v96, v8, s0
	ds_write_b16 v130, v112 offset:2368
	v_cvt_pk_bf16_f32 v112, v25, s0
	ds_write_b16 v130, v96 offset:6912
	v_cvt_pk_bf16_f32 v96, v104, s0
	ds_write_b16 v130, v112 offset:2448
	v_cvt_pk_bf16_f32 v112, v121, s0
	ds_write_b16 v130, v96 offset:6976
	v_cvt_pk_bf16_f32 v96, v9, s0
	ds_write_b16 v130, v112 offset:2512
	v_cvt_pk_bf16_f32 v112, v26, s0
	ds_write_b16 v130, v96 offset:7056
	v_cvt_pk_bf16_f32 v96, v105, s0
	ds_write_b16 v130, v112 offset:2592
	v_cvt_pk_bf16_f32 v112, v122, s0
	ds_write_b16 v130, v96 offset:7120
	v_cvt_pk_bf16_f32 v96, v10, s0
	ds_write_b16 v130, v112 offset:2656
	v_cvt_pk_bf16_f32 v112, v27, s0
	ds_write_b16 v130, v96 offset:7200
	v_cvt_pk_bf16_f32 v96, v106, s0
	ds_write_b16 v130, v112 offset:2736
	v_cvt_pk_bf16_f32 v112, v123, s0
	ds_write_b16 v130, v96 offset:7264
	v_cvt_pk_bf16_f32 v96, v11, s0
	ds_write_b16 v130, v112 offset:2800
	v_cvt_pk_bf16_f32 v112, v28, s0
	ds_write_b16 v130, v96 offset:7344
	v_cvt_pk_bf16_f32 v96, v107, s0
	ds_write_b16 v130, v112 offset:3456
	v_cvt_pk_bf16_f32 v112, v124, s0
	ds_write_b16 v130, v96 offset:7408
	v_cvt_pk_bf16_f32 v96, v12, s0
	ds_write_b16 v130, v112 offset:3520
	v_cvt_pk_bf16_f32 v112, v29, s0
	ds_write_b16 v130, v96 offset:8064
	v_cvt_pk_bf16_f32 v96, v108, s0
	ds_write_b16 v130, v112 offset:3600
	v_cvt_pk_bf16_f32 v112, v125, s0
	ds_write_b16 v130, v96 offset:8128
	v_cvt_pk_bf16_f32 v96, v13, s0
	ds_write_b16 v130, v112 offset:3664
	v_cvt_pk_bf16_f32 v112, v30, s0
	ds_write_b16 v130, v96 offset:8208
	v_cvt_pk_bf16_f32 v96, v109, s0
	ds_write_b16 v130, v112 offset:3744
	v_cvt_pk_bf16_f32 v112, v126, s0
	ds_write_b16 v130, v96 offset:8272
	v_cvt_pk_bf16_f32 v96, v14, s0
	ds_write_b16 v130, v112 offset:3808
	v_cvt_pk_bf16_f32 v112, v31, s0
	ds_write_b16 v130, v96 offset:8352
	v_cvt_pk_bf16_f32 v96, v110, s0
	ds_write_b16 v130, v112 offset:3888
	v_cvt_pk_bf16_f32 v112, v127, s0
	ds_write_b16 v130, v96 offset:8416
	v_cvt_pk_bf16_f32 v96, v15, s0
	v_cvt_pk_bf16_f32 v133, v16, s0
	ds_write_b16 v130, v112 offset:3952
	v_cvt_pk_bf16_f32 v112, v0, s0
	ds_write_b16 v130, v96 offset:8496
	v_cvt_pk_bf16_f32 v96, v111, s0
	ds_write_b16 v130, v133
	ds_write_b16 v130, v112 offset:4608
	ds_write_b16 v130, v96 offset:8560
	v_lshrrev_b32_e32 v109, 3, v232
	s_waitcnt lgkmcnt(0)
	v_mad_u32_u24 v96, v109, s42, v132
	ds_read_b128 v[96:99], v96
	v_mov_b32_e32 v176, v128
	v_or_b32_e32 v110, v131, v109
	s_mov_b64 s[4:5], -1
	s_and_b64 vcc, exec, s[2:3]
	s_cbranch_vccz .LBB0_224
	s_and_b64 vcc, exec, s[0:1]
	s_cbranch_vccz .LBB0_221
	v_readlane_b32 s16, v254, 15
	v_readlane_b32 s18, v254, 17
	v_readlane_b32 s19, v254, 18
	v_readlane_b32 s17, v254, 16
	v_readlane_b32 s20, v254, 19
	v_mov_b64_e32 v[100:101], s[18:19]
	v_mad_i64_i32 v[100:101], s[4:5], v110, s89, v[100:101]
	s_movk_i32 s4, 0xec00
	v_lshl_add_u64 v[100:101], v[176:177], 1, v[100:101]
	s_mov_b32 s5, -1
	v_readlane_b32 s21, v254, 20
	v_readlane_b32 s22, v254, 21
	v_readlane_b32 s23, v254, 22
	v_readlane_b32 s24, v254, 23
	v_readlane_b32 s25, v254, 24
	v_readlane_b32 s26, v254, 25
	v_readlane_b32 s27, v254, 26
	v_readlane_b32 s28, v254, 27
	v_readlane_b32 s29, v254, 28
	v_readlane_b32 s30, v254, 29
	v_readlane_b32 s31, v254, 30
	v_lshl_add_u64 v[100:101], v[100:101], 0, s[4:5]
	s_mov_b64 s[4:5], 0

.LBB0_923:
	s_ashr_i32 s2, s4, 31
	s_lshr_b32 s2, s2, 26
	s_add_i32 s2, s4, s2
	s_ashr_i32 s3, s2, 6
	s_lshl_b32 s3, s3, 3
	s_sub_i32 s8, s25, s3
	s_min_i32 s8, s8, 8
	s_abs_i32 s9, s8
	v_cvt_f32_u32_e32 v0, s9
	s_sub_i32 s12, 0, s9
	s_andn2_b32 s2, s2, 63
	s_sub_i32 s10, s4, s2
	v_rcp_iflag_f32_e32 v0, v0
	s_abs_i32 s2, s10
	s_xor_b32 s11, s10, s8
	s_ashr_i32 s11, s11, 31
	v_mul_f32_e32 v0, 0x4f7ffffe, v0
	v_cvt_u32_f32_e32 v0, v0
	v_mov_b32_e32 v181, v179
	v_readfirstlane_b32 s13, v0
	s_mul_i32 s12, s12, s13
	s_mul_hi_u32 s12, s13, s12
	s_add_i32 s13, s13, s12
	s_mul_hi_u32 s12, s2, s13
	s_mul_i32 s13, s12, s9
	s_sub_i32 s2, s2, s13
	s_add_i32 s14, s12, 1
	s_sub_i32 s13, s2, s9
	s_cmp_ge_u32 s2, s9
	s_cselect_b32 s12, s14, s12
	s_cselect_b32 s2, s13, s2
	s_add_i32 s13, s12, 1
	s_cmp_ge_u32 s2, s9
	s_cselect_b32 s2, s13, s12
	s_xor_b32 s2, s2, s11
	s_sub_i32 s2, s2, s11
	s_mul_i32 s8, s8, s2
	s_add_i32 s3, s3, s7
	s_sub_i32 s8, s10, s8
	v_ashrrev_i32_e32 v237, 6, v181
	s_add_i32 s8, s3, s8
	v_lshlrev_b32_e32 v0, 1, v237
	v_lshl_add_u32 v0, s8, 3, v0
	v_ashrrev_i32_e32 v1, 31, v0
	v_bfe_u32 v183, v181, 5, 1
	v_lshlrev_b64 v[0:1], 16, v[0:1]
	v_and_b32_e32 v238, 31, v181
	v_lshl_add_u64 v[0:1], s[64:65], 0, v[0:1]
	v_lshlrev_b32_e32 v176, 9, v183
	s_ashr_i32 s3, s2, 31
	v_lshl_add_u64 v[0:1], v[0:1], 0, v[176:177]
	v_lshlrev_b32_e32 v176, 4, v238
	v_ashrrev_i32_e32 v40, 2, v181
	s_lshl_b64 s[10:11], s[2:3], 18
	v_lshl_add_u64 v[184:185], v[0:1], 0, v[176:177]
	s_add_u32 s10, s5, s10
	v_lshlrev_b32_e32 v0, 5, v40
	s_addc_u32 s11, s6, s11
	v_ashrrev_i32_e32 v1, 31, v0
	v_lshlrev_b32_e32 v2, 4, v181
	v_lshl_add_u64 v[0:1], v[0:1], 1, s[10:11]
	v_and_b32_e32 v176, 48, v2
	v_lshl_add_u64 v[186:187], v[0:1], 0, v[176:177]
	s_movk_i32 s3, 0x2000
	v_add_co_u32_e32 v36, vcc, s3, v186
	v_mul_u32_u24_e32 v38, 40, v238
	s_nop 0
	v_addc_co_u32_e32 v37, vcc, 0, v187, vcc
	v_lshlrev_b32_e32 v39, 4, v183
	v_lshl_add_u32 v240, v38, 1, v39
	v_add_co_u32_e32 v38, vcc, s41, v184
	s_movk_i32 s9, 0x50
	s_nop 0
	v_addc_co_u32_e32 v39, vcc, 0, v185, vcc
	v_and_b32_e32 v239, 63, v181
	v_bfe_u32 v247, v181, 4, 2
	v_lshlrev_b32_e32 v247, 1, v247
	v_mov_b32_e32 v176, 0x78
	v_lshrrev_b32_e32 v247, v247, v176
	v_and_b32_e32 v247, 3, v247
	v_and_b32_e32 v246, 3, v181
	v_xor_b32_e32 v247, v247, v246
	v_lshlrev_b32_e32 v247, 4, v247
	v_and_b32_e32 v188, 0xffffffcf, v186
	v_or_b32_e32 v188, v188, v247
	v_mov_b32_e32 v189, v187
	v_lshrrev_b32_e32 v176, 6, v181
	v_lshlrev_b32_e32 v247, 11, v176
	v_lshlrev_b32_e32 v176, 10, v176
	v_lshl_add_u64 v[188:189], v[188:189], 0, v[176:177]
	v_readfirstlane_b32 vcc_lo, v247
	v_bfe_u32 v247, v181, 4, 1
	v_lshlrev_b32_e32 v176, 9, v183
	v_lshl_add_u32 v176, v247, 8, v176
	v_lshl_add_u64 v[184:185], v[184:185], 0, v[176:177]
	v_mov_b32_e32 v176, s41
	v_lshl_add_u64 v[186:187], v[184:185], 0, v[176:177]
	v_mov_b32_e32 v176, 0x78
	v_bfe_u32 v247, v181, 2, 2
	v_lshlrev_b32_e32 v247, 1, v247
	v_lshrrev_b32_e32 v247, v247, v176
	v_and_b32_e32 v247, 3, v247
	v_bfe_u32 v246, v181, 4, 2
	v_xor_b32_e32 v247, v247, v246
	v_lshlrev_b32_e32 v247, 4, v247
	v_and_b32_e32 v246, 15, v181
	v_lshl_add_u32 v246, v246, 6, v247
	s_mov_b32 s96, 0
	s_mov_b32 m0, vcc_lo
	v_lshl_add_u64 v[248:249], v[188:189], 0, s[96:97]
	global_load_lds_dwordx4 v[248:249], off
	global_load_lds_dwordx4 v[248:249], off offset:1024
	s_mov_b32 s96, 0
	v_lshl_add_u64 v[248:249], v[184:185], 0, s[96:97]
	v_lshl_add_u64 v[250:251], v[186:187], 0, s[96:97]
	global_load_dwordx4 v[128:131], v[248:249], off
	global_load_dwordx4 v[132:135], v[248:249], off offset:256
	global_load_dwordx4 v[136:139], v[250:251], off
	global_load_dwordx4 v[140:143], v[250:251], off offset:256
	s_movk_i32 s96, 0x800
	v_lshl_add_u64 v[248:249], v[184:185], 0, s[96:97]
	v_lshl_add_u64 v[250:251], v[186:187], 0, s[96:97]
	global_load_dwordx4 v[144:147], v[248:249], off
	global_load_dwordx4 v[148:151], v[248:249], off offset:256
	global_load_dwordx4 v[152:155], v[250:251], off
	global_load_dwordx4 v[156:159], v[250:251], off offset:256
	s_movk_i32 s96, 0x2000
	s_add_i32 m0, vcc_lo, 8192
	v_lshl_add_u64 v[248:249], v[188:189], 0, s[96:97]
	global_load_lds_dwordx4 v[248:249], off
	global_load_lds_dwordx4 v[248:249], off offset:1024
	s_movk_i32 s96, 0x1000
	v_lshl_add_u64 v[248:249], v[184:185], 0, s[96:97]
	v_lshl_add_u64 v[250:251], v[186:187], 0, s[96:97]
	global_load_dwordx4 v[160:163], v[248:249], off
	global_load_dwordx4 v[164:167], v[248:249], off offset:256
	global_load_dwordx4 v[168:171], v[250:251], off
	global_load_dwordx4 v[172:175], v[250:251], off offset:256
	v_mov_b32_e32 v0, 0
	v_mov_b32_e32 v1, 0
	v_mov_b32_e32 v2, 0
	v_mov_b32_e32 v3, 0
	v_mov_b32_e32 v4, 0
	v_mov_b32_e32 v5, 0
	v_mov_b32_e32 v6, 0
	v_mov_b32_e32 v7, 0
	v_mov_b32_e32 v8, 0
	v_mov_b32_e32 v9, 0
	v_mov_b32_e32 v10, 0
	v_mov_b32_e32 v11, 0
	v_mov_b32_e32 v12, 0
	v_mov_b32_e32 v13, 0
	v_mov_b32_e32 v14, 0
	v_mov_b32_e32 v15, 0
	v_mov_b32_e32 v16, 0
	v_mov_b32_e32 v17, 0
	v_mov_b32_e32 v18, 0
	v_mov_b32_e32 v19, 0
	v_mov_b32_e32 v20, 0
	v_mov_b32_e32 v21, 0
	v_mov_b32_e32 v22, 0
	v_mov_b32_e32 v23, 0
	v_mov_b32_e32 v24, 0
	v_mov_b32_e32 v25, 0
	v_mov_b32_e32 v26, 0
	v_mov_b32_e32 v27, 0
	v_mov_b32_e32 v28, 0
	v_mov_b32_e32 v29, 0
	v_mov_b32_e32 v30, 0
	v_mov_b32_e32 v31, 0
	v_mov_b32_e32 v32, 0
	v_mov_b32_e32 v33, 0
	v_mov_b32_e32 v34, 0
	v_mov_b32_e32 v35, 0
	v_mov_b32_e32 v36, 0
	v_mov_b32_e32 v37, 0
	v_mov_b32_e32 v38, 0
	v_mov_b32_e32 v39, 0
	v_mov_b32_e32 v40, 0
	v_mov_b32_e32 v41, 0
	v_mov_b32_e32 v42, 0
	v_mov_b32_e32 v43, 0
	v_mov_b32_e32 v44, 0
	v_mov_b32_e32 v45, 0
	v_mov_b32_e32 v46, 0
	v_mov_b32_e32 v47, 0
	v_mov_b32_e32 v48, 0
	v_mov_b32_e32 v49, 0
	v_mov_b32_e32 v50, 0
	v_mov_b32_e32 v51, 0
	v_mov_b32_e32 v52, 0
	v_mov_b32_e32 v53, 0
	v_mov_b32_e32 v54, 0
	v_mov_b32_e32 v55, 0
	v_mov_b32_e32 v56, 0
	v_mov_b32_e32 v57, 0
	v_mov_b32_e32 v58, 0
	v_mov_b32_e32 v59, 0
	v_mov_b32_e32 v60, 0
	v_mov_b32_e32 v61, 0
	v_mov_b32_e32 v62, 0
	v_mov_b32_e32 v63, 0
	v_mov_b32_e32 v64, 0
	v_mov_b32_e32 v65, 0
	v_mov_b32_e32 v66, 0
	v_mov_b32_e32 v67, 0
	v_mov_b32_e32 v68, 0
	v_mov_b32_e32 v69, 0
	v_mov_b32_e32 v70, 0
	v_mov_b32_e32 v71, 0
	v_mov_b32_e32 v72, 0
	v_mov_b32_e32 v73, 0
	v_mov_b32_e32 v74, 0
	v_mov_b32_e32 v75, 0
	v_mov_b32_e32 v76, 0
	v_mov_b32_e32 v77, 0
	v_mov_b32_e32 v78, 0
	v_mov_b32_e32 v79, 0
	v_mov_b32_e32 v80, 0
	v_mov_b32_e32 v81, 0
	v_mov_b32_e32 v82, 0
	v_mov_b32_e32 v83, 0
	v_mov_b32_e32 v84, 0
	v_mov_b32_e32 v85, 0
	v_mov_b32_e32 v86, 0
	v_mov_b32_e32 v87, 0
	v_mov_b32_e32 v88, 0
	v_mov_b32_e32 v89, 0
	v_mov_b32_e32 v90, 0
	v_mov_b32_e32 v91, 0
	v_mov_b32_e32 v92, 0
	v_mov_b32_e32 v93, 0
	v_mov_b32_e32 v94, 0
	v_mov_b32_e32 v95, 0
	v_mov_b32_e32 v96, 0
	v_mov_b32_e32 v97, 0
	v_mov_b32_e32 v98, 0
	v_mov_b32_e32 v99, 0
	v_mov_b32_e32 v100, 0
	v_mov_b32_e32 v101, 0
	v_mov_b32_e32 v102, 0
	v_mov_b32_e32 v103, 0
	v_mov_b32_e32 v104, 0
	v_mov_b32_e32 v105, 0
	v_mov_b32_e32 v106, 0
	v_mov_b32_e32 v107, 0
	v_mov_b32_e32 v108, 0
	v_mov_b32_e32 v109, 0
	v_mov_b32_e32 v110, 0
	v_mov_b32_e32 v111, 0
	v_mov_b32_e32 v112, 0
	v_mov_b32_e32 v113, 0
	v_mov_b32_e32 v114, 0
	v_mov_b32_e32 v115, 0
	v_mov_b32_e32 v116, 0
	v_mov_b32_e32 v117, 0
	v_mov_b32_e32 v118, 0
	v_mov_b32_e32 v119, 0
	v_mov_b32_e32 v120, 0
	v_mov_b32_e32 v121, 0
	v_mov_b32_e32 v122, 0
	v_mov_b32_e32 v123, 0
	v_mov_b32_e32 v124, 0
	v_mov_b32_e32 v125, 0
	v_mov_b32_e32 v126, 0
	v_mov_b32_e32 v127, 0
	s_mov_b32 s3, 0
	s_waitcnt vmcnt(10)
	s_barrier
.Lg16_out_k:
	s_add_i32 s9, s3, 2
	s_lshl_b32 s96, s9, 13
	s_add_i32 m0, vcc_lo, 16384
	v_lshl_add_u64 v[248:249], v[188:189], 0, s[96:97]
	global_load_lds_dwordx4 v[248:249], off
	global_load_lds_dwordx4 v[248:249], off offset:1024
	ds_read_b128 v[196:199], v246 offset:0
	ds_read_b128 v[200:203], v246 offset:1024
	ds_read_b128 v[204:207], v246 offset:2048
	ds_read_b128 v[242:245], v246 offset:3072
	s_add_i32 s9, s3, 3
	s_min_u32 s9, s9, 31
	s_lshl_b32 s96, s9, 11
	v_lshl_add_u64 v[248:249], v[184:185], 0, s[96:97]
	v_lshl_add_u64 v[250:251], v[186:187], 0, s[96:97]
	s_waitcnt lgkmcnt(3)
	v_mfma_f32_16x16x32_bf16 v[112:115], v[128:131], v[196:199], v[112:115]
	v_mfma_f32_16x16x32_bf16 v[120:123], v[132:135], v[196:199], v[120:123]
	v_mfma_f32_16x16x32_bf16 v[48:51], v[136:139], v[196:199], v[48:51]
	v_mfma_f32_16x16x32_bf16 v[56:59], v[140:143], v[196:199], v[56:59]
	ds_read_b128 v[196:199], v246 offset:4096
	s_waitcnt lgkmcnt(3)
	v_mfma_f32_16x16x32_bf16 v[116:119], v[128:131], v[200:203], v[116:119]
	v_mfma_f32_16x16x32_bf16 v[124:127], v[132:135], v[200:203], v[124:127]
	v_mfma_f32_16x16x32_bf16 v[52:55], v[136:139], v[200:203], v[52:55]
	v_mfma_f32_16x16x32_bf16 v[60:63], v[140:143], v[200:203], v[60:63]
	ds_read_b128 v[200:203], v246 offset:5120
	s_waitcnt lgkmcnt(3)
	v_mfma_f32_16x16x32_bf16 v[96:99], v[128:131], v[204:207], v[96:99]
	v_mfma_f32_16x16x32_bf16 v[104:107], v[132:135], v[204:207], v[104:107]
	v_mfma_f32_16x16x32_bf16 v[32:35], v[136:139], v[204:207], v[32:35]
	v_mfma_f32_16x16x32_bf16 v[40:43], v[140:143], v[204:207], v[40:43]
	ds_read_b128 v[204:207], v246 offset:6144
	s_waitcnt lgkmcnt(3)
	v_mfma_f32_16x16x32_bf16 v[100:103], v[128:131], v[242:245], v[100:103]
	v_mfma_f32_16x16x32_bf16 v[108:111], v[132:135], v[242:245], v[108:111]
	v_mfma_f32_16x16x32_bf16 v[36:39], v[136:139], v[242:245], v[36:39]
	v_mfma_f32_16x16x32_bf16 v[44:47], v[140:143], v[242:245], v[44:47]
	ds_read_b128 v[242:245], v246 offset:7168
	s_waitcnt lgkmcnt(3)
	v_mfma_f32_16x16x32_bf16 v[80:83], v[128:131], v[196:199], v[80:83]
	v_mfma_f32_16x16x32_bf16 v[88:91], v[132:135], v[196:199], v[88:91]
	v_mfma_f32_16x16x32_bf16 v[16:19], v[136:139], v[196:199], v[16:19]
	v_mfma_f32_16x16x32_bf16 v[24:27], v[140:143], v[196:199], v[24:27]
	s_waitcnt lgkmcnt(2)
	v_mfma_f32_16x16x32_bf16 v[84:87], v[128:131], v[200:203], v[84:87]
	v_mfma_f32_16x16x32_bf16 v[92:95], v[132:135], v[200:203], v[92:95]
	v_mfma_f32_16x16x32_bf16 v[20:23], v[136:139], v[200:203], v[20:23]
	v_mfma_f32_16x16x32_bf16 v[28:31], v[140:143], v[200:203], v[28:31]
	s_waitcnt lgkmcnt(1)
	v_mfma_f32_16x16x32_bf16 v[64:67], v[128:131], v[204:207], v[64:67]
	v_mfma_f32_16x16x32_bf16 v[72:75], v[132:135], v[204:207], v[72:75]
	v_mfma_f32_16x16x32_bf16 v[0:3], v[136:139], v[204:207], v[0:3]
	v_mfma_f32_16x16x32_bf16 v[8:11], v[140:143], v[204:207], v[8:11]
	s_waitcnt lgkmcnt(0)
	v_mfma_f32_16x16x32_bf16 v[68:71], v[128:131], v[242:245], v[68:71]
	v_mfma_f32_16x16x32_bf16 v[76:79], v[132:135], v[242:245], v[76:79]
	v_mfma_f32_16x16x32_bf16 v[4:7], v[136:139], v[242:245], v[4:7]
	v_mfma_f32_16x16x32_bf16 v[12:15], v[140:143], v[242:245], v[12:15]
	global_load_dwordx4 v[128:131], v[248:249], off
	global_load_dwordx4 v[132:135], v[248:249], off offset:256
	global_load_dwordx4 v[136:139], v[250:251], off
	global_load_dwordx4 v[140:143], v[250:251], off offset:256
	s_waitcnt vmcnt(10)
	s_barrier
	s_add_i32 s9, s3, 3
	s_lshl_b32 s96, s9, 13
	s_mov_b32 m0, vcc_lo
	v_lshl_add_u64 v[248:249], v[188:189], 0, s[96:97]
	global_load_lds_dwordx4 v[248:249], off
	global_load_lds_dwordx4 v[248:249], off offset:1024
	ds_read_b128 v[196:199], v246 offset:8192
	ds_read_b128 v[200:203], v246 offset:9216
	ds_read_b128 v[204:207], v246 offset:10240
	ds_read_b128 v[242:245], v246 offset:11264
	s_add_i32 s9, s3, 4
	s_min_u32 s9, s9, 31
	s_lshl_b32 s96, s9, 11
	v_lshl_add_u64 v[248:249], v[184:185], 0, s[96:97]
	v_lshl_add_u64 v[250:251], v[186:187], 0, s[96:97]
	s_waitcnt lgkmcnt(3)
	v_mfma_f32_16x16x32_bf16 v[112:115], v[144:147], v[196:199], v[112:115]
	v_mfma_f32_16x16x32_bf16 v[120:123], v[148:151], v[196:199], v[120:123]
	v_mfma_f32_16x16x32_bf16 v[48:51], v[152:155], v[196:199], v[48:51]
	v_mfma_f32_16x16x32_bf16 v[56:59], v[156:159], v[196:199], v[56:59]
	ds_read_b128 v[196:199], v246 offset:12288
	s_waitcnt lgkmcnt(3)
	v_mfma_f32_16x16x32_bf16 v[116:119], v[144:147], v[200:203], v[116:119]
	v_mfma_f32_16x16x32_bf16 v[124:127], v[148:151], v[200:203], v[124:127]
	v_mfma_f32_16x16x32_bf16 v[52:55], v[152:155], v[200:203], v[52:55]
	v_mfma_f32_16x16x32_bf16 v[60:63], v[156:159], v[200:203], v[60:63]
	ds_read_b128 v[200:203], v246 offset:13312
	s_waitcnt lgkmcnt(3)
	v_mfma_f32_16x16x32_bf16 v[96:99], v[144:147], v[204:207], v[96:99]
	v_mfma_f32_16x16x32_bf16 v[104:107], v[148:151], v[204:207], v[104:107]
	v_mfma_f32_16x16x32_bf16 v[32:35], v[152:155], v[204:207], v[32:35]
	v_mfma_f32_16x16x32_bf16 v[40:43], v[156:159], v[204:207], v[40:43]
	ds_read_b128 v[204:207], v246 offset:14336
	s_waitcnt lgkmcnt(3)
	v_mfma_f32_16x16x32_bf16 v[100:103], v[144:147], v[242:245], v[100:103]
	v_mfma_f32_16x16x32_bf16 v[108:111], v[148:151], v[242:245], v[108:111]
	v_mfma_f32_16x16x32_bf16 v[36:39], v[152:155], v[242:245], v[36:39]
	v_mfma_f32_16x16x32_bf16 v[44:47], v[156:159], v[242:245], v[44:47]
	ds_read_b128 v[242:245], v246 offset:15360
	s_waitcnt lgkmcnt(3)
	v_mfma_f32_16x16x32_bf16 v[80:83], v[144:147], v[196:199], v[80:83]
	v_mfma_f32_16x16x32_bf16 v[88:91], v[148:151], v[196:199], v[88:91]
	v_mfma_f32_16x16x32_bf16 v[16:19], v[152:155], v[196:199], v[16:19]
	v_mfma_f32_16x16x32_bf16 v[24:27], v[156:159], v[196:199], v[24:27]
	s_waitcnt lgkmcnt(2)
	v_mfma_f32_16x16x32_bf16 v[84:87], v[144:147], v[200:203], v[84:87]
	v_mfma_f32_16x16x32_bf16 v[92:95], v[148:151], v[200:203], v[92:95]
	v_mfma_f32_16x16x32_bf16 v[20:23], v[152:155], v[200:203], v[20:23]
	v_mfma_f32_16x16x32_bf16 v[28:31], v[156:159], v[200:203], v[28:31]
	s_waitcnt lgkmcnt(1)
	v_mfma_f32_16x16x32_bf16 v[64:67], v[144:147], v[204:207], v[64:67]
	v_mfma_f32_16x16x32_bf16 v[72:75], v[148:151], v[204:207], v[72:75]
	v_mfma_f32_16x16x32_bf16 v[0:3], v[152:155], v[204:207], v[0:3]
	v_mfma_f32_16x16x32_bf16 v[8:11], v[156:159], v[204:207], v[8:11]
	s_waitcnt lgkmcnt(0)
	v_mfma_f32_16x16x32_bf16 v[68:71], v[144:147], v[242:245], v[68:71]
	v_mfma_f32_16x16x32_bf16 v[76:79], v[148:151], v[242:245], v[76:79]
	v_mfma_f32_16x16x32_bf16 v[4:7], v[152:155], v[242:245], v[4:7]
	v_mfma_f32_16x16x32_bf16 v[12:15], v[156:159], v[242:245], v[12:15]
	global_load_dwordx4 v[144:147], v[248:249], off
	global_load_dwordx4 v[148:151], v[248:249], off offset:256
	global_load_dwordx4 v[152:155], v[250:251], off
	global_load_dwordx4 v[156:159], v[250:251], off offset:256
	s_waitcnt vmcnt(10)
	s_barrier
	s_add_i32 s9, s3, 4
	s_lshl_b32 s96, s9, 13
	s_add_i32 m0, vcc_lo, 8192
	v_lshl_add_u64 v[248:249], v[188:189], 0, s[96:97]
	global_load_lds_dwordx4 v[248:249], off
	global_load_lds_dwordx4 v[248:249], off offset:1024
	ds_read_b128 v[196:199], v246 offset:16384
	ds_read_b128 v[200:203], v246 offset:17408
	ds_read_b128 v[204:207], v246 offset:18432
	ds_read_b128 v[242:245], v246 offset:19456
	s_add_i32 s9, s3, 5
	s_min_u32 s9, s9, 31
	s_lshl_b32 s96, s9, 11
	v_lshl_add_u64 v[248:249], v[184:185], 0, s[96:97]
	v_lshl_add_u64 v[250:251], v[186:187], 0, s[96:97]
	s_waitcnt lgkmcnt(3)
	v_mfma_f32_16x16x32_bf16 v[112:115], v[160:163], v[196:199], v[112:115]
	v_mfma_f32_16x16x32_bf16 v[120:123], v[164:167], v[196:199], v[120:123]
	v_mfma_f32_16x16x32_bf16 v[48:51], v[168:171], v[196:199], v[48:51]
	v_mfma_f32_16x16x32_bf16 v[56:59], v[172:175], v[196:199], v[56:59]
	ds_read_b128 v[196:199], v246 offset:20480
	s_waitcnt lgkmcnt(3)
	v_mfma_f32_16x16x32_bf16 v[116:119], v[160:163], v[200:203], v[116:119]
	v_mfma_f32_16x16x32_bf16 v[124:127], v[164:167], v[200:203], v[124:127]
	v_mfma_f32_16x16x32_bf16 v[52:55], v[168:171], v[200:203], v[52:55]
	v_mfma_f32_16x16x32_bf16 v[60:63], v[172:175], v[200:203], v[60:63]
	ds_read_b128 v[200:203], v246 offset:21504
	s_waitcnt lgkmcnt(3)
	v_mfma_f32_16x16x32_bf16 v[96:99], v[160:163], v[204:207], v[96:99]
	v_mfma_f32_16x16x32_bf16 v[104:107], v[164:167], v[204:207], v[104:107]
	v_mfma_f32_16x16x32_bf16 v[32:35], v[168:171], v[204:207], v[32:35]
	v_mfma_f32_16x16x32_bf16 v[40:43], v[172:175], v[204:207], v[40:43]
	ds_read_b128 v[204:207], v246 offset:22528
	s_waitcnt lgkmcnt(3)
	v_mfma_f32_16x16x32_bf16 v[100:103], v[160:163], v[242:245], v[100:103]
	v_mfma_f32_16x16x32_bf16 v[108:111], v[164:167], v[242:245], v[108:111]
	v_mfma_f32_16x16x32_bf16 v[36:39], v[168:171], v[242:245], v[36:39]
	v_mfma_f32_16x16x32_bf16 v[44:47], v[172:175], v[242:245], v[44:47]
	ds_read_b128 v[242:245], v246 offset:23552
	s_waitcnt lgkmcnt(3)
	v_mfma_f32_16x16x32_bf16 v[80:83], v[160:163], v[196:199], v[80:83]
	v_mfma_f32_16x16x32_bf16 v[88:91], v[164:167], v[196:199], v[88:91]
	v_mfma_f32_16x16x32_bf16 v[16:19], v[168:171], v[196:199], v[16:19]
	v_mfma_f32_16x16x32_bf16 v[24:27], v[172:175], v[196:199], v[24:27]
	s_waitcnt lgkmcnt(2)
	v_mfma_f32_16x16x32_bf16 v[84:87], v[160:163], v[200:203], v[84:87]
	v_mfma_f32_16x16x32_bf16 v[92:95], v[164:167], v[200:203], v[92:95]
	v_mfma_f32_16x16x32_bf16 v[20:23], v[168:171], v[200:203], v[20:23]
	v_mfma_f32_16x16x32_bf16 v[28:31], v[172:175], v[200:203], v[28:31]
	s_waitcnt lgkmcnt(1)
	v_mfma_f32_16x16x32_bf16 v[64:67], v[160:163], v[204:207], v[64:67]
	v_mfma_f32_16x16x32_bf16 v[72:75], v[164:167], v[204:207], v[72:75]
	v_mfma_f32_16x16x32_bf16 v[0:3], v[168:171], v[204:207], v[0:3]
	v_mfma_f32_16x16x32_bf16 v[8:11], v[172:175], v[204:207], v[8:11]
	s_waitcnt lgkmcnt(0)
	v_mfma_f32_16x16x32_bf16 v[68:71], v[160:163], v[242:245], v[68:71]
	v_mfma_f32_16x16x32_bf16 v[76:79], v[164:167], v[242:245], v[76:79]
	v_mfma_f32_16x16x32_bf16 v[4:7], v[168:171], v[242:245], v[4:7]
	v_mfma_f32_16x16x32_bf16 v[12:15], v[172:175], v[242:245], v[12:15]
	global_load_dwordx4 v[160:163], v[248:249], off
	global_load_dwordx4 v[164:167], v[248:249], off offset:256
	global_load_dwordx4 v[168:171], v[250:251], off
	global_load_dwordx4 v[172:175], v[250:251], off offset:256
	s_waitcnt vmcnt(10)
	s_barrier
	s_add_i32 s9, s3, 5
	s_lshl_b32 s96, s9, 13
	s_add_i32 m0, vcc_lo, 16384
	v_lshl_add_u64 v[248:249], v[188:189], 0, s[96:97]
	global_load_lds_dwordx4 v[248:249], off
	global_load_lds_dwordx4 v[248:249], off offset:1024
	ds_read_b128 v[196:199], v246 offset:0
	ds_read_b128 v[200:203], v246 offset:1024
	ds_read_b128 v[204:207], v246 offset:2048
	ds_read_b128 v[242:245], v246 offset:3072
	s_add_i32 s9, s3, 6
	s_min_u32 s9, s9, 31
	s_lshl_b32 s96, s9, 11
	v_lshl_add_u64 v[248:249], v[184:185], 0, s[96:97]
	v_lshl_add_u64 v[250:251], v[186:187], 0, s[96:97]
	s_waitcnt lgkmcnt(3)
	v_mfma_f32_16x16x32_bf16 v[112:115], v[128:131], v[196:199], v[112:115]
	v_mfma_f32_16x16x32_bf16 v[120:123], v[132:135], v[196:199], v[120:123]
	v_mfma_f32_16x16x32_bf16 v[48:51], v[136:139], v[196:199], v[48:51]
	v_mfma_f32_16x16x32_bf16 v[56:59], v[140:143], v[196:199], v[56:59]
	ds_read_b128 v[196:199], v246 offset:4096
	s_waitcnt lgkmcnt(3)
	v_mfma_f32_16x16x32_bf16 v[116:119], v[128:131], v[200:203], v[116:119]
	v_mfma_f32_16x16x32_bf16 v[124:127], v[132:135], v[200:203], v[124:127]
	v_mfma_f32_16x16x32_bf16 v[52:55], v[136:139], v[200:203], v[52:55]
	v_mfma_f32_16x16x32_bf16 v[60:63], v[140:143], v[200:203], v[60:63]
	ds_read_b128 v[200:203], v246 offset:5120
	s_waitcnt lgkmcnt(3)
	v_mfma_f32_16x16x32_bf16 v[96:99], v[128:131], v[204:207], v[96:99]
	v_mfma_f32_16x16x32_bf16 v[104:107], v[132:135], v[204:207], v[104:107]
	v_mfma_f32_16x16x32_bf16 v[32:35], v[136:139], v[204:207], v[32:35]
	v_mfma_f32_16x16x32_bf16 v[40:43], v[140:143], v[204:207], v[40:43]
	ds_read_b128 v[204:207], v246 offset:6144
	s_waitcnt lgkmcnt(3)
	v_mfma_f32_16x16x32_bf16 v[100:103], v[128:131], v[242:245], v[100:103]
	v_mfma_f32_16x16x32_bf16 v[108:111], v[132:135], v[242:245], v[108:111]
	v_mfma_f32_16x16x32_bf16 v[36:39], v[136:139], v[242:245], v[36:39]
	v_mfma_f32_16x16x32_bf16 v[44:47], v[140:143], v[242:245], v[44:47]
	ds_read_b128 v[242:245], v246 offset:7168
	s_waitcnt lgkmcnt(3)
	v_mfma_f32_16x16x32_bf16 v[80:83], v[128:131], v[196:199], v[80:83]
	v_mfma_f32_16x16x32_bf16 v[88:91], v[132:135], v[196:199], v[88:91]
	v_mfma_f32_16x16x32_bf16 v[16:19], v[136:139], v[196:199], v[16:19]
	v_mfma_f32_16x16x32_bf16 v[24:27], v[140:143], v[196:199], v[24:27]
	s_waitcnt lgkmcnt(2)
	v_mfma_f32_16x16x32_bf16 v[84:87], v[128:131], v[200:203], v[84:87]
	v_mfma_f32_16x16x32_bf16 v[92:95], v[132:135], v[200:203], v[92:95]
	v_mfma_f32_16x16x32_bf16 v[20:23], v[136:139], v[200:203], v[20:23]
	v_mfma_f32_16x16x32_bf16 v[28:31], v[140:143], v[200:203], v[28:31]
	s_waitcnt lgkmcnt(1)
	v_mfma_f32_16x16x32_bf16 v[64:67], v[128:131], v[204:207], v[64:67]
	v_mfma_f32_16x16x32_bf16 v[72:75], v[132:135], v[204:207], v[72:75]
	v_mfma_f32_16x16x32_bf16 v[0:3], v[136:139], v[204:207], v[0:3]
	v_mfma_f32_16x16x32_bf16 v[8:11], v[140:143], v[204:207], v[8:11]
	s_waitcnt lgkmcnt(0)
	v_mfma_f32_16x16x32_bf16 v[68:71], v[128:131], v[242:245], v[68:71]
	v_mfma_f32_16x16x32_bf16 v[76:79], v[132:135], v[242:245], v[76:79]
	v_mfma_f32_16x16x32_bf16 v[4:7], v[136:139], v[242:245], v[4:7]
	v_mfma_f32_16x16x32_bf16 v[12:15], v[140:143], v[242:245], v[12:15]
	global_load_dwordx4 v[128:131], v[248:249], off
	global_load_dwordx4 v[132:135], v[248:249], off offset:256
	global_load_dwordx4 v[136:139], v[250:251], off
	global_load_dwordx4 v[140:143], v[250:251], off offset:256
	s_waitcnt vmcnt(10)
	s_barrier
	s_add_i32 s9, s3, 6
	s_lshl_b32 s96, s9, 13
	s_mov_b32 m0, vcc_lo
	v_lshl_add_u64 v[248:249], v[188:189], 0, s[96:97]
	global_load_lds_dwordx4 v[248:249], off
	global_load_lds_dwordx4 v[248:249], off offset:1024
	ds_read_b128 v[196:199], v246 offset:8192
	ds_read_b128 v[200:203], v246 offset:9216
	ds_read_b128 v[204:207], v246 offset:10240
	ds_read_b128 v[242:245], v246 offset:11264
	s_add_i32 s9, s3, 7
	s_min_u32 s9, s9, 31
	s_lshl_b32 s96, s9, 11
	v_lshl_add_u64 v[248:249], v[184:185], 0, s[96:97]
	v_lshl_add_u64 v[250:251], v[186:187], 0, s[96:97]
	s_waitcnt lgkmcnt(3)
	v_mfma_f32_16x16x32_bf16 v[112:115], v[144:147], v[196:199], v[112:115]
	v_mfma_f32_16x16x32_bf16 v[120:123], v[148:151], v[196:199], v[120:123]
	v_mfma_f32_16x16x32_bf16 v[48:51], v[152:155], v[196:199], v[48:51]
	v_mfma_f32_16x16x32_bf16 v[56:59], v[156:159], v[196:199], v[56:59]
	ds_read_b128 v[196:199], v246 offset:12288
	s_waitcnt lgkmcnt(3)
	v_mfma_f32_16x16x32_bf16 v[116:119], v[144:147], v[200:203], v[116:119]
	v_mfma_f32_16x16x32_bf16 v[124:127], v[148:151], v[200:203], v[124:127]
	v_mfma_f32_16x16x32_bf16 v[52:55], v[152:155], v[200:203], v[52:55]
	v_mfma_f32_16x16x32_bf16 v[60:63], v[156:159], v[200:203], v[60:63]
	ds_read_b128 v[200:203], v246 offset:13312
	s_waitcnt lgkmcnt(3)
	v_mfma_f32_16x16x32_bf16 v[96:99], v[144:147], v[204:207], v[96:99]
	v_mfma_f32_16x16x32_bf16 v[104:107], v[148:151], v[204:207], v[104:107]
	v_mfma_f32_16x16x32_bf16 v[32:35], v[152:155], v[204:207], v[32:35]
	v_mfma_f32_16x16x32_bf16 v[40:43], v[156:159], v[204:207], v[40:43]
	ds_read_b128 v[204:207], v246 offset:14336
	s_waitcnt lgkmcnt(3)
	v_mfma_f32_16x16x32_bf16 v[100:103], v[144:147], v[242:245], v[100:103]
	v_mfma_f32_16x16x32_bf16 v[108:111], v[148:151], v[242:245], v[108:111]
	v_mfma_f32_16x16x32_bf16 v[36:39], v[152:155], v[242:245], v[36:39]
	v_mfma_f32_16x16x32_bf16 v[44:47], v[156:159], v[242:245], v[44:47]
	ds_read_b128 v[242:245], v246 offset:15360
	s_waitcnt lgkmcnt(3)
	v_mfma_f32_16x16x32_bf16 v[80:83], v[144:147], v[196:199], v[80:83]
	v_mfma_f32_16x16x32_bf16 v[88:91], v[148:151], v[196:199], v[88:91]
	v_mfma_f32_16x16x32_bf16 v[16:19], v[152:155], v[196:199], v[16:19]
	v_mfma_f32_16x16x32_bf16 v[24:27], v[156:159], v[196:199], v[24:27]
	s_waitcnt lgkmcnt(2)
	v_mfma_f32_16x16x32_bf16 v[84:87], v[144:147], v[200:203], v[84:87]
	v_mfma_f32_16x16x32_bf16 v[92:95], v[148:151], v[200:203], v[92:95]
	v_mfma_f32_16x16x32_bf16 v[20:23], v[152:155], v[200:203], v[20:23]
	v_mfma_f32_16x16x32_bf16 v[28:31], v[156:159], v[200:203], v[28:31]
	s_waitcnt lgkmcnt(1)
	v_mfma_f32_16x16x32_bf16 v[64:67], v[144:147], v[204:207], v[64:67]
	v_mfma_f32_16x16x32_bf16 v[72:75], v[148:151], v[204:207], v[72:75]
	v_mfma_f32_16x16x32_bf16 v[0:3], v[152:155], v[204:207], v[0:3]
	v_mfma_f32_16x16x32_bf16 v[8:11], v[156:159], v[204:207], v[8:11]
	s_waitcnt lgkmcnt(0)
	v_mfma_f32_16x16x32_bf16 v[68:71], v[144:147], v[242:245], v[68:71]
	v_mfma_f32_16x16x32_bf16 v[76:79], v[148:151], v[242:245], v[76:79]
	v_mfma_f32_16x16x32_bf16 v[4:7], v[152:155], v[242:245], v[4:7]
	v_mfma_f32_16x16x32_bf16 v[12:15], v[156:159], v[242:245], v[12:15]
	global_load_dwordx4 v[144:147], v[248:249], off
	global_load_dwordx4 v[148:151], v[248:249], off offset:256
	global_load_dwordx4 v[152:155], v[250:251], off
	global_load_dwordx4 v[156:159], v[250:251], off offset:256
	s_waitcnt vmcnt(10)
	s_barrier
	s_add_i32 s9, s3, 7
	s_lshl_b32 s96, s9, 13
	s_add_i32 m0, vcc_lo, 8192
	v_lshl_add_u64 v[248:249], v[188:189], 0, s[96:97]
	global_load_lds_dwordx4 v[248:249], off
	global_load_lds_dwordx4 v[248:249], off offset:1024
	ds_read_b128 v[196:199], v246 offset:16384
	ds_read_b128 v[200:203], v246 offset:17408
	ds_read_b128 v[204:207], v246 offset:18432
	ds_read_b128 v[242:245], v246 offset:19456
	s_add_i32 s9, s3, 8
	s_min_u32 s9, s9, 31
	s_lshl_b32 s96, s9, 11
	v_lshl_add_u64 v[248:249], v[184:185], 0, s[96:97]
	v_lshl_add_u64 v[250:251], v[186:187], 0, s[96:97]
	s_waitcnt lgkmcnt(3)
	v_mfma_f32_16x16x32_bf16 v[112:115], v[160:163], v[196:199], v[112:115]
	v_mfma_f32_16x16x32_bf16 v[120:123], v[164:167], v[196:199], v[120:123]
	v_mfma_f32_16x16x32_bf16 v[48:51], v[168:171], v[196:199], v[48:51]
	v_mfma_f32_16x16x32_bf16 v[56:59], v[172:175], v[196:199], v[56:59]
	ds_read_b128 v[196:199], v246 offset:20480
	s_waitcnt lgkmcnt(3)
	v_mfma_f32_16x16x32_bf16 v[116:119], v[160:163], v[200:203], v[116:119]
	v_mfma_f32_16x16x32_bf16 v[124:127], v[164:167], v[200:203], v[124:127]
	v_mfma_f32_16x16x32_bf16 v[52:55], v[168:171], v[200:203], v[52:55]
	v_mfma_f32_16x16x32_bf16 v[60:63], v[172:175], v[200:203], v[60:63]
	ds_read_b128 v[200:203], v246 offset:21504
	s_waitcnt lgkmcnt(3)
	v_mfma_f32_16x16x32_bf16 v[96:99], v[160:163], v[204:207], v[96:99]
	v_mfma_f32_16x16x32_bf16 v[104:107], v[164:167], v[204:207], v[104:107]
	v_mfma_f32_16x16x32_bf16 v[32:35], v[168:171], v[204:207], v[32:35]
	v_mfma_f32_16x16x32_bf16 v[40:43], v[172:175], v[204:207], v[40:43]
	ds_read_b128 v[204:207], v246 offset:22528
	s_waitcnt lgkmcnt(3)
	v_mfma_f32_16x16x32_bf16 v[100:103], v[160:163], v[242:245], v[100:103]
	v_mfma_f32_16x16x32_bf16 v[108:111], v[164:167], v[242:245], v[108:111]
	v_mfma_f32_16x16x32_bf16 v[36:39], v[168:171], v[242:245], v[36:39]
	v_mfma_f32_16x16x32_bf16 v[44:47], v[172:175], v[242:245], v[44:47]
	ds_read_b128 v[242:245], v246 offset:23552
	s_waitcnt lgkmcnt(3)
	v_mfma_f32_16x16x32_bf16 v[80:83], v[160:163], v[196:199], v[80:83]
	v_mfma_f32_16x16x32_bf16 v[88:91], v[164:167], v[196:199], v[88:91]
	v_mfma_f32_16x16x32_bf16 v[16:19], v[168:171], v[196:199], v[16:19]
	v_mfma_f32_16x16x32_bf16 v[24:27], v[172:175], v[196:199], v[24:27]
	s_waitcnt lgkmcnt(2)
	v_mfma_f32_16x16x32_bf16 v[84:87], v[160:163], v[200:203], v[84:87]
	v_mfma_f32_16x16x32_bf16 v[92:95], v[164:167], v[200:203], v[92:95]
	v_mfma_f32_16x16x32_bf16 v[20:23], v[168:171], v[200:203], v[20:23]
	v_mfma_f32_16x16x32_bf16 v[28:31], v[172:175], v[200:203], v[28:31]
	s_waitcnt lgkmcnt(1)
	v_mfma_f32_16x16x32_bf16 v[64:67], v[160:163], v[204:207], v[64:67]
	v_mfma_f32_16x16x32_bf16 v[72:75], v[164:167], v[204:207], v[72:75]
	v_mfma_f32_16x16x32_bf16 v[0:3], v[168:171], v[204:207], v[0:3]
	v_mfma_f32_16x16x32_bf16 v[8:11], v[172:175], v[204:207], v[8:11]
	s_waitcnt lgkmcnt(0)
	v_mfma_f32_16x16x32_bf16 v[68:71], v[160:163], v[242:245], v[68:71]
	v_mfma_f32_16x16x32_bf16 v[76:79], v[164:167], v[242:245], v[76:79]
	v_mfma_f32_16x16x32_bf16 v[4:7], v[168:171], v[242:245], v[4:7]
	v_mfma_f32_16x16x32_bf16 v[12:15], v[172:175], v[242:245], v[12:15]
	global_load_dwordx4 v[160:163], v[248:249], off
	global_load_dwordx4 v[164:167], v[248:249], off offset:256
	global_load_dwordx4 v[168:171], v[250:251], off
	global_load_dwordx4 v[172:175], v[250:251], off offset:256
	s_waitcnt vmcnt(10)
	s_barrier
	s_add_i32 s3, s3, 6
	s_cmp_lt_u32 s3, 30
	s_cbranch_scc1 .Lg16_out_k
	ds_read_b128 v[196:199], v246 offset:0
	ds_read_b128 v[200:203], v246 offset:1024
	ds_read_b128 v[204:207], v246 offset:2048
	ds_read_b128 v[242:245], v246 offset:3072
	s_waitcnt lgkmcnt(3)
	v_mfma_f32_16x16x32_bf16 v[112:115], v[128:131], v[196:199], v[112:115]
	v_mfma_f32_16x16x32_bf16 v[120:123], v[132:135], v[196:199], v[120:123]
	v_mfma_f32_16x16x32_bf16 v[48:51], v[136:139], v[196:199], v[48:51]
	v_mfma_f32_16x16x32_bf16 v[56:59], v[140:143], v[196:199], v[56:59]
	ds_read_b128 v[196:199], v246 offset:4096
	s_waitcnt lgkmcnt(3)
	v_mfma_f32_16x16x32_bf16 v[116:119], v[128:131], v[200:203], v[116:119]
	v_mfma_f32_16x16x32_bf16 v[124:127], v[132:135], v[200:203], v[124:127]
	v_mfma_f32_16x16x32_bf16 v[52:55], v[136:139], v[200:203], v[52:55]
	v_mfma_f32_16x16x32_bf16 v[60:63], v[140:143], v[200:203], v[60:63]
	ds_read_b128 v[200:203], v246 offset:5120
	s_waitcnt lgkmcnt(3)
	v_mfma_f32_16x16x32_bf16 v[96:99], v[128:131], v[204:207], v[96:99]
	v_mfma_f32_16x16x32_bf16 v[104:107], v[132:135], v[204:207], v[104:107]
	v_mfma_f32_16x16x32_bf16 v[32:35], v[136:139], v[204:207], v[32:35]
	v_mfma_f32_16x16x32_bf16 v[40:43], v[140:143], v[204:207], v[40:43]
	ds_read_b128 v[204:207], v246 offset:6144
	s_waitcnt lgkmcnt(3)
	v_mfma_f32_16x16x32_bf16 v[100:103], v[128:131], v[242:245], v[100:103]
	v_mfma_f32_16x16x32_bf16 v[108:111], v[132:135], v[242:245], v[108:111]
	v_mfma_f32_16x16x32_bf16 v[36:39], v[136:139], v[242:245], v[36:39]
	v_mfma_f32_16x16x32_bf16 v[44:47], v[140:143], v[242:245], v[44:47]
	ds_read_b128 v[242:245], v246 offset:7168
	s_waitcnt lgkmcnt(3)
	v_mfma_f32_16x16x32_bf16 v[80:83], v[128:131], v[196:199], v[80:83]
	v_mfma_f32_16x16x32_bf16 v[88:91], v[132:135], v[196:199], v[88:91]
	v_mfma_f32_16x16x32_bf16 v[16:19], v[136:139], v[196:199], v[16:19]
	v_mfma_f32_16x16x32_bf16 v[24:27], v[140:143], v[196:199], v[24:27]
	s_waitcnt lgkmcnt(2)
	v_mfma_f32_16x16x32_bf16 v[84:87], v[128:131], v[200:203], v[84:87]
	v_mfma_f32_16x16x32_bf16 v[92:95], v[132:135], v[200:203], v[92:95]
	v_mfma_f32_16x16x32_bf16 v[20:23], v[136:139], v[200:203], v[20:23]
	v_mfma_f32_16x16x32_bf16 v[28:31], v[140:143], v[200:203], v[28:31]
	s_waitcnt lgkmcnt(1)
	v_mfma_f32_16x16x32_bf16 v[64:67], v[128:131], v[204:207], v[64:67]
	v_mfma_f32_16x16x32_bf16 v[72:75], v[132:135], v[204:207], v[72:75]
	v_mfma_f32_16x16x32_bf16 v[0:3], v[136:139], v[204:207], v[0:3]
	v_mfma_f32_16x16x32_bf16 v[8:11], v[140:143], v[204:207], v[8:11]
	s_waitcnt lgkmcnt(0)
	v_mfma_f32_16x16x32_bf16 v[68:71], v[128:131], v[242:245], v[68:71]
	v_mfma_f32_16x16x32_bf16 v[76:79], v[132:135], v[242:245], v[76:79]
	v_mfma_f32_16x16x32_bf16 v[4:7], v[136:139], v[242:245], v[4:7]
	v_mfma_f32_16x16x32_bf16 v[12:15], v[140:143], v[242:245], v[12:15]
	s_waitcnt vmcnt(4)
	s_barrier
	ds_read_b128 v[196:199], v246 offset:8192
	ds_read_b128 v[200:203], v246 offset:9216
	ds_read_b128 v[204:207], v246 offset:10240
	ds_read_b128 v[242:245], v246 offset:11264
	s_waitcnt lgkmcnt(3)
	v_mfma_f32_16x16x32_bf16 v[112:115], v[144:147], v[196:199], v[112:115]
	v_mfma_f32_16x16x32_bf16 v[120:123], v[148:151], v[196:199], v[120:123]
	v_mfma_f32_16x16x32_bf16 v[48:51], v[152:155], v[196:199], v[48:51]
	v_mfma_f32_16x16x32_bf16 v[56:59], v[156:159], v[196:199], v[56:59]
	ds_read_b128 v[196:199], v246 offset:12288
	s_waitcnt lgkmcnt(3)
	v_mfma_f32_16x16x32_bf16 v[116:119], v[144:147], v[200:203], v[116:119]
	v_mfma_f32_16x16x32_bf16 v[124:127], v[148:151], v[200:203], v[124:127]
	v_mfma_f32_16x16x32_bf16 v[52:55], v[152:155], v[200:203], v[52:55]
	v_mfma_f32_16x16x32_bf16 v[60:63], v[156:159], v[200:203], v[60:63]
	ds_read_b128 v[200:203], v246 offset:13312
	s_waitcnt lgkmcnt(3)
	v_mfma_f32_16x16x32_bf16 v[96:99], v[144:147], v[204:207], v[96:99]
	v_mfma_f32_16x16x32_bf16 v[104:107], v[148:151], v[204:207], v[104:107]
	v_mfma_f32_16x16x32_bf16 v[32:35], v[152:155], v[204:207], v[32:35]
	v_mfma_f32_16x16x32_bf16 v[40:43], v[156:159], v[204:207], v[40:43]
	ds_read_b128 v[204:207], v246 offset:14336
	s_waitcnt lgkmcnt(3)
	v_mfma_f32_16x16x32_bf16 v[100:103], v[144:147], v[242:245], v[100:103]
	v_mfma_f32_16x16x32_bf16 v[108:111], v[148:151], v[242:245], v[108:111]
	v_mfma_f32_16x16x32_bf16 v[36:39], v[152:155], v[242:245], v[36:39]
	v_mfma_f32_16x16x32_bf16 v[44:47], v[156:159], v[242:245], v[44:47]
	ds_read_b128 v[242:245], v246 offset:15360
	v_permlane16_swap_b32_e32 v112, v116
	v_permlane16_swap_b32_e32 v113, v117
	v_permlane16_swap_b32_e32 v114, v118
	v_permlane16_swap_b32_e32 v115, v119
	v_permlane16_swap_b32_e32 v120, v124
	v_permlane16_swap_b32_e32 v121, v125
	v_permlane16_swap_b32_e32 v122, v126
	v_permlane16_swap_b32_e32 v123, v127
	v_permlane16_swap_b32_e32 v48, v52
	v_permlane16_swap_b32_e32 v49, v53
	v_permlane16_swap_b32_e32 v50, v54
	v_permlane16_swap_b32_e32 v51, v55
	v_permlane16_swap_b32_e32 v56, v60
	v_permlane16_swap_b32_e32 v57, v61
	v_permlane16_swap_b32_e32 v58, v62
	v_permlane16_swap_b32_e32 v59, v63
	v_permlane32_swap_b32_e32 v112, v116
	v_permlane32_swap_b32_e32 v113, v117
	v_permlane32_swap_b32_e32 v114, v118
	v_permlane32_swap_b32_e32 v115, v119
	v_permlane32_swap_b32_e32 v120, v124
	v_permlane32_swap_b32_e32 v121, v125
	v_permlane32_swap_b32_e32 v122, v126
	v_permlane32_swap_b32_e32 v123, v127
	v_permlane32_swap_b32_e32 v48, v52
	v_permlane32_swap_b32_e32 v49, v53
	v_permlane32_swap_b32_e32 v50, v54
	v_permlane32_swap_b32_e32 v51, v55
	v_permlane32_swap_b32_e32 v56, v60
	v_permlane32_swap_b32_e32 v57, v61
	v_permlane32_swap_b32_e32 v58, v62
	v_permlane32_swap_b32_e32 v59, v63
	s_waitcnt lgkmcnt(3)
	v_mfma_f32_16x16x32_bf16 v[80:83], v[144:147], v[196:199], v[80:83]
	v_mfma_f32_16x16x32_bf16 v[88:91], v[148:151], v[196:199], v[88:91]
	v_mfma_f32_16x16x32_bf16 v[16:19], v[152:155], v[196:199], v[16:19]
	v_mfma_f32_16x16x32_bf16 v[24:27], v[156:159], v[196:199], v[24:27]
	s_waitcnt lgkmcnt(2)
	v_mfma_f32_16x16x32_bf16 v[84:87], v[144:147], v[200:203], v[84:87]
	v_mfma_f32_16x16x32_bf16 v[92:95], v[148:151], v[200:203], v[92:95]
	v_mfma_f32_16x16x32_bf16 v[20:23], v[152:155], v[200:203], v[20:23]
	v_mfma_f32_16x16x32_bf16 v[28:31], v[156:159], v[200:203], v[28:31]
	v_permlane16_swap_b32_e32 v96, v100
	v_permlane16_swap_b32_e32 v97, v101
	v_permlane16_swap_b32_e32 v98, v102
	v_permlane16_swap_b32_e32 v99, v103
	v_permlane16_swap_b32_e32 v104, v108
	v_permlane16_swap_b32_e32 v105, v109
	v_permlane16_swap_b32_e32 v106, v110
	v_permlane16_swap_b32_e32 v107, v111
	v_permlane16_swap_b32_e32 v32, v36
	v_permlane16_swap_b32_e32 v33, v37
	v_permlane16_swap_b32_e32 v34, v38
	v_permlane16_swap_b32_e32 v35, v39
	v_permlane16_swap_b32_e32 v40, v44
	v_permlane16_swap_b32_e32 v41, v45
	v_permlane16_swap_b32_e32 v42, v46
	v_permlane16_swap_b32_e32 v43, v47
	v_permlane32_swap_b32_e32 v96, v100
	v_permlane32_swap_b32_e32 v97, v101
	v_permlane32_swap_b32_e32 v98, v102
	v_permlane32_swap_b32_e32 v99, v103
	v_permlane32_swap_b32_e32 v104, v108
	v_permlane32_swap_b32_e32 v105, v109
	v_permlane32_swap_b32_e32 v106, v110
	v_permlane32_swap_b32_e32 v107, v111
	v_permlane32_swap_b32_e32 v32, v36
	v_permlane32_swap_b32_e32 v33, v37
	v_permlane32_swap_b32_e32 v34, v38
	v_permlane32_swap_b32_e32 v35, v39
	v_permlane32_swap_b32_e32 v40, v44
	v_permlane32_swap_b32_e32 v41, v45
	v_permlane32_swap_b32_e32 v42, v46
	v_permlane32_swap_b32_e32 v43, v47
	s_waitcnt lgkmcnt(1)
	v_mfma_f32_16x16x32_bf16 v[64:67], v[144:147], v[204:207], v[64:67]
	v_mfma_f32_16x16x32_bf16 v[72:75], v[148:151], v[204:207], v[72:75]
	v_mfma_f32_16x16x32_bf16 v[0:3], v[152:155], v[204:207], v[0:3]
	v_mfma_f32_16x16x32_bf16 v[8:11], v[156:159], v[204:207], v[8:11]
	s_waitcnt lgkmcnt(0)
	v_mfma_f32_16x16x32_bf16 v[68:71], v[144:147], v[242:245], v[68:71]
	v_mfma_f32_16x16x32_bf16 v[76:79], v[148:151], v[242:245], v[76:79]
	v_mfma_f32_16x16x32_bf16 v[4:7], v[152:155], v[242:245], v[4:7]
	v_mfma_f32_16x16x32_bf16 v[12:15], v[156:159], v[242:245], v[12:15]
	v_permlane16_swap_b32_e32 v80, v84
	v_permlane16_swap_b32_e32 v81, v85
	v_permlane16_swap_b32_e32 v82, v86
	v_permlane16_swap_b32_e32 v83, v87
	v_permlane16_swap_b32_e32 v88, v92
	v_permlane16_swap_b32_e32 v89, v93
	v_permlane16_swap_b32_e32 v90, v94
	v_permlane16_swap_b32_e32 v91, v95
	v_permlane16_swap_b32_e32 v16, v20
	v_permlane16_swap_b32_e32 v17, v21
	v_permlane16_swap_b32_e32 v18, v22
	v_permlane16_swap_b32_e32 v19, v23
	v_permlane16_swap_b32_e32 v24, v28
	v_permlane16_swap_b32_e32 v25, v29
	v_permlane16_swap_b32_e32 v26, v30
	v_permlane16_swap_b32_e32 v27, v31
	v_permlane32_swap_b32_e32 v80, v84
	v_permlane32_swap_b32_e32 v81, v85
	v_permlane32_swap_b32_e32 v82, v86
	v_permlane32_swap_b32_e32 v83, v87
	v_permlane32_swap_b32_e32 v88, v92
	v_permlane32_swap_b32_e32 v89, v93
	v_permlane32_swap_b32_e32 v90, v94
	v_permlane32_swap_b32_e32 v91, v95
	v_permlane32_swap_b32_e32 v16, v20
	v_permlane32_swap_b32_e32 v17, v21
	v_permlane32_swap_b32_e32 v18, v22
	v_permlane32_swap_b32_e32 v19, v23
	v_permlane32_swap_b32_e32 v24, v28
	v_permlane32_swap_b32_e32 v25, v29
	v_permlane32_swap_b32_e32 v26, v30
	v_permlane32_swap_b32_e32 v27, v31
	s_barrier
	s_nop 7
	v_permlane16_swap_b32_e32 v64, v68
	v_permlane16_swap_b32_e32 v65, v69
	v_permlane16_swap_b32_e32 v66, v70
	v_permlane16_swap_b32_e32 v67, v71
	v_permlane16_swap_b32_e32 v72, v76
	v_permlane16_swap_b32_e32 v73, v77
	v_permlane16_swap_b32_e32 v74, v78
	v_permlane16_swap_b32_e32 v75, v79
	v_permlane16_swap_b32_e32 v0, v4
	v_permlane16_swap_b32_e32 v1, v5
	v_permlane16_swap_b32_e32 v2, v6
	v_permlane16_swap_b32_e32 v3, v7
	v_permlane16_swap_b32_e32 v8, v12
	v_permlane16_swap_b32_e32 v9, v13
	v_permlane16_swap_b32_e32 v10, v14
	v_permlane16_swap_b32_e32 v11, v15
	v_permlane32_swap_b32_e32 v64, v68
	v_permlane32_swap_b32_e32 v65, v69
	v_permlane32_swap_b32_e32 v66, v70
	v_permlane32_swap_b32_e32 v67, v71
	v_permlane32_swap_b32_e32 v72, v76
	v_permlane32_swap_b32_e32 v73, v77
	v_permlane32_swap_b32_e32 v74, v78
	v_permlane32_swap_b32_e32 v75, v79
	v_permlane32_swap_b32_e32 v0, v4
	v_permlane32_swap_b32_e32 v1, v5
	v_permlane32_swap_b32_e32 v2, v6
	v_permlane32_swap_b32_e32 v3, v7
	v_permlane32_swap_b32_e32 v8, v12
	v_permlane32_swap_b32_e32 v9, v13
	v_permlane32_swap_b32_e32 v10, v14
	v_permlane32_swap_b32_e32 v11, v15
	s_waitcnt vmcnt(0)
	s_movk_i32 s3, 0x2400
	s_waitcnt vmcnt(6)
	v_lshlrev_b32_e32 v128, 2, v181
	s_waitcnt vmcnt(0)
	v_and_b32_e32 v133, 0xffffffc0, v181
	v_mul_lo_u32 v129, v237, s3
	v_lshlrev_b32_e32 v130, 2, v238
	v_and_b32_e32 v128, 60, v128
	v_lshl_add_u32 v176, s8, 8, v133
	v_mul_u32_u24_e32 v133, 0x110, v183
	v_or_b32_e32 v131, v129, v130
	v_lshl_or_b32 v132, v128, 2, v129
	v_lshl_or_b32 v128, s2, 7, v128
	v_lshlrev_b32_e32 v133, 2, v133
	v_lshrrev_b32_e32 v175, 4, v239
	s_movk_i32 s2, 0x110
	v_add_u32_e32 v147, v131, v133
	v_add3_u32 v148, v129, v133, v130
	v_mad_u32_u24 v146, v175, s2, v132
	v_readlane_b32 s2, v254, 39
	v_readlane_b32 s8, v253, 36
	v_add_u32_e32 v149, 0x800, v147
	v_add_u32_e32 v150, 0x800, v148
	v_add_u32_e32 v151, 0xa00, v148
	v_mov_b32_e32 v160, s2
	v_readlane_b32 s2, v254, 37
	v_readlane_b32 s9, v253, 37
	v_readlane_b32 s10, v253, 38
	v_readlane_b32 s11, v253, 39
	v_readlane_b32 s12, v253, 40
	v_readlane_b32 s13, v253, 41
	v_readlane_b32 s14, v253, 42
	v_readlane_b32 s15, v253, 43
	v_readlane_b32 s16, v253, 44
	v_readlane_b32 s17, v253, 45
	ds_write2_b32 v147, v112, v113 offset1:68
	ds_write2_b32 v148, v96, v97 offset0:32 offset1:100
	ds_write2_b32 v147, v114, v115 offset0:136 offset1:204
	ds_write2_b32 v148, v98, v99 offset0:168 offset1:236
	ds_write2_b32 v149, v116, v117 offset0:32 offset1:100
	ds_write2_b32 v150, v100, v101 offset0:64 offset1:132
	ds_write2_b32 v149, v118, v119 offset0:168 offset1:236
	ds_write2_b32 v151, v102, v103 offset0:72 offset1:140
	v_or_b32_e32 v102, v176, v175
	v_mov_b32_e32 v161, s2
	v_readlane_b32 s2, v254, 40
	v_readlane_b32 s18, v253, 46
	v_readlane_b32 s19, v253, 47
	v_readlane_b32 s20, v253, 48
	v_readlane_b32 s21, v253, 49
	v_readlane_b32 s22, v253, 50
	v_readlane_b32 s23, v253, 51
	s_mov_b64 s[8:9], s[16:17]
	v_cmp_gt_i32_e32 vcc, s39, v102
	v_add_u32_e32 v96, 0xffff8000, v102
	v_ashrrev_i32_e32 v97, 31, v102
	v_mov_b32_e32 v162, s2
	v_readlane_b32 s2, v254, 38
	s_mov_b64 s[10:11], s[18:19]
	v_cndmask_b32_e32 v97, 0, v97, vcc
	v_cndmask_b32_e32 v96, v96, v102, vcc
	v_mov_b32_e32 v163, s2
	v_mov_b32_e32 v164, s63
	v_mov_b32_e32 v165, s11
	v_mov_b32_e32 v166, s62
	v_mov_b32_e32 v167, s10
	v_min_i32_e32 v102, 0x8000, v102
	v_add_u32_e32 v152, 0x1000, v147
	v_add_u32_e32 v153, 0x1000, v148
	v_add_u32_e32 v154, 0x1200, v147
	v_add_u32_e32 v155, 0x1200, v148
	v_add_u32_e32 v156, 0x1800, v147
	v_add_u32_e32 v157, 0x1800, v148
	v_add_u32_e32 v158, 0x1a00, v147
	v_add_u32_e32 v159, 0x1c00, v148
	v_ashrrev_i32_e32 v129, 31, v128
	v_cndmask_b32_e32 v99, v160, v161, vcc
	v_cndmask_b32_e32 v98, v162, v163, vcc
	v_lshlrev_b64 v[96:97], 12, v[96:97]
	v_cndmask_b32_e32 v101, v164, v165, vcc
	v_cndmask_b32_e32 v100, v166, v167, vcc
	v_ashrrev_i32_e32 v102, 12, v102
	ds_write2_b32 v152, v120, v121 offset0:64 offset1:132
	ds_write2_b32 v153, v104, v105 offset0:96 offset1:164
	ds_write2_b32 v154, v122, v123 offset0:72 offset1:140
	ds_write2_b32 v155, v106, v107 offset0:104 offset1:172
	ds_write2_b32 v156, v124, v125 offset0:96 offset1:164
	ds_write2_b32 v157, v108, v109 offset0:128 offset1:196
	ds_write2_b32 v158, v126, v127 offset0:104 offset1:172
	ds_write2_b32 v159, v110, v111 offset0:8 offset1:76
	v_lshl_add_u64 v[98:99], v[98:99], 0, v[96:97]
	v_lshl_add_u64 v[100:101], v[100:101], 0, v[96:97]
	v_lshlrev_b64 v[96:97], 2, v[128:129]
	v_mul_hi_i32_i24_e32 v103, 0x6000, v102
	v_mul_i32_i24_e32 v102, 0x6000, v102
	s_waitcnt lgkmcnt(0)
	v_lshl_add_u64 v[98:99], v[98:99], 0, v[96:97]
	v_lshl_add_u64 v[102:103], s[0:1], 0, v[102:103]
	v_lshl_add_u64 v[102:103], v[102:103], 0, v[96:97]
	ds_read_b128 v[104:107], v146
	global_load_dwordx4 v[108:111], v[98:99], off
	global_load_dwordx4 v[112:115], v[102:103], off
	v_or_b32_e32 v168, 4, v175
	v_lshl_add_u64 v[100:101], v[100:101], 0, v[96:97]
	v_or_b32_e32 v169, 8, v175
	v_or_b32_e32 v170, 12, v175
	v_or_b32_e32 v171, 16, v175
	v_or_b32_e32 v172, 20, v175
	v_or_b32_e32 v173, 24, v175
	v_or_b32_e32 v174, 28, v175
	v_or_b32_e32 v181, v176, v174
	v_readlane_b32 s2, v254, 11
	s_add_i32 s4, s4, s2
	s_cmp_lt_i32 s4, s26
	s_mov_b64 s[12:13], s[20:21]
	s_mov_b64 s[14:15], s[22:23]
	s_waitcnt vmcnt(0) lgkmcnt(0)
	v_pk_fma_f32 v[104:105], v[104:105], v[112:113], v[108:109]
	v_pk_fma_f32 v[106:107], v[106:107], v[114:115], v[110:111]
	v_or_b32_e32 v110, v176, v168
	global_store_dwordx4 v[100:101], v[104:107], off
	v_cmp_gt_i32_e32 vcc, s39, v110
	s_nop 0
	v_ashrrev_i32_e32 v104, 31, v110
	v_add_u32_e32 v106, 0xffff8000, v110
	v_cndmask_b32_e32 v105, 0, v104, vcc
	v_cndmask_b32_e32 v104, v106, v110, vcc
	v_cndmask_b32_e32 v107, v160, v161, vcc
	v_cndmask_b32_e32 v106, v162, v163, vcc
	v_lshlrev_b64 v[104:105], 12, v[104:105]
	v_cndmask_b32_e32 v109, v164, v165, vcc
	v_cndmask_b32_e32 v108, v166, v167, vcc
	v_lshl_add_u64 v[106:107], v[106:107], 0, v[104:105]
	v_lshl_add_u64 v[104:105], v[108:109], 0, v[104:105]
	v_min_i32_e32 v108, 0x8000, v110
	v_ashrrev_i32_e32 v108, 12, v108
	v_mul_hi_i32_i24_e32 v109, 0x6000, v108
	v_mul_i32_i24_e32 v108, 0x6000, v108
	v_lshl_add_u64 v[106:107], v[106:107], 0, v[96:97]
	v_lshl_add_u64 v[108:109], s[0:1], 0, v[108:109]
	v_lshl_add_u64 v[108:109], v[108:109], 0, v[96:97]
	ds_read_b128 v[110:113], v146 offset:1088
	global_load_dwordx4 v[114:117], v[106:107], off
	global_load_dwordx4 v[118:121], v[108:109], off
	v_lshl_add_u64 v[104:105], v[104:105], 0, v[96:97]
	s_waitcnt vmcnt(0) lgkmcnt(0)
	v_pk_fma_f32 v[110:111], v[110:111], v[118:119], v[114:115]
	v_pk_fma_f32 v[112:113], v[112:113], v[120:121], v[116:117]
	v_or_b32_e32 v118, v176, v169
	global_store_dwordx4 v[104:105], v[110:113], off
	v_cmp_gt_i32_e32 vcc, s39, v118
	s_nop 0
	v_ashrrev_i32_e32 v110, 31, v118
	v_add_u32_e32 v112, 0xffff8000, v118
	v_cndmask_b32_e32 v111, 0, v110, vcc
	v_cndmask_b32_e32 v110, v112, v118, vcc
	v_cndmask_b32_e32 v113, v160, v161, vcc
	v_cndmask_b32_e32 v112, v162, v163, vcc
	v_lshlrev_b64 v[110:111], 12, v[110:111]
	v_lshl_add_u64 v[112:113], v[112:113], 0, v[110:111]
	v_cndmask_b32_e32 v115, v164, v165, vcc
	v_cndmask_b32_e32 v114, v166, v167, vcc
	v_lshl_add_u64 v[116:117], v[114:115], 0, v[110:111]
	v_lshl_add_u64 v[110:111], v[112:113], 0, v[96:97]
	v_min_i32_e32 v112, 0x8000, v118
	v_ashrrev_i32_e32 v112, 12, v112
	v_mul_hi_i32_i24_e32 v113, 0x6000, v112
	v_mul_i32_i24_e32 v112, 0x6000, v112
	v_lshl_add_u64 v[112:113], s[0:1], 0, v[112:113]
	v_lshl_add_u64 v[114:115], v[112:113], 0, v[96:97]
	v_lshl_add_u64 v[112:113], v[116:117], 0, v[96:97]
	ds_read_b128 v[116:119], v146 offset:2176
	global_load_dwordx4 v[120:123], v[110:111], off
	global_load_dwordx4 v[124:127], v[114:115], off
	s_waitcnt vmcnt(0) lgkmcnt(0)
	v_pk_fma_f32 v[116:117], v[116:117], v[124:125], v[120:121]
	v_pk_fma_f32 v[118:119], v[118:119], v[126:127], v[122:123]
	v_or_b32_e32 v124, v176, v170
	global_store_dwordx4 v[112:113], v[116:119], off
	v_cmp_gt_i32_e32 vcc, s39, v124
	s_nop 0
	v_ashrrev_i32_e32 v116, 31, v124
	v_add_u32_e32 v118, 0xffff8000, v124
	v_cndmask_b32_e32 v117, 0, v116, vcc
	v_cndmask_b32_e32 v116, v118, v124, vcc
	v_cndmask_b32_e32 v119, v160, v161, vcc
	v_cndmask_b32_e32 v118, v162, v163, vcc
	v_lshlrev_b64 v[116:117], 12, v[116:117]
	v_lshl_add_u64 v[118:119], v[118:119], 0, v[116:117]
	v_cndmask_b32_e32 v121, v164, v165, vcc
	v_cndmask_b32_e32 v120, v166, v167, vcc
	v_lshl_add_u64 v[122:123], v[120:121], 0, v[116:117]
	v_lshl_add_u64 v[116:117], v[118:119], 0, v[96:97]
	v_min_i32_e32 v118, 0x8000, v124
	v_ashrrev_i32_e32 v118, 12, v118
	v_mul_hi_i32_i24_e32 v119, 0x6000, v118
	v_mul_i32_i24_e32 v118, 0x6000, v118
	v_lshl_add_u64 v[118:119], s[0:1], 0, v[118:119]
	v_lshl_add_u64 v[120:121], v[118:119], 0, v[96:97]
	v_lshl_add_u64 v[118:119], v[122:123], 0, v[96:97]
	ds_read_b128 v[122:125], v146 offset:3264
	global_load_dwordx4 v[126:129], v[116:117], off
	global_load_dwordx4 v[130:133], v[120:121], off
	s_waitcnt vmcnt(0) lgkmcnt(0)
	v_pk_fma_f32 v[122:123], v[122:123], v[130:131], v[126:127]
	v_pk_fma_f32 v[124:125], v[124:125], v[132:133], v[128:129]
	v_or_b32_e32 v130, v176, v171
	global_store_dwordx4 v[118:119], v[122:125], off
	v_cmp_gt_i32_e32 vcc, s39, v130
	s_nop 0
	v_ashrrev_i32_e32 v122, 31, v130
	v_add_u32_e32 v124, 0xffff8000, v130
	v_cndmask_b32_e32 v123, 0, v122, vcc
	v_cndmask_b32_e32 v122, v124, v130, vcc
	v_cndmask_b32_e32 v125, v160, v161, vcc
	v_cndmask_b32_e32 v124, v162, v163, vcc
	v_lshlrev_b64 v[122:123], 12, v[122:123]
	v_lshl_add_u64 v[124:125], v[124:125], 0, v[122:123]
	v_cndmask_b32_e32 v127, v164, v165, vcc
	v_cndmask_b32_e32 v126, v166, v167, vcc
	v_lshl_add_u64 v[128:129], v[126:127], 0, v[122:123]
	v_lshl_add_u64 v[122:123], v[124:125], 0, v[96:97]
	v_min_i32_e32 v124, 0x8000, v130
	v_ashrrev_i32_e32 v124, 12, v124
	v_mul_hi_i32_i24_e32 v125, 0x6000, v124
	v_mul_i32_i24_e32 v124, 0x6000, v124
	v_lshl_add_u64 v[124:125], s[0:1], 0, v[124:125]
	v_lshl_add_u64 v[126:127], v[124:125], 0, v[96:97]
	v_lshl_add_u64 v[124:125], v[128:129], 0, v[96:97]
	ds_read_b128 v[128:131], v146 offset:4352
	global_load_dwordx4 v[132:135], v[122:123], off
	global_load_dwordx4 v[136:139], v[126:127], off
	s_waitcnt vmcnt(0) lgkmcnt(0)
	v_pk_fma_f32 v[128:129], v[128:129], v[136:137], v[132:133]
	v_pk_fma_f32 v[130:131], v[130:131], v[138:139], v[134:135]
	v_or_b32_e32 v136, v176, v172
	global_store_dwordx4 v[124:125], v[128:131], off
	v_cmp_gt_i32_e32 vcc, s39, v136
	s_nop 0
	v_ashrrev_i32_e32 v128, 31, v136
	v_add_u32_e32 v130, 0xffff8000, v136
	v_cndmask_b32_e32 v129, 0, v128, vcc
	v_cndmask_b32_e32 v128, v130, v136, vcc
	v_cndmask_b32_e32 v131, v160, v161, vcc
	v_cndmask_b32_e32 v130, v162, v163, vcc
	v_lshlrev_b64 v[128:129], 12, v[128:129]
	v_lshl_add_u64 v[130:131], v[130:131], 0, v[128:129]
	v_cndmask_b32_e32 v133, v164, v165, vcc
	v_cndmask_b32_e32 v132, v166, v167, vcc
	v_lshl_add_u64 v[134:135], v[132:133], 0, v[128:129]
	v_lshl_add_u64 v[128:129], v[130:131], 0, v[96:97]
	v_min_i32_e32 v130, 0x8000, v136
	v_ashrrev_i32_e32 v130, 12, v130
	v_mul_hi_i32_i24_e32 v131, 0x6000, v130
	v_mul_i32_i24_e32 v130, 0x6000, v130
	v_lshl_add_u64 v[130:131], s[0:1], 0, v[130:131]
	v_lshl_add_u64 v[132:133], v[130:131], 0, v[96:97]
	v_lshl_add_u64 v[130:131], v[134:135], 0, v[96:97]
	ds_read_b128 v[134:137], v146 offset:5440
	global_load_dwordx4 v[138:141], v[128:129], off
	global_load_dwordx4 v[142:145], v[132:133], off
	s_waitcnt vmcnt(0) lgkmcnt(0)
	v_pk_fma_f32 v[134:135], v[134:135], v[142:143], v[138:139]
	v_pk_fma_f32 v[136:137], v[136:137], v[144:145], v[140:141]
	v_or_b32_e32 v142, v176, v173
	global_store_dwordx4 v[130:131], v[134:137], off
	v_cmp_gt_i32_e32 vcc, s39, v142
	s_nop 0
	v_ashrrev_i32_e32 v134, 31, v142
	v_add_u32_e32 v136, 0xffff8000, v142
	v_cndmask_b32_e32 v135, 0, v134, vcc
	v_cndmask_b32_e32 v134, v136, v142, vcc
	v_cndmask_b32_e32 v137, v160, v161, vcc
	v_cndmask_b32_e32 v136, v162, v163, vcc
	v_lshlrev_b64 v[134:135], 12, v[134:135]
	v_lshl_add_u64 v[136:137], v[136:137], 0, v[134:135]
	v_cndmask_b32_e32 v139, v164, v165, vcc
	v_cndmask_b32_e32 v138, v166, v167, vcc
	v_lshl_add_u64 v[140:141], v[138:139], 0, v[134:135]
	v_lshl_add_u64 v[134:135], v[136:137], 0, v[96:97]
	v_min_i32_e32 v136, 0x8000, v142
	v_ashrrev_i32_e32 v136, 12, v136
	v_mul_hi_i32_i24_e32 v137, 0x6000, v136
	v_mul_i32_i24_e32 v136, 0x6000, v136
	v_lshl_add_u64 v[136:137], s[0:1], 0, v[136:137]
	v_lshl_add_u64 v[138:139], v[136:137], 0, v[96:97]
	v_lshl_add_u64 v[136:137], v[140:141], 0, v[96:97]
	ds_read_b128 v[140:143], v146 offset:6528
	global_load_dwordx4 v[184:187], v[134:135], off
	global_load_dwordx4 v[196:199], v[138:139], off
	v_cmp_gt_i32_e32 vcc, s39, v181
	s_waitcnt vmcnt(0) lgkmcnt(0)
	v_pk_fma_f32 v[140:141], v[140:141], v[196:197], v[184:185]
	v_pk_fma_f32 v[142:143], v[142:143], v[198:199], v[186:187]
	global_store_dwordx4 v[136:137], v[140:143], off
	v_cndmask_b32_e32 v145, v164, v165, vcc
	v_cndmask_b32_e32 v144, v166, v167, vcc
	v_ashrrev_i32_e32 v140, 31, v181
	v_add_u32_e32 v142, 0xffff8000, v181
	v_cndmask_b32_e32 v141, 0, v140, vcc
	v_cndmask_b32_e32 v140, v142, v181, vcc
	v_cndmask_b32_e32 v143, v160, v161, vcc
	v_cndmask_b32_e32 v142, v162, v163, vcc
	v_lshlrev_b64 v[140:141], 12, v[140:141]
	v_lshl_add_u64 v[142:143], v[142:143], 0, v[140:141]
	v_lshl_add_u64 v[184:185], v[144:145], 0, v[140:141]
	v_lshl_add_u64 v[140:141], v[142:143], 0, v[96:97]
	v_min_i32_e32 v142, 0x8000, v181
	v_ashrrev_i32_e32 v142, 12, v142
	v_mul_hi_i32_i24_e32 v143, 0x6000, v142
	v_mul_i32_i24_e32 v142, 0x6000, v142
	v_lshl_add_u64 v[142:143], s[0:1], 0, v[142:143]
	v_lshl_add_u64 v[144:145], v[142:143], 0, v[96:97]
	v_lshl_add_u64 v[142:143], v[184:185], 0, v[96:97]
	ds_read_b128 v[184:187], v146 offset:7616
	global_load_dwordx4 v[196:199], v[140:141], off
	global_load_dwordx4 v[200:203], v[144:145], off
	s_waitcnt vmcnt(0) lgkmcnt(0)
	v_pk_fma_f32 v[184:185], v[184:185], v[200:201], v[196:197]
	v_pk_fma_f32 v[186:187], v[186:187], v[202:203], v[198:199]
	global_store_dwordx4 v[142:143], v[184:187], off
	s_waitcnt lgkmcnt(0)
	ds_write2_b32 v147, v80, v81 offset1:68
	ds_write2_b32 v148, v64, v65 offset0:32 offset1:100
	ds_write2_b32 v147, v82, v83 offset0:136 offset1:204
	ds_write2_b32 v148, v66, v67 offset0:168 offset1:236
	ds_write2_b32 v149, v84, v85 offset0:32 offset1:100
	ds_write2_b32 v150, v68, v69 offset0:64 offset1:132
	ds_write2_b32 v149, v86, v87 offset0:168 offset1:236
	ds_write2_b32 v151, v70, v71 offset0:72 offset1:140
	ds_write2_b32 v152, v88, v89 offset0:64 offset1:132
	ds_write2_b32 v153, v72, v73 offset0:96 offset1:164
	ds_write2_b32 v154, v90, v91 offset0:72 offset1:140
	ds_write2_b32 v155, v74, v75 offset0:104 offset1:172
	ds_write2_b32 v156, v92, v93 offset0:96 offset1:164
	ds_write2_b32 v157, v76, v77 offset0:128 offset1:196
	ds_write2_b32 v158, v94, v95 offset0:104 offset1:172
	ds_write2_b32 v159, v78, v79 offset0:8 offset1:76
	s_waitcnt lgkmcnt(0)
	ds_read_b128 v[64:67], v146
	global_load_dwordx4 v[68:71], v[98:99], off offset:256
	global_load_dwordx4 v[72:75], v[102:103], off offset:256
	s_waitcnt vmcnt(0) lgkmcnt(0)
	v_pk_fma_f32 v[64:65], v[64:65], v[72:73], v[68:69]
	v_pk_fma_f32 v[66:67], v[66:67], v[74:75], v[70:71]
	global_store_dwordx4 v[100:101], v[64:67], off offset:256
	ds_read_b128 v[64:67], v146 offset:1088
	global_load_dwordx4 v[68:71], v[106:107], off offset:256
	global_load_dwordx4 v[72:75], v[108:109], off offset:256
	s_waitcnt vmcnt(0) lgkmcnt(0)
	v_pk_fma_f32 v[64:65], v[64:65], v[72:73], v[68:69]
	v_pk_fma_f32 v[66:67], v[66:67], v[74:75], v[70:71]
	global_store_dwordx4 v[104:105], v[64:67], off offset:256
	ds_read_b128 v[64:67], v146 offset:2176
	global_load_dwordx4 v[68:71], v[110:111], off offset:256
	global_load_dwordx4 v[72:75], v[114:115], off offset:256
	s_waitcnt vmcnt(0) lgkmcnt(0)
	v_pk_fma_f32 v[64:65], v[64:65], v[72:73], v[68:69]
	v_pk_fma_f32 v[66:67], v[66:67], v[74:75], v[70:71]
	global_store_dwordx4 v[112:113], v[64:67], off offset:256
	ds_read_b128 v[64:67], v146 offset:3264
	global_load_dwordx4 v[68:71], v[116:117], off offset:256
	global_load_dwordx4 v[72:75], v[120:121], off offset:256
	s_waitcnt vmcnt(0) lgkmcnt(0)
	v_pk_fma_f32 v[64:65], v[64:65], v[72:73], v[68:69]
	v_pk_fma_f32 v[66:67], v[66:67], v[74:75], v[70:71]
	global_store_dwordx4 v[118:119], v[64:67], off offset:256
	ds_read_b128 v[64:67], v146 offset:4352
	global_load_dwordx4 v[68:71], v[122:123], off offset:256
	global_load_dwordx4 v[72:75], v[126:127], off offset:256
	s_waitcnt vmcnt(0) lgkmcnt(0)
	v_pk_fma_f32 v[64:65], v[64:65], v[72:73], v[68:69]
	v_pk_fma_f32 v[66:67], v[66:67], v[74:75], v[70:71]
	global_store_dwordx4 v[124:125], v[64:67], off offset:256
	ds_read_b128 v[64:67], v146 offset:5440
	global_load_dwordx4 v[68:71], v[128:129], off offset:256
	global_load_dwordx4 v[72:75], v[132:133], off offset:256
	s_waitcnt vmcnt(0) lgkmcnt(0)
	v_pk_fma_f32 v[64:65], v[64:65], v[72:73], v[68:69]
	v_pk_fma_f32 v[66:67], v[66:67], v[74:75], v[70:71]
	global_store_dwordx4 v[130:131], v[64:67], off offset:256
	ds_read_b128 v[64:67], v146 offset:6528
	global_load_dwordx4 v[68:71], v[134:135], off offset:256
	global_load_dwordx4 v[72:75], v[138:139], off offset:256
	s_waitcnt vmcnt(0) lgkmcnt(0)
	v_pk_fma_f32 v[64:65], v[64:65], v[72:73], v[68:69]
	v_pk_fma_f32 v[66:67], v[66:67], v[74:75], v[70:71]
	global_store_dwordx4 v[136:137], v[64:67], off offset:256
	ds_read_b128 v[64:67], v146 offset:7616
	global_load_dwordx4 v[68:71], v[140:141], off offset:256
	global_load_dwordx4 v[72:75], v[144:145], off offset:256
	s_waitcnt vmcnt(0) lgkmcnt(0)
	v_pk_fma_f32 v[64:65], v[64:65], v[72:73], v[68:69]
	v_pk_fma_f32 v[66:67], v[66:67], v[74:75], v[70:71]
	global_store_dwordx4 v[142:143], v[64:67], off offset:256
	v_or_b32_e32 v74, 32, v176
	s_waitcnt lgkmcnt(0)
	ds_write2_b32 v147, v48, v49 offset1:68
	ds_write2_b32 v148, v32, v33 offset0:32 offset1:100
	ds_write2_b32 v147, v50, v51 offset0:136 offset1:204
	ds_write2_b32 v148, v34, v35 offset0:168 offset1:236
	ds_write2_b32 v149, v52, v53 offset0:32 offset1:100
	ds_write2_b32 v150, v36, v37 offset0:64 offset1:132
	ds_write2_b32 v149, v54, v55 offset0:168 offset1:236
	ds_write2_b32 v151, v38, v39 offset0:72 offset1:140
	ds_write2_b32 v152, v56, v57 offset0:64 offset1:132
	ds_write2_b32 v153, v40, v41 offset0:96 offset1:164
	ds_write2_b32 v154, v58, v59 offset0:72 offset1:140
	ds_write2_b32 v155, v42, v43 offset0:104 offset1:172
	ds_write2_b32 v156, v60, v61 offset0:96 offset1:164
	ds_write2_b32 v157, v44, v45 offset0:128 offset1:196
	ds_write2_b32 v158, v62, v63 offset0:104 offset1:172
	ds_write2_b32 v159, v46, v47 offset0:8 offset1:76
	v_or_b32_e32 v40, v74, v175
	v_cmp_gt_i32_e32 vcc, s39, v40
	v_ashrrev_i32_e32 v32, 31, v40
	v_add_u32_e32 v34, 0xffff8000, v40
	v_cndmask_b32_e32 v33, 0, v32, vcc
	v_cndmask_b32_e32 v32, v34, v40, vcc
	v_cndmask_b32_e32 v35, v160, v161, vcc
	v_cndmask_b32_e32 v34, v162, v163, vcc
	v_lshlrev_b64 v[32:33], 12, v[32:33]
	v_lshl_add_u64 v[34:35], v[34:35], 0, v[32:33]
	v_cndmask_b32_e32 v37, v164, v165, vcc
	v_cndmask_b32_e32 v36, v166, v167, vcc
	v_lshl_add_u64 v[38:39], v[36:37], 0, v[32:33]
	v_lshl_add_u64 v[32:33], v[34:35], 0, v[96:97]
	v_min_i32_e32 v34, 0x8000, v40
	v_ashrrev_i32_e32 v34, 12, v34
	v_mul_hi_i32_i24_e32 v35, 0x6000, v34
	v_mul_i32_i24_e32 v34, 0x6000, v34
	s_waitcnt lgkmcnt(0)
	v_lshl_add_u64 v[34:35], s[0:1], 0, v[34:35]
	v_lshl_add_u64 v[36:37], v[34:35], 0, v[96:97]
	v_lshl_add_u64 v[34:35], v[38:39], 0, v[96:97]
	ds_read_b128 v[38:41], v146
	global_load_dwordx4 v[42:45], v[32:33], off
	global_load_dwordx4 v[46:49], v[36:37], off
	v_or_b32_e32 v75, v74, v173
	s_waitcnt vmcnt(0) lgkmcnt(0)
	v_pk_fma_f32 v[38:39], v[38:39], v[46:47], v[42:43]
	v_pk_fma_f32 v[40:41], v[40:41], v[48:49], v[44:45]
	v_or_b32_e32 v46, v74, v168
	global_store_dwordx4 v[34:35], v[38:41], off
	v_cmp_gt_i32_e32 vcc, s39, v46
	s_nop 0
	v_ashrrev_i32_e32 v38, 31, v46
	v_add_u32_e32 v40, 0xffff8000, v46
	v_cndmask_b32_e32 v39, 0, v38, vcc
	v_cndmask_b32_e32 v38, v40, v46, vcc
	v_cndmask_b32_e32 v41, v160, v161, vcc
	v_cndmask_b32_e32 v40, v162, v163, vcc
	v_lshlrev_b64 v[38:39], 12, v[38:39]
	v_lshl_add_u64 v[40:41], v[40:41], 0, v[38:39]
	v_cndmask_b32_e32 v43, v164, v165, vcc
	v_cndmask_b32_e32 v42, v166, v167, vcc
	v_lshl_add_u64 v[44:45], v[42:43], 0, v[38:39]
	v_lshl_add_u64 v[38:39], v[40:41], 0, v[96:97]
	v_min_i32_e32 v40, 0x8000, v46
	v_ashrrev_i32_e32 v40, 12, v40
	v_mul_hi_i32_i24_e32 v41, 0x6000, v40
	v_mul_i32_i24_e32 v40, 0x6000, v40
	v_lshl_add_u64 v[40:41], s[0:1], 0, v[40:41]
	v_lshl_add_u64 v[42:43], v[40:41], 0, v[96:97]
	v_lshl_add_u64 v[40:41], v[44:45], 0, v[96:97]
	ds_read_b128 v[44:47], v146 offset:1088
	global_load_dwordx4 v[48:51], v[38:39], off
	global_load_dwordx4 v[52:55], v[42:43], off
	s_waitcnt vmcnt(0) lgkmcnt(0)
	v_pk_fma_f32 v[44:45], v[44:45], v[52:53], v[48:49]
	v_pk_fma_f32 v[46:47], v[46:47], v[54:55], v[50:51]
	v_or_b32_e32 v52, v74, v169
	global_store_dwordx4 v[40:41], v[44:47], off
	v_cmp_gt_i32_e32 vcc, s39, v52
	s_nop 0
	v_ashrrev_i32_e32 v44, 31, v52
	v_add_u32_e32 v46, 0xffff8000, v52
	v_cndmask_b32_e32 v45, 0, v44, vcc
	v_cndmask_b32_e32 v44, v46, v52, vcc
	v_cndmask_b32_e32 v47, v160, v161, vcc
	v_cndmask_b32_e32 v46, v162, v163, vcc
	v_lshlrev_b64 v[44:45], 12, v[44:45]
	v_lshl_add_u64 v[46:47], v[46:47], 0, v[44:45]
	v_cndmask_b32_e32 v49, v164, v165, vcc
	v_cndmask_b32_e32 v48, v166, v167, vcc
	v_lshl_add_u64 v[50:51], v[48:49], 0, v[44:45]
	v_lshl_add_u64 v[44:45], v[46:47], 0, v[96:97]
	v_min_i32_e32 v46, 0x8000, v52
	v_ashrrev_i32_e32 v46, 12, v46
	v_mul_hi_i32_i24_e32 v47, 0x6000, v46
	v_mul_i32_i24_e32 v46, 0x6000, v46
	v_lshl_add_u64 v[46:47], s[0:1], 0, v[46:47]
	v_lshl_add_u64 v[48:49], v[46:47], 0, v[96:97]
	v_lshl_add_u64 v[46:47], v[50:51], 0, v[96:97]
	ds_read_b128 v[50:53], v146 offset:2176
	global_load_dwordx4 v[54:57], v[44:45], off
	global_load_dwordx4 v[58:61], v[48:49], off
	s_waitcnt vmcnt(0) lgkmcnt(0)
	v_pk_fma_f32 v[50:51], v[50:51], v[58:59], v[54:55]
	v_pk_fma_f32 v[52:53], v[52:53], v[60:61], v[56:57]
	v_or_b32_e32 v58, v74, v170
	global_store_dwordx4 v[46:47], v[50:53], off
	v_cmp_gt_i32_e32 vcc, s39, v58
	s_nop 0
	v_ashrrev_i32_e32 v50, 31, v58
	v_add_u32_e32 v52, 0xffff8000, v58
	v_cndmask_b32_e32 v51, 0, v50, vcc
	v_cndmask_b32_e32 v50, v52, v58, vcc
	v_cndmask_b32_e32 v53, v160, v161, vcc
	v_cndmask_b32_e32 v52, v162, v163, vcc
	v_lshlrev_b64 v[50:51], 12, v[50:51]
	v_lshl_add_u64 v[52:53], v[52:53], 0, v[50:51]
	v_cndmask_b32_e32 v55, v164, v165, vcc
	v_cndmask_b32_e32 v54, v166, v167, vcc
	v_lshl_add_u64 v[56:57], v[54:55], 0, v[50:51]
	v_lshl_add_u64 v[50:51], v[52:53], 0, v[96:97]
	v_min_i32_e32 v52, 0x8000, v58
	v_ashrrev_i32_e32 v52, 12, v52
	v_mul_hi_i32_i24_e32 v53, 0x6000, v52
	v_mul_i32_i24_e32 v52, 0x6000, v52
	v_lshl_add_u64 v[52:53], s[0:1], 0, v[52:53]
	v_lshl_add_u64 v[54:55], v[52:53], 0, v[96:97]
	v_lshl_add_u64 v[52:53], v[56:57], 0, v[96:97]
	ds_read_b128 v[56:59], v146 offset:3264
	global_load_dwordx4 v[60:63], v[50:51], off
	global_load_dwordx4 v[64:67], v[54:55], off
	s_waitcnt vmcnt(0) lgkmcnt(0)
	v_pk_fma_f32 v[56:57], v[56:57], v[64:65], v[60:61]
	v_pk_fma_f32 v[58:59], v[58:59], v[66:67], v[62:63]
	v_or_b32_e32 v64, v74, v171
	global_store_dwordx4 v[52:53], v[56:59], off
	v_cmp_gt_i32_e32 vcc, s39, v64
	s_nop 0
	v_ashrrev_i32_e32 v56, 31, v64
	v_add_u32_e32 v58, 0xffff8000, v64
	v_cndmask_b32_e32 v57, 0, v56, vcc
	v_cndmask_b32_e32 v56, v58, v64, vcc
	v_cndmask_b32_e32 v59, v160, v161, vcc
	v_cndmask_b32_e32 v58, v162, v163, vcc
	v_lshlrev_b64 v[56:57], 12, v[56:57]
	v_lshl_add_u64 v[58:59], v[58:59], 0, v[56:57]
	v_cndmask_b32_e32 v61, v164, v165, vcc
	v_cndmask_b32_e32 v60, v166, v167, vcc
	v_lshl_add_u64 v[62:63], v[60:61], 0, v[56:57]
	v_lshl_add_u64 v[56:57], v[58:59], 0, v[96:97]
	v_min_i32_e32 v58, 0x8000, v64
	v_ashrrev_i32_e32 v58, 12, v58
	v_mul_hi_i32_i24_e32 v59, 0x6000, v58
	v_mul_i32_i24_e32 v58, 0x6000, v58
	v_lshl_add_u64 v[58:59], s[0:1], 0, v[58:59]
	v_lshl_add_u64 v[60:61], v[58:59], 0, v[96:97]
	v_lshl_add_u64 v[58:59], v[62:63], 0, v[96:97]
	ds_read_b128 v[62:65], v146 offset:4352
	global_load_dwordx4 v[66:69], v[56:57], off
	global_load_dwordx4 v[70:73], v[60:61], off
	s_waitcnt vmcnt(0) lgkmcnt(0)
	v_pk_fma_f32 v[62:63], v[62:63], v[70:71], v[66:67]
	v_pk_fma_f32 v[64:65], v[64:65], v[72:73], v[68:69]
	v_or_b32_e32 v70, v74, v172
	global_store_dwordx4 v[58:59], v[62:65], off
	v_cmp_gt_i32_e32 vcc, s39, v70
	s_nop 0
	v_ashrrev_i32_e32 v62, 31, v70
	v_add_u32_e32 v64, 0xffff8000, v70
	v_cndmask_b32_e32 v63, 0, v62, vcc
	v_cndmask_b32_e32 v62, v64, v70, vcc
	v_cndmask_b32_e32 v65, v160, v161, vcc
	v_cndmask_b32_e32 v64, v162, v163, vcc
	v_lshlrev_b64 v[62:63], 12, v[62:63]
	v_lshl_add_u64 v[64:65], v[64:65], 0, v[62:63]
	v_cndmask_b32_e32 v67, v164, v165, vcc
	v_cndmask_b32_e32 v66, v166, v167, vcc
	v_lshl_add_u64 v[68:69], v[66:67], 0, v[62:63]
	v_lshl_add_u64 v[62:63], v[64:65], 0, v[96:97]
	v_min_i32_e32 v64, 0x8000, v70
	v_ashrrev_i32_e32 v64, 12, v64
	v_mul_hi_i32_i24_e32 v65, 0x6000, v64
	v_mul_i32_i24_e32 v64, 0x6000, v64
	v_lshl_add_u64 v[64:65], s[0:1], 0, v[64:65]
	v_lshl_add_u64 v[66:67], v[64:65], 0, v[96:97]
	v_lshl_add_u64 v[64:65], v[68:69], 0, v[96:97]
	ds_read_b128 v[68:71], v146 offset:5440
	global_load_dwordx4 v[76:79], v[62:63], off
	global_load_dwordx4 v[80:83], v[66:67], off
	v_cmp_gt_i32_e32 vcc, s39, v75
	s_waitcnt vmcnt(0) lgkmcnt(0)
	v_pk_fma_f32 v[68:69], v[68:69], v[80:81], v[76:77]
	v_pk_fma_f32 v[70:71], v[70:71], v[82:83], v[78:79]
	global_store_dwordx4 v[64:65], v[68:71], off
	v_cndmask_b32_e32 v73, v164, v165, vcc
	v_cndmask_b32_e32 v72, v166, v167, vcc
	v_ashrrev_i32_e32 v68, 31, v75
	v_add_u32_e32 v70, 0xffff8000, v75
	v_cndmask_b32_e32 v69, 0, v68, vcc
	v_cndmask_b32_e32 v68, v70, v75, vcc
	v_cndmask_b32_e32 v71, v160, v161, vcc
	v_cndmask_b32_e32 v70, v162, v163, vcc
	v_lshlrev_b64 v[68:69], 12, v[68:69]
	v_lshl_add_u64 v[70:71], v[70:71], 0, v[68:69]
	v_lshl_add_u64 v[76:77], v[72:73], 0, v[68:69]
	v_lshl_add_u64 v[68:69], v[70:71], 0, v[96:97]
	v_min_i32_e32 v70, 0x8000, v75
	v_ashrrev_i32_e32 v70, 12, v70
	v_mul_hi_i32_i24_e32 v71, 0x6000, v70
	v_mul_i32_i24_e32 v70, 0x6000, v70
	v_lshl_add_u64 v[70:71], s[0:1], 0, v[70:71]
	v_lshl_add_u64 v[72:73], v[70:71], 0, v[96:97]
	v_lshl_add_u64 v[70:71], v[76:77], 0, v[96:97]
	ds_read_b128 v[76:79], v146 offset:6528
	global_load_dwordx4 v[80:83], v[68:69], off
	global_load_dwordx4 v[84:87], v[72:73], off
	s_waitcnt vmcnt(0) lgkmcnt(0)
	v_pk_fma_f32 v[76:77], v[76:77], v[84:85], v[80:81]
	v_pk_fma_f32 v[78:79], v[78:79], v[86:87], v[82:83]
	v_or_b32_e32 v82, v74, v174
	global_store_dwordx4 v[70:71], v[76:79], off
	v_cmp_gt_i32_e32 vcc, s39, v82
	v_ashrrev_i32_e32 v74, 31, v82
	v_add_u32_e32 v76, 0xffff8000, v82
	v_cndmask_b32_e32 v75, 0, v74, vcc
	v_cndmask_b32_e32 v74, v76, v82, vcc
	v_cndmask_b32_e32 v77, v160, v161, vcc
	v_cndmask_b32_e32 v76, v162, v163, vcc
	v_lshlrev_b64 v[74:75], 12, v[74:75]
	v_lshl_add_u64 v[76:77], v[76:77], 0, v[74:75]
	v_cndmask_b32_e32 v79, v164, v165, vcc
	v_cndmask_b32_e32 v78, v166, v167, vcc
	v_lshl_add_u64 v[80:81], v[78:79], 0, v[74:75]
	v_lshl_add_u64 v[74:75], v[76:77], 0, v[96:97]
	v_min_i32_e32 v76, 0x8000, v82
	v_ashrrev_i32_e32 v76, 12, v76
	v_mul_hi_i32_i24_e32 v77, 0x6000, v76
	v_mul_i32_i24_e32 v76, 0x6000, v76
	v_lshl_add_u64 v[76:77], s[0:1], 0, v[76:77]
	v_lshl_add_u64 v[78:79], v[76:77], 0, v[96:97]
	v_lshl_add_u64 v[76:77], v[80:81], 0, v[96:97]
	ds_read_b128 v[80:83], v146 offset:7616
	global_load_dwordx4 v[84:87], v[74:75], off
	global_load_dwordx4 v[88:91], v[78:79], off
	s_waitcnt vmcnt(0) lgkmcnt(0)
	v_pk_fma_f32 v[80:81], v[80:81], v[88:89], v[84:85]
	v_pk_fma_f32 v[82:83], v[82:83], v[90:91], v[86:87]
	global_store_dwordx4 v[76:77], v[80:83], off
	s_waitcnt lgkmcnt(0)
	ds_write2_b32 v147, v16, v17 offset1:68
	ds_write2_b32 v148, v0, v1 offset0:32 offset1:100
	ds_write2_b32 v147, v18, v19 offset0:136 offset1:204
	ds_write2_b32 v148, v2, v3 offset0:168 offset1:236
	ds_write2_b32 v149, v20, v21 offset0:32 offset1:100
	ds_write2_b32 v150, v4, v5 offset0:64 offset1:132
	ds_write2_b32 v149, v22, v23 offset0:168 offset1:236
	ds_write2_b32 v151, v6, v7 offset0:72 offset1:140
	ds_write2_b32 v152, v24, v25 offset0:64 offset1:132
	ds_write2_b32 v153, v8, v9 offset0:96 offset1:164
	ds_write2_b32 v154, v26, v27 offset0:72 offset1:140
	ds_write2_b32 v155, v10, v11 offset0:104 offset1:172
	ds_write2_b32 v156, v28, v29 offset0:96 offset1:164
	ds_write2_b32 v157, v12, v13 offset0:128 offset1:196
	ds_write2_b32 v158, v30, v31 offset0:104 offset1:172
	ds_write2_b32 v159, v14, v15 offset0:8 offset1:76
	s_waitcnt lgkmcnt(0)
	ds_read_b128 v[0:3], v146
	global_load_dwordx4 v[4:7], v[32:33], off offset:256
	global_load_dwordx4 v[8:11], v[36:37], off offset:256
	s_waitcnt vmcnt(0) lgkmcnt(0)
	v_pk_fma_f32 v[0:1], v[0:1], v[8:9], v[4:5]
	v_pk_fma_f32 v[2:3], v[2:3], v[10:11], v[6:7]
	global_store_dwordx4 v[34:35], v[0:3], off offset:256
	ds_read_b128 v[0:3], v146 offset:1088
	global_load_dwordx4 v[4:7], v[38:39], off offset:256
	global_load_dwordx4 v[8:11], v[42:43], off offset:256
	s_waitcnt vmcnt(0) lgkmcnt(0)
	v_pk_fma_f32 v[0:1], v[0:1], v[8:9], v[4:5]
	v_pk_fma_f32 v[2:3], v[2:3], v[10:11], v[6:7]
	global_store_dwordx4 v[40:41], v[0:3], off offset:256
	ds_read_b128 v[0:3], v146 offset:2176
	global_load_dwordx4 v[4:7], v[44:45], off offset:256
	global_load_dwordx4 v[8:11], v[48:49], off offset:256
	s_waitcnt vmcnt(0) lgkmcnt(0)
	v_pk_fma_f32 v[0:1], v[0:1], v[8:9], v[4:5]
	v_pk_fma_f32 v[2:3], v[2:3], v[10:11], v[6:7]
	global_store_dwordx4 v[46:47], v[0:3], off offset:256
	ds_read_b128 v[0:3], v146 offset:3264
	global_load_dwordx4 v[4:7], v[50:51], off offset:256
	global_load_dwordx4 v[8:11], v[54:55], off offset:256
	s_waitcnt vmcnt(0) lgkmcnt(0)
	v_pk_fma_f32 v[0:1], v[0:1], v[8:9], v[4:5]
	v_pk_fma_f32 v[2:3], v[2:3], v[10:11], v[6:7]
	global_store_dwordx4 v[52:53], v[0:3], off offset:256
	ds_read_b128 v[0:3], v146 offset:4352
	global_load_dwordx4 v[4:7], v[56:57], off offset:256
	global_load_dwordx4 v[8:11], v[60:61], off offset:256
	s_waitcnt vmcnt(0) lgkmcnt(0)
	v_pk_fma_f32 v[0:1], v[0:1], v[8:9], v[4:5]
	v_pk_fma_f32 v[2:3], v[2:3], v[10:11], v[6:7]
	global_store_dwordx4 v[58:59], v[0:3], off offset:256
	ds_read_b128 v[0:3], v146 offset:5440
	global_load_dwordx4 v[4:7], v[62:63], off offset:256
	global_load_dwordx4 v[8:11], v[66:67], off offset:256
	s_waitcnt vmcnt(0) lgkmcnt(0)
	v_pk_fma_f32 v[0:1], v[0:1], v[8:9], v[4:5]
	v_pk_fma_f32 v[2:3], v[2:3], v[10:11], v[6:7]
	global_store_dwordx4 v[64:65], v[0:3], off offset:256
	ds_read_b128 v[0:3], v146 offset:6528
	global_load_dwordx4 v[4:7], v[68:69], off offset:256
	global_load_dwordx4 v[8:11], v[72:73], off offset:256
	s_waitcnt vmcnt(0) lgkmcnt(0)
	v_pk_fma_f32 v[0:1], v[0:1], v[8:9], v[4:5]
	v_pk_fma_f32 v[2:3], v[2:3], v[10:11], v[6:7]
	global_store_dwordx4 v[70:71], v[0:3], off offset:256
	ds_read_b128 v[0:3], v146 offset:7616
	global_load_dwordx4 v[4:7], v[74:75], off offset:256
	global_load_dwordx4 v[8:11], v[78:79], off offset:256
	s_waitcnt vmcnt(0) lgkmcnt(0)
	v_pk_fma_f32 v[0:1], v[0:1], v[8:9], v[4:5]
	v_pk_fma_f32 v[2:3], v[2:3], v[10:11], v[6:7]
	global_store_dwordx4 v[76:77], v[0:3], off offset:256
	s_waitcnt lgkmcnt(0)
	s_barrier
	s_cbranch_scc1 .LBB0_923

.LBB0_1031:
	s_mul_hi_i32 s0, s2, 0x2e8ba2e9
	s_lshr_b32 s1, s0, 31
	s_ashr_i32 s0, s0, 6
	s_add_i32 s0, s0, s1
	s_lshl_b32 s1, s0, 3
	s_sub_i32 s7, s25, s1
	s_min_i32 s7, s7, 8
	s_abs_i32 s8, s7
	v_cvt_f32_u32_e32 v0, s8
	s_sub_i32 s11, 0, s8
	s_mulk_i32 s0, 0xfea0
	s_add_i32 s9, s0, s2
	v_rcp_iflag_f32_e32 v0, v0
	s_abs_i32 s0, s9
	s_xor_b32 s10, s9, s7
	s_ashr_i32 s10, s10, 31
	v_mul_f32_e32 v0, 0x4f7ffffe, v0
	v_cvt_u32_f32_e32 v0, v0
	v_mov_b32_e32 v237, v179
	v_readfirstlane_b32 s12, v0
	s_mul_i32 s11, s11, s12
	s_mul_hi_u32 s11, s12, s11
	s_add_i32 s12, s12, s11
	s_mul_hi_u32 s11, s0, s12
	s_mul_i32 s12, s11, s8
	s_sub_i32 s0, s0, s12
	s_add_i32 s13, s11, 1
	s_sub_i32 s12, s0, s8
	s_cmp_ge_u32 s0, s8
	s_cselect_b32 s11, s13, s11
	s_cselect_b32 s0, s12, s0
	s_add_i32 s12, s11, 1
	s_cmp_ge_u32 s0, s8
	s_cselect_b32 s0, s12, s11
	s_xor_b32 s0, s0, s10
	s_sub_i32 s0, s0, s10
	s_mul_i32 s7, s7, s0
	s_sub_i32 s7, s9, s7
	s_add_i32 s1, s1, s6
	v_ashrrev_i32_e32 v238, 6, v237
	s_add_i32 s7, s1, s7
	v_lshlrev_b32_e32 v0, 1, v238
	v_lshl_add_u32 v0, s7, 3, v0
	v_ashrrev_i32_e32 v1, 31, v0
	v_bfe_u32 v183, v237, 5, 1
	v_lshlrev_b64 v[0:1], 16, v[0:1]
	v_and_b32_e32 v239, 31, v237
	v_lshl_add_u64 v[0:1], s[64:65], 0, v[0:1]
	v_lshlrev_b32_e32 v176, 9, v183
	s_ashr_i32 s1, s0, 31
	v_lshl_add_u64 v[0:1], v[0:1], 0, v[176:177]
	v_lshlrev_b32_e32 v176, 4, v239
	v_ashrrev_i32_e32 v38, 2, v237
	s_lshl_b64 s[8:9], s[0:1], 18
	v_lshl_add_u64 v[184:185], v[0:1], 0, v[176:177]
	s_add_u32 s8, s4, s8
	v_lshlrev_b32_e32 v0, 5, v38
	v_lshlrev_b32_e32 v2, 3, v237
	s_addc_u32 s9, s5, s9
	v_ashrrev_i32_e32 v1, 31, v0
	v_and_b32_e32 v181, 24, v2
	v_lshl_add_u64 v[0:1], v[0:1], 1, s[8:9]
	v_lshlrev_b32_e32 v176, 1, v181
	v_lshl_add_u64 v[186:187], v[0:1], 0, v[176:177]
	s_movk_i32 s1, 0x2000
	v_add_co_u32_e32 v34, vcc, s1, v186
	v_mul_u32_u24_e32 v36, 40, v239
	s_nop 0
	v_addc_co_u32_e32 v35, vcc, 0, v187, vcc
	v_lshlrev_b32_e32 v37, 4, v183
	v_lshl_add_u32 v241, v36, 1, v37
	v_add_co_u32_e32 v36, vcc, s41, v184
	s_movk_i32 s8, 0x50
	s_nop 0
	v_addc_co_u32_e32 v37, vcc, 0, v185, vcc
	v_mad_u64_u32 v[188:189], s[8:9], v38, s8, v[176:177]
	v_and_b32_e32 v240, 63, v237
	v_bfe_u32 v247, v237, 4, 2
	v_lshlrev_b32_e32 v247, 1, v247
	v_mov_b32_e32 v176, 0x78
	v_lshrrev_b32_e32 v247, v247, v176
	v_and_b32_e32 v247, 3, v247
	v_and_b32_e32 v246, 3, v237
	v_xor_b32_e32 v247, v247, v246
	v_lshlrev_b32_e32 v247, 4, v247
	v_and_b32_e32 v188, 0xffffffcf, v186
	v_or_b32_e32 v188, v188, v247
	v_mov_b32_e32 v189, v187
	v_lshrrev_b32_e32 v176, 6, v237
	v_lshlrev_b32_e32 v247, 11, v176
	v_lshlrev_b32_e32 v176, 10, v176
	v_lshl_add_u64 v[188:189], v[188:189], 0, v[176:177]
	v_readfirstlane_b32 vcc_lo, v247
	v_bfe_u32 v247, v237, 4, 1
	v_lshlrev_b32_e32 v176, 9, v183
	v_lshl_add_u32 v176, v247, 8, v176
	v_lshl_add_u64 v[184:185], v[184:185], 0, v[176:177]
	v_mov_b32_e32 v176, s41
	v_lshl_add_u64 v[186:187], v[184:185], 0, v[176:177]
	v_mov_b32_e32 v176, 0x78
	v_bfe_u32 v247, v237, 2, 2
	v_lshlrev_b32_e32 v247, 1, v247
	v_lshrrev_b32_e32 v247, v247, v176
	v_and_b32_e32 v247, 3, v247
	v_bfe_u32 v246, v237, 4, 2
	v_xor_b32_e32 v247, v247, v246
	v_lshlrev_b32_e32 v247, 4, v247
	v_and_b32_e32 v246, 15, v237
	v_lshl_add_u32 v246, v246, 6, v247
	s_mov_b32 s96, 0
	s_mov_b32 m0, vcc_lo
	v_lshl_add_u64 v[248:249], v[188:189], 0, s[96:97]
	global_load_lds_dwordx4 v[248:249], off
	global_load_lds_dwordx4 v[248:249], off offset:1024
	s_mov_b32 s96, 0
	v_lshl_add_u64 v[248:249], v[184:185], 0, s[96:97]
	v_lshl_add_u64 v[250:251], v[186:187], 0, s[96:97]
	global_load_dwordx4 v[128:131], v[248:249], off
	global_load_dwordx4 v[132:135], v[248:249], off offset:256
	global_load_dwordx4 v[136:139], v[250:251], off
	global_load_dwordx4 v[140:143], v[250:251], off offset:256
	s_movk_i32 s96, 0x800
	v_lshl_add_u64 v[248:249], v[184:185], 0, s[96:97]
	v_lshl_add_u64 v[250:251], v[186:187], 0, s[96:97]
	global_load_dwordx4 v[144:147], v[248:249], off
	global_load_dwordx4 v[148:151], v[248:249], off offset:256
	global_load_dwordx4 v[152:155], v[250:251], off
	global_load_dwordx4 v[156:159], v[250:251], off offset:256
	s_movk_i32 s96, 0x2000
	s_add_i32 m0, vcc_lo, 8192
	v_lshl_add_u64 v[248:249], v[188:189], 0, s[96:97]
	global_load_lds_dwordx4 v[248:249], off
	global_load_lds_dwordx4 v[248:249], off offset:1024
	s_movk_i32 s96, 0x1000
	v_lshl_add_u64 v[248:249], v[184:185], 0, s[96:97]
	v_lshl_add_u64 v[250:251], v[186:187], 0, s[96:97]
	global_load_dwordx4 v[160:163], v[248:249], off
	global_load_dwordx4 v[164:167], v[248:249], off offset:256
	global_load_dwordx4 v[168:171], v[250:251], off
	global_load_dwordx4 v[172:175], v[250:251], off offset:256
	v_mov_b32_e32 v0, 0
	v_mov_b32_e32 v1, 0
	v_mov_b32_e32 v2, 0
	v_mov_b32_e32 v3, 0
	v_mov_b32_e32 v4, 0
	v_mov_b32_e32 v5, 0
	v_mov_b32_e32 v6, 0
	v_mov_b32_e32 v7, 0
	v_mov_b32_e32 v8, 0
	v_mov_b32_e32 v9, 0
	v_mov_b32_e32 v10, 0
	v_mov_b32_e32 v11, 0
	v_mov_b32_e32 v12, 0
	v_mov_b32_e32 v13, 0
	v_mov_b32_e32 v14, 0
	v_mov_b32_e32 v15, 0
	v_mov_b32_e32 v16, 0
	v_mov_b32_e32 v17, 0
	v_mov_b32_e32 v18, 0
	v_mov_b32_e32 v19, 0
	v_mov_b32_e32 v20, 0
	v_mov_b32_e32 v21, 0
	v_mov_b32_e32 v22, 0
	v_mov_b32_e32 v23, 0
	v_mov_b32_e32 v24, 0
	v_mov_b32_e32 v25, 0
	v_mov_b32_e32 v26, 0
	v_mov_b32_e32 v27, 0
	v_mov_b32_e32 v28, 0
	v_mov_b32_e32 v29, 0
	v_mov_b32_e32 v30, 0
	v_mov_b32_e32 v31, 0
	v_mov_b32_e32 v32, 0
	v_mov_b32_e32 v33, 0
	v_mov_b32_e32 v34, 0
	v_mov_b32_e32 v35, 0
	v_mov_b32_e32 v36, 0
	v_mov_b32_e32 v37, 0
	v_mov_b32_e32 v38, 0
	v_mov_b32_e32 v39, 0
	v_mov_b32_e32 v40, 0
	v_mov_b32_e32 v41, 0
	v_mov_b32_e32 v42, 0
	v_mov_b32_e32 v43, 0
	v_mov_b32_e32 v44, 0
	v_mov_b32_e32 v45, 0
	v_mov_b32_e32 v46, 0
	v_mov_b32_e32 v47, 0
	v_mov_b32_e32 v48, 0
	v_mov_b32_e32 v49, 0
	v_mov_b32_e32 v50, 0
	v_mov_b32_e32 v51, 0
	v_mov_b32_e32 v52, 0
	v_mov_b32_e32 v53, 0
	v_mov_b32_e32 v54, 0
	v_mov_b32_e32 v55, 0
	v_mov_b32_e32 v56, 0
	v_mov_b32_e32 v57, 0
	v_mov_b32_e32 v58, 0
	v_mov_b32_e32 v59, 0
	v_mov_b32_e32 v60, 0
	v_mov_b32_e32 v61, 0
	v_mov_b32_e32 v62, 0
	v_mov_b32_e32 v63, 0
	v_mov_b32_e32 v64, 0
	v_mov_b32_e32 v65, 0
	v_mov_b32_e32 v66, 0
	v_mov_b32_e32 v67, 0
	v_mov_b32_e32 v68, 0
	v_mov_b32_e32 v69, 0
	v_mov_b32_e32 v70, 0
	v_mov_b32_e32 v71, 0
	v_mov_b32_e32 v72, 0
	v_mov_b32_e32 v73, 0
	v_mov_b32_e32 v74, 0
	v_mov_b32_e32 v75, 0
	v_mov_b32_e32 v76, 0
	v_mov_b32_e32 v77, 0
	v_mov_b32_e32 v78, 0
	v_mov_b32_e32 v79, 0
	v_mov_b32_e32 v80, 0
	v_mov_b32_e32 v81, 0
	v_mov_b32_e32 v82, 0
	v_mov_b32_e32 v83, 0
	v_mov_b32_e32 v84, 0
	v_mov_b32_e32 v85, 0
	v_mov_b32_e32 v86, 0
	v_mov_b32_e32 v87, 0
	v_mov_b32_e32 v88, 0
	v_mov_b32_e32 v89, 0
	v_mov_b32_e32 v90, 0
	v_mov_b32_e32 v91, 0
	v_mov_b32_e32 v92, 0
	v_mov_b32_e32 v93, 0
	v_mov_b32_e32 v94, 0
	v_mov_b32_e32 v95, 0
	v_mov_b32_e32 v96, 0
	v_mov_b32_e32 v97, 0
	v_mov_b32_e32 v98, 0
	v_mov_b32_e32 v99, 0
	v_mov_b32_e32 v100, 0
	v_mov_b32_e32 v101, 0
	v_mov_b32_e32 v102, 0
	v_mov_b32_e32 v103, 0
	v_mov_b32_e32 v104, 0
	v_mov_b32_e32 v105, 0
	v_mov_b32_e32 v106, 0
	v_mov_b32_e32 v107, 0
	v_mov_b32_e32 v108, 0
	v_mov_b32_e32 v109, 0
	v_mov_b32_e32 v110, 0
	v_mov_b32_e32 v111, 0
	v_mov_b32_e32 v112, 0
	v_mov_b32_e32 v113, 0
	v_mov_b32_e32 v114, 0
	v_mov_b32_e32 v115, 0
	v_mov_b32_e32 v116, 0
	v_mov_b32_e32 v117, 0
	v_mov_b32_e32 v118, 0
	v_mov_b32_e32 v119, 0
	v_mov_b32_e32 v120, 0
	v_mov_b32_e32 v121, 0
	v_mov_b32_e32 v122, 0
	v_mov_b32_e32 v123, 0
	v_mov_b32_e32 v124, 0
	v_mov_b32_e32 v125, 0
	v_mov_b32_e32 v126, 0
	v_mov_b32_e32 v127, 0
	s_mov_b32 s1, 0
	s_waitcnt vmcnt(10)
	s_barrier
.Lg16_gu_k:
	s_add_i32 s8, s1, 2
	s_lshl_b32 s96, s8, 13
	s_add_i32 m0, vcc_lo, 16384
	v_lshl_add_u64 v[248:249], v[188:189], 0, s[96:97]
	global_load_lds_dwordx4 v[248:249], off
	global_load_lds_dwordx4 v[248:249], off offset:1024
	ds_read_b128 v[196:199], v246 offset:0
	ds_read_b128 v[200:203], v246 offset:1024
	ds_read_b128 v[204:207], v246 offset:2048
	ds_read_b128 v[242:245], v246 offset:3072
	s_add_i32 s8, s1, 3
	s_min_u32 s8, s8, 31
	s_lshl_b32 s96, s8, 11
	v_lshl_add_u64 v[248:249], v[184:185], 0, s[96:97]
	v_lshl_add_u64 v[250:251], v[186:187], 0, s[96:97]
	s_waitcnt lgkmcnt(3)
	v_mfma_f32_16x16x32_bf16 v[112:115], v[128:131], v[196:199], v[112:115]
	v_mfma_f32_16x16x32_bf16 v[120:123], v[132:135], v[196:199], v[120:123]
	v_mfma_f32_16x16x32_bf16 v[80:83], v[136:139], v[196:199], v[80:83]
	v_mfma_f32_16x16x32_bf16 v[88:91], v[140:143], v[196:199], v[88:91]
	ds_read_b128 v[196:199], v246 offset:4096
	s_waitcnt lgkmcnt(3)
	v_mfma_f32_16x16x32_bf16 v[116:119], v[128:131], v[200:203], v[116:119]
	v_mfma_f32_16x16x32_bf16 v[124:127], v[132:135], v[200:203], v[124:127]
	v_mfma_f32_16x16x32_bf16 v[84:87], v[136:139], v[200:203], v[84:87]
	v_mfma_f32_16x16x32_bf16 v[92:95], v[140:143], v[200:203], v[92:95]
	ds_read_b128 v[200:203], v246 offset:5120
	s_waitcnt lgkmcnt(3)
	v_mfma_f32_16x16x32_bf16 v[96:99], v[128:131], v[204:207], v[96:99]
	v_mfma_f32_16x16x32_bf16 v[104:107], v[132:135], v[204:207], v[104:107]
	v_mfma_f32_16x16x32_bf16 v[64:67], v[136:139], v[204:207], v[64:67]
	v_mfma_f32_16x16x32_bf16 v[72:75], v[140:143], v[204:207], v[72:75]
	ds_read_b128 v[204:207], v246 offset:6144
	s_waitcnt lgkmcnt(3)
	v_mfma_f32_16x16x32_bf16 v[100:103], v[128:131], v[242:245], v[100:103]
	v_mfma_f32_16x16x32_bf16 v[108:111], v[132:135], v[242:245], v[108:111]
	v_mfma_f32_16x16x32_bf16 v[68:71], v[136:139], v[242:245], v[68:71]
	v_mfma_f32_16x16x32_bf16 v[76:79], v[140:143], v[242:245], v[76:79]
	ds_read_b128 v[242:245], v246 offset:7168
	s_waitcnt lgkmcnt(3)
	v_mfma_f32_16x16x32_bf16 v[48:51], v[128:131], v[196:199], v[48:51]
	v_mfma_f32_16x16x32_bf16 v[56:59], v[132:135], v[196:199], v[56:59]
	v_mfma_f32_16x16x32_bf16 v[16:19], v[136:139], v[196:199], v[16:19]
	v_mfma_f32_16x16x32_bf16 v[24:27], v[140:143], v[196:199], v[24:27]
	s_waitcnt lgkmcnt(2)
	v_mfma_f32_16x16x32_bf16 v[52:55], v[128:131], v[200:203], v[52:55]
	v_mfma_f32_16x16x32_bf16 v[60:63], v[132:135], v[200:203], v[60:63]
	v_mfma_f32_16x16x32_bf16 v[20:23], v[136:139], v[200:203], v[20:23]
	v_mfma_f32_16x16x32_bf16 v[28:31], v[140:143], v[200:203], v[28:31]
	s_waitcnt lgkmcnt(1)
	v_mfma_f32_16x16x32_bf16 v[32:35], v[128:131], v[204:207], v[32:35]
	v_mfma_f32_16x16x32_bf16 v[40:43], v[132:135], v[204:207], v[40:43]
	v_mfma_f32_16x16x32_bf16 v[0:3], v[136:139], v[204:207], v[0:3]
	v_mfma_f32_16x16x32_bf16 v[8:11], v[140:143], v[204:207], v[8:11]
	s_waitcnt lgkmcnt(0)
	v_mfma_f32_16x16x32_bf16 v[36:39], v[128:131], v[242:245], v[36:39]
	v_mfma_f32_16x16x32_bf16 v[44:47], v[132:135], v[242:245], v[44:47]
	v_mfma_f32_16x16x32_bf16 v[4:7], v[136:139], v[242:245], v[4:7]
	v_mfma_f32_16x16x32_bf16 v[12:15], v[140:143], v[242:245], v[12:15]
	global_load_dwordx4 v[128:131], v[248:249], off
	global_load_dwordx4 v[132:135], v[248:249], off offset:256
	global_load_dwordx4 v[136:139], v[250:251], off
	global_load_dwordx4 v[140:143], v[250:251], off offset:256
	s_waitcnt vmcnt(10)
	s_barrier
	s_add_i32 s8, s1, 3
	s_lshl_b32 s96, s8, 13
	s_mov_b32 m0, vcc_lo
	v_lshl_add_u64 v[248:249], v[188:189], 0, s[96:97]
	global_load_lds_dwordx4 v[248:249], off
	global_load_lds_dwordx4 v[248:249], off offset:1024
	ds_read_b128 v[196:199], v246 offset:8192
	ds_read_b128 v[200:203], v246 offset:9216
	ds_read_b128 v[204:207], v246 offset:10240
	ds_read_b128 v[242:245], v246 offset:11264
	s_add_i32 s8, s1, 4
	s_min_u32 s8, s8, 31
	s_lshl_b32 s96, s8, 11
	v_lshl_add_u64 v[248:249], v[184:185], 0, s[96:97]
	v_lshl_add_u64 v[250:251], v[186:187], 0, s[96:97]
	s_waitcnt lgkmcnt(3)
	v_mfma_f32_16x16x32_bf16 v[112:115], v[144:147], v[196:199], v[112:115]
	v_mfma_f32_16x16x32_bf16 v[120:123], v[148:151], v[196:199], v[120:123]
	v_mfma_f32_16x16x32_bf16 v[80:83], v[152:155], v[196:199], v[80:83]
	v_mfma_f32_16x16x32_bf16 v[88:91], v[156:159], v[196:199], v[88:91]
	ds_read_b128 v[196:199], v246 offset:12288
	s_waitcnt lgkmcnt(3)
	v_mfma_f32_16x16x32_bf16 v[116:119], v[144:147], v[200:203], v[116:119]
	v_mfma_f32_16x16x32_bf16 v[124:127], v[148:151], v[200:203], v[124:127]
	v_mfma_f32_16x16x32_bf16 v[84:87], v[152:155], v[200:203], v[84:87]
	v_mfma_f32_16x16x32_bf16 v[92:95], v[156:159], v[200:203], v[92:95]
	ds_read_b128 v[200:203], v246 offset:13312
	s_waitcnt lgkmcnt(3)
	v_mfma_f32_16x16x32_bf16 v[96:99], v[144:147], v[204:207], v[96:99]
	v_mfma_f32_16x16x32_bf16 v[104:107], v[148:151], v[204:207], v[104:107]
	v_mfma_f32_16x16x32_bf16 v[64:67], v[152:155], v[204:207], v[64:67]
	v_mfma_f32_16x16x32_bf16 v[72:75], v[156:159], v[204:207], v[72:75]
	ds_read_b128 v[204:207], v246 offset:14336
	s_waitcnt lgkmcnt(3)
	v_mfma_f32_16x16x32_bf16 v[100:103], v[144:147], v[242:245], v[100:103]
	v_mfma_f32_16x16x32_bf16 v[108:111], v[148:151], v[242:245], v[108:111]
	v_mfma_f32_16x16x32_bf16 v[68:71], v[152:155], v[242:245], v[68:71]
	v_mfma_f32_16x16x32_bf16 v[76:79], v[156:159], v[242:245], v[76:79]
	ds_read_b128 v[242:245], v246 offset:15360
	s_waitcnt lgkmcnt(3)
	v_mfma_f32_16x16x32_bf16 v[48:51], v[144:147], v[196:199], v[48:51]
	v_mfma_f32_16x16x32_bf16 v[56:59], v[148:151], v[196:199], v[56:59]
	v_mfma_f32_16x16x32_bf16 v[16:19], v[152:155], v[196:199], v[16:19]
	v_mfma_f32_16x16x32_bf16 v[24:27], v[156:159], v[196:199], v[24:27]
	s_waitcnt lgkmcnt(2)
	v_mfma_f32_16x16x32_bf16 v[52:55], v[144:147], v[200:203], v[52:55]
	v_mfma_f32_16x16x32_bf16 v[60:63], v[148:151], v[200:203], v[60:63]
	v_mfma_f32_16x16x32_bf16 v[20:23], v[152:155], v[200:203], v[20:23]
	v_mfma_f32_16x16x32_bf16 v[28:31], v[156:159], v[200:203], v[28:31]
	s_waitcnt lgkmcnt(1)
	v_mfma_f32_16x16x32_bf16 v[32:35], v[144:147], v[204:207], v[32:35]
	v_mfma_f32_16x16x32_bf16 v[40:43], v[148:151], v[204:207], v[40:43]
	v_mfma_f32_16x16x32_bf16 v[0:3], v[152:155], v[204:207], v[0:3]
	v_mfma_f32_16x16x32_bf16 v[8:11], v[156:159], v[204:207], v[8:11]
	s_waitcnt lgkmcnt(0)
	v_mfma_f32_16x16x32_bf16 v[36:39], v[144:147], v[242:245], v[36:39]
	v_mfma_f32_16x16x32_bf16 v[44:47], v[148:151], v[242:245], v[44:47]
	v_mfma_f32_16x16x32_bf16 v[4:7], v[152:155], v[242:245], v[4:7]
	v_mfma_f32_16x16x32_bf16 v[12:15], v[156:159], v[242:245], v[12:15]
	global_load_dwordx4 v[144:147], v[248:249], off
	global_load_dwordx4 v[148:151], v[248:249], off offset:256
	global_load_dwordx4 v[152:155], v[250:251], off
	global_load_dwordx4 v[156:159], v[250:251], off offset:256
	s_waitcnt vmcnt(10)
	s_barrier
	s_add_i32 s8, s1, 4
	s_lshl_b32 s96, s8, 13
	s_add_i32 m0, vcc_lo, 8192
	v_lshl_add_u64 v[248:249], v[188:189], 0, s[96:97]
	global_load_lds_dwordx4 v[248:249], off
	global_load_lds_dwordx4 v[248:249], off offset:1024
	ds_read_b128 v[196:199], v246 offset:16384
	ds_read_b128 v[200:203], v246 offset:17408
	ds_read_b128 v[204:207], v246 offset:18432
	ds_read_b128 v[242:245], v246 offset:19456
	s_add_i32 s8, s1, 5
	s_min_u32 s8, s8, 31
	s_lshl_b32 s96, s8, 11
	v_lshl_add_u64 v[248:249], v[184:185], 0, s[96:97]
	v_lshl_add_u64 v[250:251], v[186:187], 0, s[96:97]
	s_waitcnt lgkmcnt(3)
	v_mfma_f32_16x16x32_bf16 v[112:115], v[160:163], v[196:199], v[112:115]
	v_mfma_f32_16x16x32_bf16 v[120:123], v[164:167], v[196:199], v[120:123]
	v_mfma_f32_16x16x32_bf16 v[80:83], v[168:171], v[196:199], v[80:83]
	v_mfma_f32_16x16x32_bf16 v[88:91], v[172:175], v[196:199], v[88:91]
	ds_read_b128 v[196:199], v246 offset:20480
	s_waitcnt lgkmcnt(3)
	v_mfma_f32_16x16x32_bf16 v[116:119], v[160:163], v[200:203], v[116:119]
	v_mfma_f32_16x16x32_bf16 v[124:127], v[164:167], v[200:203], v[124:127]
	v_mfma_f32_16x16x32_bf16 v[84:87], v[168:171], v[200:203], v[84:87]
	v_mfma_f32_16x16x32_bf16 v[92:95], v[172:175], v[200:203], v[92:95]
	ds_read_b128 v[200:203], v246 offset:21504
	s_waitcnt lgkmcnt(3)
	v_mfma_f32_16x16x32_bf16 v[96:99], v[160:163], v[204:207], v[96:99]
	v_mfma_f32_16x16x32_bf16 v[104:107], v[164:167], v[204:207], v[104:107]
	v_mfma_f32_16x16x32_bf16 v[64:67], v[168:171], v[204:207], v[64:67]
	v_mfma_f32_16x16x32_bf16 v[72:75], v[172:175], v[204:207], v[72:75]
	ds_read_b128 v[204:207], v246 offset:22528
	s_waitcnt lgkmcnt(3)
	v_mfma_f32_16x16x32_bf16 v[100:103], v[160:163], v[242:245], v[100:103]
	v_mfma_f32_16x16x32_bf16 v[108:111], v[164:167], v[242:245], v[108:111]
	v_mfma_f32_16x16x32_bf16 v[68:71], v[168:171], v[242:245], v[68:71]
	v_mfma_f32_16x16x32_bf16 v[76:79], v[172:175], v[242:245], v[76:79]
	ds_read_b128 v[242:245], v246 offset:23552
	s_waitcnt lgkmcnt(3)
	v_mfma_f32_16x16x32_bf16 v[48:51], v[160:163], v[196:199], v[48:51]
	v_mfma_f32_16x16x32_bf16 v[56:59], v[164:167], v[196:199], v[56:59]
	v_mfma_f32_16x16x32_bf16 v[16:19], v[168:171], v[196:199], v[16:19]
	v_mfma_f32_16x16x32_bf16 v[24:27], v[172:175], v[196:199], v[24:27]
	s_waitcnt lgkmcnt(2)
	v_mfma_f32_16x16x32_bf16 v[52:55], v[160:163], v[200:203], v[52:55]
	v_mfma_f32_16x16x32_bf16 v[60:63], v[164:167], v[200:203], v[60:63]
	v_mfma_f32_16x16x32_bf16 v[20:23], v[168:171], v[200:203], v[20:23]
	v_mfma_f32_16x16x32_bf16 v[28:31], v[172:175], v[200:203], v[28:31]
	s_waitcnt lgkmcnt(1)
	v_mfma_f32_16x16x32_bf16 v[32:35], v[160:163], v[204:207], v[32:35]
	v_mfma_f32_16x16x32_bf16 v[40:43], v[164:167], v[204:207], v[40:43]
	v_mfma_f32_16x16x32_bf16 v[0:3], v[168:171], v[204:207], v[0:3]
	v_mfma_f32_16x16x32_bf16 v[8:11], v[172:175], v[204:207], v[8:11]
	s_waitcnt lgkmcnt(0)
	v_mfma_f32_16x16x32_bf16 v[36:39], v[160:163], v[242:245], v[36:39]
	v_mfma_f32_16x16x32_bf16 v[44:47], v[164:167], v[242:245], v[44:47]
	v_mfma_f32_16x16x32_bf16 v[4:7], v[168:171], v[242:245], v[4:7]
	v_mfma_f32_16x16x32_bf16 v[12:15], v[172:175], v[242:245], v[12:15]
	global_load_dwordx4 v[160:163], v[248:249], off
	global_load_dwordx4 v[164:167], v[248:249], off offset:256
	global_load_dwordx4 v[168:171], v[250:251], off
	global_load_dwordx4 v[172:175], v[250:251], off offset:256
	s_waitcnt vmcnt(10)
	s_barrier
	s_add_i32 s8, s1, 5
	s_lshl_b32 s96, s8, 13
	s_add_i32 m0, vcc_lo, 16384
	v_lshl_add_u64 v[248:249], v[188:189], 0, s[96:97]
	global_load_lds_dwordx4 v[248:249], off
	global_load_lds_dwordx4 v[248:249], off offset:1024
	ds_read_b128 v[196:199], v246 offset:0
	ds_read_b128 v[200:203], v246 offset:1024
	ds_read_b128 v[204:207], v246 offset:2048
	ds_read_b128 v[242:245], v246 offset:3072
	s_add_i32 s8, s1, 6
	s_min_u32 s8, s8, 31
	s_lshl_b32 s96, s8, 11
	v_lshl_add_u64 v[248:249], v[184:185], 0, s[96:97]
	v_lshl_add_u64 v[250:251], v[186:187], 0, s[96:97]
	s_waitcnt lgkmcnt(3)
	v_mfma_f32_16x16x32_bf16 v[112:115], v[128:131], v[196:199], v[112:115]
	v_mfma_f32_16x16x32_bf16 v[120:123], v[132:135], v[196:199], v[120:123]
	v_mfma_f32_16x16x32_bf16 v[80:83], v[136:139], v[196:199], v[80:83]
	v_mfma_f32_16x16x32_bf16 v[88:91], v[140:143], v[196:199], v[88:91]
	ds_read_b128 v[196:199], v246 offset:4096
	s_waitcnt lgkmcnt(3)
	v_mfma_f32_16x16x32_bf16 v[116:119], v[128:131], v[200:203], v[116:119]
	v_mfma_f32_16x16x32_bf16 v[124:127], v[132:135], v[200:203], v[124:127]
	v_mfma_f32_16x16x32_bf16 v[84:87], v[136:139], v[200:203], v[84:87]
	v_mfma_f32_16x16x32_bf16 v[92:95], v[140:143], v[200:203], v[92:95]
	ds_read_b128 v[200:203], v246 offset:5120
	s_waitcnt lgkmcnt(3)
	v_mfma_f32_16x16x32_bf16 v[96:99], v[128:131], v[204:207], v[96:99]
	v_mfma_f32_16x16x32_bf16 v[104:107], v[132:135], v[204:207], v[104:107]
	v_mfma_f32_16x16x32_bf16 v[64:67], v[136:139], v[204:207], v[64:67]
	v_mfma_f32_16x16x32_bf16 v[72:75], v[140:143], v[204:207], v[72:75]
	ds_read_b128 v[204:207], v246 offset:6144
	s_waitcnt lgkmcnt(3)
	v_mfma_f32_16x16x32_bf16 v[100:103], v[128:131], v[242:245], v[100:103]
	v_mfma_f32_16x16x32_bf16 v[108:111], v[132:135], v[242:245], v[108:111]
	v_mfma_f32_16x16x32_bf16 v[68:71], v[136:139], v[242:245], v[68:71]
	v_mfma_f32_16x16x32_bf16 v[76:79], v[140:143], v[242:245], v[76:79]
	ds_read_b128 v[242:245], v246 offset:7168
	s_waitcnt lgkmcnt(3)
	v_mfma_f32_16x16x32_bf16 v[48:51], v[128:131], v[196:199], v[48:51]
	v_mfma_f32_16x16x32_bf16 v[56:59], v[132:135], v[196:199], v[56:59]
	v_mfma_f32_16x16x32_bf16 v[16:19], v[136:139], v[196:199], v[16:19]
	v_mfma_f32_16x16x32_bf16 v[24:27], v[140:143], v[196:199], v[24:27]
	s_waitcnt lgkmcnt(2)
	v_mfma_f32_16x16x32_bf16 v[52:55], v[128:131], v[200:203], v[52:55]
	v_mfma_f32_16x16x32_bf16 v[60:63], v[132:135], v[200:203], v[60:63]
	v_mfma_f32_16x16x32_bf16 v[20:23], v[136:139], v[200:203], v[20:23]
	v_mfma_f32_16x16x32_bf16 v[28:31], v[140:143], v[200:203], v[28:31]
	s_waitcnt lgkmcnt(1)
	v_mfma_f32_16x16x32_bf16 v[32:35], v[128:131], v[204:207], v[32:35]
	v_mfma_f32_16x16x32_bf16 v[40:43], v[132:135], v[204:207], v[40:43]
	v_mfma_f32_16x16x32_bf16 v[0:3], v[136:139], v[204:207], v[0:3]
	v_mfma_f32_16x16x32_bf16 v[8:11], v[140:143], v[204:207], v[8:11]
	s_waitcnt lgkmcnt(0)
	v_mfma_f32_16x16x32_bf16 v[36:39], v[128:131], v[242:245], v[36:39]
	v_mfma_f32_16x16x32_bf16 v[44:47], v[132:135], v[242:245], v[44:47]
	v_mfma_f32_16x16x32_bf16 v[4:7], v[136:139], v[242:245], v[4:7]
	v_mfma_f32_16x16x32_bf16 v[12:15], v[140:143], v[242:245], v[12:15]
	global_load_dwordx4 v[128:131], v[248:249], off
	global_load_dwordx4 v[132:135], v[248:249], off offset:256
	global_load_dwordx4 v[136:139], v[250:251], off
	global_load_dwordx4 v[140:143], v[250:251], off offset:256
	s_waitcnt vmcnt(10)
	s_barrier
	s_add_i32 s8, s1, 6
	s_lshl_b32 s96, s8, 13
	s_mov_b32 m0, vcc_lo
	v_lshl_add_u64 v[248:249], v[188:189], 0, s[96:97]
	global_load_lds_dwordx4 v[248:249], off
	global_load_lds_dwordx4 v[248:249], off offset:1024
	ds_read_b128 v[196:199], v246 offset:8192
	ds_read_b128 v[200:203], v246 offset:9216
	ds_read_b128 v[204:207], v246 offset:10240
	ds_read_b128 v[242:245], v246 offset:11264
	s_add_i32 s8, s1, 7
	s_min_u32 s8, s8, 31
	s_lshl_b32 s96, s8, 11
	v_lshl_add_u64 v[248:249], v[184:185], 0, s[96:97]
	v_lshl_add_u64 v[250:251], v[186:187], 0, s[96:97]
	s_waitcnt lgkmcnt(3)
	v_mfma_f32_16x16x32_bf16 v[112:115], v[144:147], v[196:199], v[112:115]
	v_mfma_f32_16x16x32_bf16 v[120:123], v[148:151], v[196:199], v[120:123]
	v_mfma_f32_16x16x32_bf16 v[80:83], v[152:155], v[196:199], v[80:83]
	v_mfma_f32_16x16x32_bf16 v[88:91], v[156:159], v[196:199], v[88:91]
	ds_read_b128 v[196:199], v246 offset:12288
	s_waitcnt lgkmcnt(3)
	v_mfma_f32_16x16x32_bf16 v[116:119], v[144:147], v[200:203], v[116:119]
	v_mfma_f32_16x16x32_bf16 v[124:127], v[148:151], v[200:203], v[124:127]
	v_mfma_f32_16x16x32_bf16 v[84:87], v[152:155], v[200:203], v[84:87]
	v_mfma_f32_16x16x32_bf16 v[92:95], v[156:159], v[200:203], v[92:95]
	ds_read_b128 v[200:203], v246 offset:13312
	s_waitcnt lgkmcnt(3)
	v_mfma_f32_16x16x32_bf16 v[96:99], v[144:147], v[204:207], v[96:99]
	v_mfma_f32_16x16x32_bf16 v[104:107], v[148:151], v[204:207], v[104:107]
	v_mfma_f32_16x16x32_bf16 v[64:67], v[152:155], v[204:207], v[64:67]
	v_mfma_f32_16x16x32_bf16 v[72:75], v[156:159], v[204:207], v[72:75]
	ds_read_b128 v[204:207], v246 offset:14336
	s_waitcnt lgkmcnt(3)
	v_mfma_f32_16x16x32_bf16 v[100:103], v[144:147], v[242:245], v[100:103]
	v_mfma_f32_16x16x32_bf16 v[108:111], v[148:151], v[242:245], v[108:111]
	v_mfma_f32_16x16x32_bf16 v[68:71], v[152:155], v[242:245], v[68:71]
	v_mfma_f32_16x16x32_bf16 v[76:79], v[156:159], v[242:245], v[76:79]
	ds_read_b128 v[242:245], v246 offset:15360
	s_waitcnt lgkmcnt(3)
	v_mfma_f32_16x16x32_bf16 v[48:51], v[144:147], v[196:199], v[48:51]
	v_mfma_f32_16x16x32_bf16 v[56:59], v[148:151], v[196:199], v[56:59]
	v_mfma_f32_16x16x32_bf16 v[16:19], v[152:155], v[196:199], v[16:19]
	v_mfma_f32_16x16x32_bf16 v[24:27], v[156:159], v[196:199], v[24:27]
	s_waitcnt lgkmcnt(2)
	v_mfma_f32_16x16x32_bf16 v[52:55], v[144:147], v[200:203], v[52:55]
	v_mfma_f32_16x16x32_bf16 v[60:63], v[148:151], v[200:203], v[60:63]
	v_mfma_f32_16x16x32_bf16 v[20:23], v[152:155], v[200:203], v[20:23]
	v_mfma_f32_16x16x32_bf16 v[28:31], v[156:159], v[200:203], v[28:31]
	s_waitcnt lgkmcnt(1)
	v_mfma_f32_16x16x32_bf16 v[32:35], v[144:147], v[204:207], v[32:35]
	v_mfma_f32_16x16x32_bf16 v[40:43], v[148:151], v[204:207], v[40:43]
	v_mfma_f32_16x16x32_bf16 v[0:3], v[152:155], v[204:207], v[0:3]
	v_mfma_f32_16x16x32_bf16 v[8:11], v[156:159], v[204:207], v[8:11]
	s_waitcnt lgkmcnt(0)
	v_mfma_f32_16x16x32_bf16 v[36:39], v[144:147], v[242:245], v[36:39]
	v_mfma_f32_16x16x32_bf16 v[44:47], v[148:151], v[242:245], v[44:47]
	v_mfma_f32_16x16x32_bf16 v[4:7], v[152:155], v[242:245], v[4:7]
	v_mfma_f32_16x16x32_bf16 v[12:15], v[156:159], v[242:245], v[12:15]
	global_load_dwordx4 v[144:147], v[248:249], off
	global_load_dwordx4 v[148:151], v[248:249], off offset:256
	global_load_dwordx4 v[152:155], v[250:251], off
	global_load_dwordx4 v[156:159], v[250:251], off offset:256
	s_waitcnt vmcnt(10)
	s_barrier
	s_add_i32 s8, s1, 7
	s_lshl_b32 s96, s8, 13
	s_add_i32 m0, vcc_lo, 8192
	v_lshl_add_u64 v[248:249], v[188:189], 0, s[96:97]
	global_load_lds_dwordx4 v[248:249], off
	global_load_lds_dwordx4 v[248:249], off offset:1024
	ds_read_b128 v[196:199], v246 offset:16384
	ds_read_b128 v[200:203], v246 offset:17408
	ds_read_b128 v[204:207], v246 offset:18432
	ds_read_b128 v[242:245], v246 offset:19456
	s_add_i32 s8, s1, 8
	s_min_u32 s8, s8, 31
	s_lshl_b32 s96, s8, 11
	v_lshl_add_u64 v[248:249], v[184:185], 0, s[96:97]
	v_lshl_add_u64 v[250:251], v[186:187], 0, s[96:97]
	s_waitcnt lgkmcnt(3)
	v_mfma_f32_16x16x32_bf16 v[112:115], v[160:163], v[196:199], v[112:115]
	v_mfma_f32_16x16x32_bf16 v[120:123], v[164:167], v[196:199], v[120:123]
	v_mfma_f32_16x16x32_bf16 v[80:83], v[168:171], v[196:199], v[80:83]
	v_mfma_f32_16x16x32_bf16 v[88:91], v[172:175], v[196:199], v[88:91]
	ds_read_b128 v[196:199], v246 offset:20480
	s_waitcnt lgkmcnt(3)
	v_mfma_f32_16x16x32_bf16 v[116:119], v[160:163], v[200:203], v[116:119]
	v_mfma_f32_16x16x32_bf16 v[124:127], v[164:167], v[200:203], v[124:127]
	v_mfma_f32_16x16x32_bf16 v[84:87], v[168:171], v[200:203], v[84:87]
	v_mfma_f32_16x16x32_bf16 v[92:95], v[172:175], v[200:203], v[92:95]
	ds_read_b128 v[200:203], v246 offset:21504
	s_waitcnt lgkmcnt(3)
	v_mfma_f32_16x16x32_bf16 v[96:99], v[160:163], v[204:207], v[96:99]
	v_mfma_f32_16x16x32_bf16 v[104:107], v[164:167], v[204:207], v[104:107]
	v_mfma_f32_16x16x32_bf16 v[64:67], v[168:171], v[204:207], v[64:67]
	v_mfma_f32_16x16x32_bf16 v[72:75], v[172:175], v[204:207], v[72:75]
	ds_read_b128 v[204:207], v246 offset:22528
	s_waitcnt lgkmcnt(3)
	v_mfma_f32_16x16x32_bf16 v[100:103], v[160:163], v[242:245], v[100:103]
	v_mfma_f32_16x16x32_bf16 v[108:111], v[164:167], v[242:245], v[108:111]
	v_mfma_f32_16x16x32_bf16 v[68:71], v[168:171], v[242:245], v[68:71]
	v_mfma_f32_16x16x32_bf16 v[76:79], v[172:175], v[242:245], v[76:79]
	ds_read_b128 v[242:245], v246 offset:23552
	s_waitcnt lgkmcnt(3)
	v_mfma_f32_16x16x32_bf16 v[48:51], v[160:163], v[196:199], v[48:51]
	v_mfma_f32_16x16x32_bf16 v[56:59], v[164:167], v[196:199], v[56:59]
	v_mfma_f32_16x16x32_bf16 v[16:19], v[168:171], v[196:199], v[16:19]
	v_mfma_f32_16x16x32_bf16 v[24:27], v[172:175], v[196:199], v[24:27]
	s_waitcnt lgkmcnt(2)
	v_mfma_f32_16x16x32_bf16 v[52:55], v[160:163], v[200:203], v[52:55]
	v_mfma_f32_16x16x32_bf16 v[60:63], v[164:167], v[200:203], v[60:63]
	v_mfma_f32_16x16x32_bf16 v[20:23], v[168:171], v[200:203], v[20:23]
	v_mfma_f32_16x16x32_bf16 v[28:31], v[172:175], v[200:203], v[28:31]
	s_waitcnt lgkmcnt(1)
	v_mfma_f32_16x16x32_bf16 v[32:35], v[160:163], v[204:207], v[32:35]
	v_mfma_f32_16x16x32_bf16 v[40:43], v[164:167], v[204:207], v[40:43]
	v_mfma_f32_16x16x32_bf16 v[0:3], v[168:171], v[204:207], v[0:3]
	v_mfma_f32_16x16x32_bf16 v[8:11], v[172:175], v[204:207], v[8:11]
	s_waitcnt lgkmcnt(0)
	v_mfma_f32_16x16x32_bf16 v[36:39], v[160:163], v[242:245], v[36:39]
	v_mfma_f32_16x16x32_bf16 v[44:47], v[164:167], v[242:245], v[44:47]
	v_mfma_f32_16x16x32_bf16 v[4:7], v[168:171], v[242:245], v[4:7]
	v_mfma_f32_16x16x32_bf16 v[12:15], v[172:175], v[242:245], v[12:15]
	global_load_dwordx4 v[160:163], v[248:249], off
	global_load_dwordx4 v[164:167], v[248:249], off offset:256
	global_load_dwordx4 v[168:171], v[250:251], off
	global_load_dwordx4 v[172:175], v[250:251], off offset:256
	s_waitcnt vmcnt(10)
	s_barrier
	s_add_i32 s1, s1, 6
	s_cmp_lt_u32 s1, 30
	s_cbranch_scc1 .Lg16_gu_k
	ds_read_b128 v[196:199], v246 offset:0
	ds_read_b128 v[200:203], v246 offset:1024
	ds_read_b128 v[204:207], v246 offset:2048
	ds_read_b128 v[242:245], v246 offset:3072
	s_waitcnt lgkmcnt(3)
	v_mfma_f32_16x16x32_bf16 v[112:115], v[128:131], v[196:199], v[112:115]
	v_mfma_f32_16x16x32_bf16 v[120:123], v[132:135], v[196:199], v[120:123]
	v_mfma_f32_16x16x32_bf16 v[80:83], v[136:139], v[196:199], v[80:83]
	v_mfma_f32_16x16x32_bf16 v[88:91], v[140:143], v[196:199], v[88:91]
	ds_read_b128 v[196:199], v246 offset:4096
	s_waitcnt lgkmcnt(3)
	v_mfma_f32_16x16x32_bf16 v[116:119], v[128:131], v[200:203], v[116:119]
	v_mfma_f32_16x16x32_bf16 v[124:127], v[132:135], v[200:203], v[124:127]
	v_mfma_f32_16x16x32_bf16 v[84:87], v[136:139], v[200:203], v[84:87]
	v_mfma_f32_16x16x32_bf16 v[92:95], v[140:143], v[200:203], v[92:95]
	ds_read_b128 v[200:203], v246 offset:5120
	s_waitcnt lgkmcnt(3)
	v_mfma_f32_16x16x32_bf16 v[96:99], v[128:131], v[204:207], v[96:99]
	v_mfma_f32_16x16x32_bf16 v[104:107], v[132:135], v[204:207], v[104:107]
	v_mfma_f32_16x16x32_bf16 v[64:67], v[136:139], v[204:207], v[64:67]
	v_mfma_f32_16x16x32_bf16 v[72:75], v[140:143], v[204:207], v[72:75]
	ds_read_b128 v[204:207], v246 offset:6144
	s_waitcnt lgkmcnt(3)
	v_mfma_f32_16x16x32_bf16 v[100:103], v[128:131], v[242:245], v[100:103]
	v_mfma_f32_16x16x32_bf16 v[108:111], v[132:135], v[242:245], v[108:111]
	v_mfma_f32_16x16x32_bf16 v[68:71], v[136:139], v[242:245], v[68:71]
	v_mfma_f32_16x16x32_bf16 v[76:79], v[140:143], v[242:245], v[76:79]
	ds_read_b128 v[242:245], v246 offset:7168
	s_waitcnt lgkmcnt(3)
	v_mfma_f32_16x16x32_bf16 v[48:51], v[128:131], v[196:199], v[48:51]
	v_mfma_f32_16x16x32_bf16 v[56:59], v[132:135], v[196:199], v[56:59]
	v_mfma_f32_16x16x32_bf16 v[16:19], v[136:139], v[196:199], v[16:19]
	v_mfma_f32_16x16x32_bf16 v[24:27], v[140:143], v[196:199], v[24:27]
	s_waitcnt lgkmcnt(2)
	v_mfma_f32_16x16x32_bf16 v[52:55], v[128:131], v[200:203], v[52:55]
	v_mfma_f32_16x16x32_bf16 v[60:63], v[132:135], v[200:203], v[60:63]
	v_mfma_f32_16x16x32_bf16 v[20:23], v[136:139], v[200:203], v[20:23]
	v_mfma_f32_16x16x32_bf16 v[28:31], v[140:143], v[200:203], v[28:31]
	s_waitcnt lgkmcnt(1)
	v_mfma_f32_16x16x32_bf16 v[32:35], v[128:131], v[204:207], v[32:35]
	v_mfma_f32_16x16x32_bf16 v[40:43], v[132:135], v[204:207], v[40:43]
	v_mfma_f32_16x16x32_bf16 v[0:3], v[136:139], v[204:207], v[0:3]
	v_mfma_f32_16x16x32_bf16 v[8:11], v[140:143], v[204:207], v[8:11]
	s_waitcnt lgkmcnt(0)
	v_mfma_f32_16x16x32_bf16 v[36:39], v[128:131], v[242:245], v[36:39]
	v_mfma_f32_16x16x32_bf16 v[44:47], v[132:135], v[242:245], v[44:47]
	v_mfma_f32_16x16x32_bf16 v[4:7], v[136:139], v[242:245], v[4:7]
	v_mfma_f32_16x16x32_bf16 v[12:15], v[140:143], v[242:245], v[12:15]
	s_waitcnt vmcnt(4)
	s_barrier
	ds_read_b128 v[196:199], v246 offset:8192
	ds_read_b128 v[200:203], v246 offset:9216
	ds_read_b128 v[204:207], v246 offset:10240
	ds_read_b128 v[242:245], v246 offset:11264
	s_waitcnt lgkmcnt(3)
	v_mfma_f32_16x16x32_bf16 v[112:115], v[144:147], v[196:199], v[112:115]
	v_mfma_f32_16x16x32_bf16 v[120:123], v[148:151], v[196:199], v[120:123]
	v_mfma_f32_16x16x32_bf16 v[80:83], v[152:155], v[196:199], v[80:83]
	v_mfma_f32_16x16x32_bf16 v[88:91], v[156:159], v[196:199], v[88:91]
	ds_read_b128 v[196:199], v246 offset:12288
	s_waitcnt lgkmcnt(3)
	v_mfma_f32_16x16x32_bf16 v[116:119], v[144:147], v[200:203], v[116:119]
	v_mfma_f32_16x16x32_bf16 v[124:127], v[148:151], v[200:203], v[124:127]
	v_mfma_f32_16x16x32_bf16 v[84:87], v[152:155], v[200:203], v[84:87]
	v_mfma_f32_16x16x32_bf16 v[92:95], v[156:159], v[200:203], v[92:95]
	ds_read_b128 v[200:203], v246 offset:13312
	s_waitcnt lgkmcnt(3)
	v_mfma_f32_16x16x32_bf16 v[96:99], v[144:147], v[204:207], v[96:99]
	v_mfma_f32_16x16x32_bf16 v[104:107], v[148:151], v[204:207], v[104:107]
	v_mfma_f32_16x16x32_bf16 v[64:67], v[152:155], v[204:207], v[64:67]
	v_mfma_f32_16x16x32_bf16 v[72:75], v[156:159], v[204:207], v[72:75]
	ds_read_b128 v[204:207], v246 offset:14336
	s_waitcnt lgkmcnt(3)
	v_mfma_f32_16x16x32_bf16 v[100:103], v[144:147], v[242:245], v[100:103]
	v_mfma_f32_16x16x32_bf16 v[108:111], v[148:151], v[242:245], v[108:111]
	v_mfma_f32_16x16x32_bf16 v[68:71], v[152:155], v[242:245], v[68:71]
	v_mfma_f32_16x16x32_bf16 v[76:79], v[156:159], v[242:245], v[76:79]
	ds_read_b128 v[242:245], v246 offset:15360
	v_permlane16_swap_b32_e32 v112, v116
	v_permlane16_swap_b32_e32 v113, v117
	v_permlane16_swap_b32_e32 v114, v118
	v_permlane16_swap_b32_e32 v115, v119
	v_permlane16_swap_b32_e32 v120, v124
	v_permlane16_swap_b32_e32 v121, v125
	v_permlane16_swap_b32_e32 v122, v126
	v_permlane16_swap_b32_e32 v123, v127
	v_permlane16_swap_b32_e32 v80, v84
	v_permlane16_swap_b32_e32 v81, v85
	v_permlane16_swap_b32_e32 v82, v86
	v_permlane16_swap_b32_e32 v83, v87
	v_permlane16_swap_b32_e32 v88, v92
	v_permlane16_swap_b32_e32 v89, v93
	v_permlane16_swap_b32_e32 v90, v94
	v_permlane16_swap_b32_e32 v91, v95
	v_permlane32_swap_b32_e32 v112, v116
	v_permlane32_swap_b32_e32 v113, v117
	v_permlane32_swap_b32_e32 v114, v118
	v_permlane32_swap_b32_e32 v115, v119
	v_permlane32_swap_b32_e32 v120, v124
	v_permlane32_swap_b32_e32 v121, v125
	v_permlane32_swap_b32_e32 v122, v126
	v_permlane32_swap_b32_e32 v123, v127
	v_permlane32_swap_b32_e32 v80, v84
	v_permlane32_swap_b32_e32 v81, v85
	v_permlane32_swap_b32_e32 v82, v86
	v_permlane32_swap_b32_e32 v83, v87
	v_permlane32_swap_b32_e32 v88, v92
	v_permlane32_swap_b32_e32 v89, v93
	v_permlane32_swap_b32_e32 v90, v94
	v_permlane32_swap_b32_e32 v91, v95
	s_waitcnt lgkmcnt(3)
	v_mfma_f32_16x16x32_bf16 v[48:51], v[144:147], v[196:199], v[48:51]
	v_mfma_f32_16x16x32_bf16 v[56:59], v[148:151], v[196:199], v[56:59]
	v_mfma_f32_16x16x32_bf16 v[16:19], v[152:155], v[196:199], v[16:19]
	v_mfma_f32_16x16x32_bf16 v[24:27], v[156:159], v[196:199], v[24:27]
	s_waitcnt lgkmcnt(2)
	v_mfma_f32_16x16x32_bf16 v[52:55], v[144:147], v[200:203], v[52:55]
	v_mfma_f32_16x16x32_bf16 v[60:63], v[148:151], v[200:203], v[60:63]
	v_mfma_f32_16x16x32_bf16 v[20:23], v[152:155], v[200:203], v[20:23]
	v_mfma_f32_16x16x32_bf16 v[28:31], v[156:159], v[200:203], v[28:31]
	v_permlane16_swap_b32_e32 v96, v100
	v_permlane16_swap_b32_e32 v97, v101
	v_permlane16_swap_b32_e32 v98, v102
	v_permlane16_swap_b32_e32 v99, v103
	v_permlane16_swap_b32_e32 v104, v108
	v_permlane16_swap_b32_e32 v105, v109
	v_permlane16_swap_b32_e32 v106, v110
	v_permlane16_swap_b32_e32 v107, v111
	v_permlane16_swap_b32_e32 v64, v68
	v_permlane16_swap_b32_e32 v65, v69
	v_permlane16_swap_b32_e32 v66, v70
	v_permlane16_swap_b32_e32 v67, v71
	v_permlane16_swap_b32_e32 v72, v76
	v_permlane16_swap_b32_e32 v73, v77
	v_permlane16_swap_b32_e32 v74, v78
	v_permlane16_swap_b32_e32 v75, v79
	v_permlane32_swap_b32_e32 v96, v100
	v_permlane32_swap_b32_e32 v97, v101
	v_permlane32_swap_b32_e32 v98, v102
	v_permlane32_swap_b32_e32 v99, v103
	v_permlane32_swap_b32_e32 v104, v108
	v_permlane32_swap_b32_e32 v105, v109
	v_permlane32_swap_b32_e32 v106, v110
	v_permlane32_swap_b32_e32 v107, v111
	v_permlane32_swap_b32_e32 v64, v68
	v_permlane32_swap_b32_e32 v65, v69
	v_permlane32_swap_b32_e32 v66, v70
	v_permlane32_swap_b32_e32 v67, v71
	v_permlane32_swap_b32_e32 v72, v76
	v_permlane32_swap_b32_e32 v73, v77
	v_permlane32_swap_b32_e32 v74, v78
	v_permlane32_swap_b32_e32 v75, v79
	s_waitcnt lgkmcnt(1)
	v_mfma_f32_16x16x32_bf16 v[32:35], v[144:147], v[204:207], v[32:35]
	v_mfma_f32_16x16x32_bf16 v[40:43], v[148:151], v[204:207], v[40:43]
	v_mfma_f32_16x16x32_bf16 v[0:3], v[152:155], v[204:207], v[0:3]
	v_mfma_f32_16x16x32_bf16 v[8:11], v[156:159], v[204:207], v[8:11]
	s_waitcnt lgkmcnt(0)
	v_mfma_f32_16x16x32_bf16 v[36:39], v[144:147], v[242:245], v[36:39]
	v_mfma_f32_16x16x32_bf16 v[44:47], v[148:151], v[242:245], v[44:47]
	v_mfma_f32_16x16x32_bf16 v[4:7], v[152:155], v[242:245], v[4:7]
	v_mfma_f32_16x16x32_bf16 v[12:15], v[156:159], v[242:245], v[12:15]
	v_permlane16_swap_b32_e32 v48, v52
	v_permlane16_swap_b32_e32 v49, v53
	v_permlane16_swap_b32_e32 v50, v54
	v_permlane16_swap_b32_e32 v51, v55
	v_permlane16_swap_b32_e32 v56, v60
	v_permlane16_swap_b32_e32 v57, v61
	v_permlane16_swap_b32_e32 v58, v62
	v_permlane16_swap_b32_e32 v59, v63
	v_permlane16_swap_b32_e32 v16, v20
	v_permlane16_swap_b32_e32 v17, v21
	v_permlane16_swap_b32_e32 v18, v22
	v_permlane16_swap_b32_e32 v19, v23
	v_permlane16_swap_b32_e32 v24, v28
	v_permlane16_swap_b32_e32 v25, v29
	v_permlane16_swap_b32_e32 v26, v30
	v_permlane16_swap_b32_e32 v27, v31
	v_permlane32_swap_b32_e32 v48, v52
	v_permlane32_swap_b32_e32 v49, v53
	v_permlane32_swap_b32_e32 v50, v54
	v_permlane32_swap_b32_e32 v51, v55
	v_permlane32_swap_b32_e32 v56, v60
	v_permlane32_swap_b32_e32 v57, v61
	v_permlane32_swap_b32_e32 v58, v62
	v_permlane32_swap_b32_e32 v59, v63
	v_permlane32_swap_b32_e32 v16, v20
	v_permlane32_swap_b32_e32 v17, v21
	v_permlane32_swap_b32_e32 v18, v22
	v_permlane32_swap_b32_e32 v19, v23
	v_permlane32_swap_b32_e32 v24, v28
	v_permlane32_swap_b32_e32 v25, v29
	v_permlane32_swap_b32_e32 v26, v30
	v_permlane32_swap_b32_e32 v27, v31
	s_barrier
	s_nop 7
	v_permlane16_swap_b32_e32 v32, v36
	v_permlane16_swap_b32_e32 v33, v37
	v_permlane16_swap_b32_e32 v34, v38
	v_permlane16_swap_b32_e32 v35, v39
	v_permlane16_swap_b32_e32 v40, v44
	v_permlane16_swap_b32_e32 v41, v45
	v_permlane16_swap_b32_e32 v42, v46
	v_permlane16_swap_b32_e32 v43, v47
	v_permlane16_swap_b32_e32 v0, v4
	v_permlane16_swap_b32_e32 v1, v5
	v_permlane16_swap_b32_e32 v2, v6
	v_permlane16_swap_b32_e32 v3, v7
	v_permlane16_swap_b32_e32 v8, v12
	v_permlane16_swap_b32_e32 v9, v13
	v_permlane16_swap_b32_e32 v10, v14
	v_permlane16_swap_b32_e32 v11, v15
	v_permlane32_swap_b32_e32 v32, v36
	v_permlane32_swap_b32_e32 v33, v37
	v_permlane32_swap_b32_e32 v34, v38
	v_permlane32_swap_b32_e32 v35, v39
	v_permlane32_swap_b32_e32 v40, v44
	v_permlane32_swap_b32_e32 v41, v45
	v_permlane32_swap_b32_e32 v42, v46
	v_permlane32_swap_b32_e32 v43, v47
	v_permlane32_swap_b32_e32 v0, v4
	v_permlane32_swap_b32_e32 v1, v5
	v_permlane32_swap_b32_e32 v2, v6
	v_permlane32_swap_b32_e32 v3, v7
	v_permlane32_swap_b32_e32 v8, v12
	v_permlane32_swap_b32_e32 v9, v13
	v_permlane32_swap_b32_e32 v10, v14
	v_permlane32_swap_b32_e32 v11, v15
	s_waitcnt vmcnt(0)
	s_waitcnt vmcnt(0)
	v_mul_f32_e32 v133, 0xbfb8aa3b, v112
	v_exp_f32_e32 v133, v133
	s_movk_i32 s1, 0x2400
	v_mul_lo_u32 v128, v238, s1
	v_lshl_or_b32 v131, s0, 6, v181
	v_add_f32_e32 v133, 1.0, v133
	v_lshl_or_b32 v132, v239, 1, v128
	v_and_b32_e32 v129, 0xffffffc0, v237
	v_lshl_or_b32 v128, v181, 1, v128
	v_rcp_f32_e32 v135, v133
	s_nop 0
	v_mul_f32_e32 v112, v112, v135
	v_mul_f32_e32 v96, v96, v112
	v_cvt_pk_bf16_f32 v112, v96, s0
	s_movk_i32 s0, 0x240
	v_mad_u32_u24 v96, v183, s0, v132
	ds_write_b16 v96, v112
	v_mul_f32_e32 v112, 0xbfb8aa3b, v113
	v_exp_f32_e32 v112, v112
	v_lshl_add_u32 v130, s7, 8, v129
	v_lshrrev_b32_e32 v129, 2, v240
	v_mad_u32_u24 v128, v129, s42, v128
	v_add_f32_e32 v112, 1.0, v112
	v_rcp_f32_e32 v133, v112
	s_nop 0
	v_mul_f32_e32 v112, v113, v133
	v_mul_f32_e32 v97, v97, v112
	v_cvt_pk_bf16_f32 v97, v97, s0
	ds_write_b16 v96, v97 offset:144
	v_mul_f32_e32 v97, 0xbfb8aa3b, v114
	v_exp_f32_e32 v97, v97
	s_nop 0
	v_add_f32_e32 v97, 1.0, v97
	v_rcp_f32_e32 v113, v97
	s_nop 0
	v_mul_f32_e32 v97, v114, v113
	v_mul_f32_e32 v97, v98, v97
	v_cvt_pk_bf16_f32 v97, v97, s0
	ds_write_b16 v96, v97 offset:288
	v_mul_f32_e32 v97, 0xbfb8aa3b, v115
	v_exp_f32_e32 v97, v97
	s_nop 0
	v_add_f32_e32 v97, 1.0, v97
	v_rcp_f32_e32 v112, v97
	s_nop 0
	v_mul_f32_e32 v97, v115, v112
	v_mul_f32_e32 v97, v99, v97
	v_cvt_pk_bf16_f32 v97, v97, s0
	ds_write_b16 v96, v97 offset:432
	v_mul_f32_e32 v97, 0xbfb8aa3b, v116
	v_exp_f32_e32 v97, v97
	s_nop 0
	v_add_f32_e32 v97, 1.0, v97
	v_rcp_f32_e32 v99, v97
	s_nop 0
	v_mul_f32_e32 v97, v116, v99
	v_mul_f32_e32 v97, v100, v97
	v_cvt_pk_bf16_f32 v97, v97, s0
	ds_write_b16 v96, v97 offset:1152
	v_mul_f32_e32 v97, 0xbfb8aa3b, v117
	v_exp_f32_e32 v97, v97
	s_nop 0
	v_add_f32_e32 v97, 1.0, v97
	v_rcp_f32_e32 v99, v97
	s_nop 0
	v_mul_f32_e32 v97, v117, v99
	v_mul_f32_e32 v97, v101, v97
	v_cvt_pk_bf16_f32 v97, v97, s0
	ds_write_b16 v96, v97 offset:1296
	v_mul_f32_e32 v97, 0xbfb8aa3b, v118
	v_exp_f32_e32 v97, v97
	s_nop 0
	v_add_f32_e32 v97, 1.0, v97
	v_rcp_f32_e32 v99, v97
	s_nop 0
	v_mul_f32_e32 v97, v118, v99
	v_mul_f32_e32 v97, v102, v97
	v_cvt_pk_bf16_f32 v97, v97, s0
	ds_write_b16 v96, v97 offset:1440
	v_mul_f32_e32 v97, 0xbfb8aa3b, v119
	v_exp_f32_e32 v97, v97
	s_nop 0
	v_add_f32_e32 v97, 1.0, v97
	v_rcp_f32_e32 v99, v97
	s_nop 0
	v_mul_f32_e32 v97, v119, v99
	v_mul_f32_e32 v97, v103, v97
	v_cvt_pk_bf16_f32 v97, v97, s0
	ds_write_b16 v96, v97 offset:1584
	v_mul_f32_e32 v97, 0xbfb8aa3b, v120
	v_exp_f32_e32 v97, v97
	s_nop 0
	v_add_f32_e32 v97, 1.0, v97
	v_rcp_f32_e32 v99, v97
	s_nop 0
	v_mul_f32_e32 v97, v120, v99
	v_mul_f32_e32 v97, v104, v97
	v_cvt_pk_bf16_f32 v97, v97, s0
	ds_write_b16 v96, v97 offset:2304
	v_mul_f32_e32 v97, 0xbfb8aa3b, v121
	v_exp_f32_e32 v97, v97
	s_nop 0
	v_add_f32_e32 v97, 1.0, v97
	v_rcp_f32_e32 v99, v97
	s_nop 0
	v_mul_f32_e32 v97, v121, v99
	v_mul_f32_e32 v97, v105, v97
	v_cvt_pk_bf16_f32 v97, v97, s0
	ds_write_b16 v96, v97 offset:2448
	v_mul_f32_e32 v97, 0xbfb8aa3b, v122
	v_exp_f32_e32 v97, v97
	s_nop 0
	v_add_f32_e32 v97, 1.0, v97
	v_rcp_f32_e32 v99, v97
	s_nop 0
	v_mul_f32_e32 v97, v122, v99
	v_mul_f32_e32 v97, v106, v97
	v_cvt_pk_bf16_f32 v97, v97, s0
	ds_write_b16 v96, v97 offset:2592
	v_mul_f32_e32 v97, 0xbfb8aa3b, v123
	v_exp_f32_e32 v97, v97
	s_nop 0
	v_add_f32_e32 v97, 1.0, v97
	v_rcp_f32_e32 v99, v97
	s_nop 0
	v_mul_f32_e32 v97, v123, v99
	v_mul_f32_e32 v97, v107, v97
	v_cvt_pk_bf16_f32 v97, v97, s0
	ds_write_b16 v96, v97 offset:2736
	v_mul_f32_e32 v97, 0xbfb8aa3b, v124
	v_exp_f32_e32 v97, v97
	s_nop 0
	v_add_f32_e32 v97, 1.0, v97
	v_rcp_f32_e32 v99, v97
	s_nop 0
	v_mul_f32_e32 v97, v124, v99
	v_mul_f32_e32 v97, v108, v97
	v_cvt_pk_bf16_f32 v97, v97, s0
	ds_write_b16 v96, v97 offset:3456
	v_mul_f32_e32 v97, 0xbfb8aa3b, v125
	v_exp_f32_e32 v97, v97
	s_nop 0
	v_add_f32_e32 v97, 1.0, v97
	v_rcp_f32_e32 v99, v97
	s_nop 0
	v_mul_f32_e32 v97, v125, v99
	v_mul_f32_e32 v97, v109, v97
	v_cvt_pk_bf16_f32 v97, v97, s0
	ds_write_b16 v96, v97 offset:3600
	v_mul_f32_e32 v97, 0xbfb8aa3b, v126
	v_exp_f32_e32 v97, v97
	s_nop 0
	v_add_f32_e32 v97, 1.0, v97
	v_rcp_f32_e32 v99, v97
	s_nop 0
	v_mul_f32_e32 v97, v126, v99
	v_mul_f32_e32 v97, v110, v97
	v_cvt_pk_bf16_f32 v97, v97, s0
	ds_write_b16 v96, v97 offset:3744
	v_mul_f32_e32 v97, 0xbfb8aa3b, v127
	v_exp_f32_e32 v97, v97
	s_nop 0
	v_add_f32_e32 v97, 1.0, v97
	v_rcp_f32_e32 v99, v97
	s_nop 0
	v_mul_f32_e32 v97, v127, v99
	v_mul_f32_e32 v97, v111, v97
	v_cvt_pk_bf16_f32 v97, v97, s0
	ds_write_b16 v96, v97 offset:3888
	v_mul_f32_e32 v97, 0xbfb8aa3b, v80
	v_exp_f32_e32 v97, v97
	s_nop 0
	v_add_f32_e32 v97, 1.0, v97
	v_rcp_f32_e32 v99, v97
	s_nop 0
	v_mul_f32_e32 v80, v80, v99
	v_mul_f32_e32 v64, v64, v80
	v_cvt_pk_bf16_f32 v64, v64, s0
	ds_write_b16 v96, v64 offset:4608
	v_mul_f32_e32 v64, 0xbfb8aa3b, v81
	v_exp_f32_e32 v64, v64
	s_nop 0
	v_add_f32_e32 v64, 1.0, v64
	v_rcp_f32_e32 v97, v64
	s_nop 0
	v_mul_f32_e32 v64, v81, v97
	v_mul_f32_e32 v64, v65, v64
	v_cvt_pk_bf16_f32 v64, v64, s0
	ds_write_b16 v96, v64 offset:4752
	v_mul_f32_e32 v64, 0xbfb8aa3b, v82
	v_exp_f32_e32 v64, v64
	s_nop 0
	v_add_f32_e32 v64, 1.0, v64
	v_rcp_f32_e32 v80, v64
	s_nop 0
	v_mul_f32_e32 v64, v82, v80
	v_mul_f32_e32 v64, v66, v64
	v_cvt_pk_bf16_f32 v64, v64, s0
	ds_write_b16 v96, v64 offset:4896
	v_mul_f32_e32 v64, 0xbfb8aa3b, v83
	v_exp_f32_e32 v64, v64
	s_nop 0
	v_add_f32_e32 v64, 1.0, v64
	v_rcp_f32_e32 v66, v64
	s_nop 0
	v_mul_f32_e32 v64, v83, v66
	v_mul_f32_e32 v64, v67, v64
	v_cvt_pk_bf16_f32 v64, v64, s0
	ds_write_b16 v96, v64 offset:5040
	v_mul_f32_e32 v64, 0xbfb8aa3b, v84
	v_exp_f32_e32 v64, v64
	s_nop 0
	v_add_f32_e32 v64, 1.0, v64
	v_rcp_f32_e32 v66, v64
	s_nop 0
	v_mul_f32_e32 v64, v84, v66
	v_mul_f32_e32 v64, v68, v64
	v_cvt_pk_bf16_f32 v64, v64, s0
	ds_write_b16 v96, v64 offset:5760
	v_mul_f32_e32 v64, 0xbfb8aa3b, v85
	v_exp_f32_e32 v64, v64
	s_nop 0
	v_add_f32_e32 v64, 1.0, v64
	v_rcp_f32_e32 v66, v64
	s_nop 0
	v_mul_f32_e32 v64, v85, v66
	v_mul_f32_e32 v64, v69, v64
	v_cvt_pk_bf16_f32 v64, v64, s0
	ds_write_b16 v96, v64 offset:5904
	v_mul_f32_e32 v64, 0xbfb8aa3b, v86
	v_exp_f32_e32 v64, v64
	s_nop 0
	v_add_f32_e32 v64, 1.0, v64
	v_rcp_f32_e32 v66, v64
	s_nop 0
	v_mul_f32_e32 v64, v86, v66
	v_mul_f32_e32 v64, v70, v64
	v_cvt_pk_bf16_f32 v64, v64, s0
	ds_write_b16 v96, v64 offset:6048
	v_mul_f32_e32 v64, 0xbfb8aa3b, v87
	v_exp_f32_e32 v64, v64
	s_nop 0
	v_add_f32_e32 v64, 1.0, v64
	v_rcp_f32_e32 v66, v64
	s_nop 0
	v_mul_f32_e32 v64, v87, v66
	v_mul_f32_e32 v64, v71, v64
	v_cvt_pk_bf16_f32 v64, v64, s0
	ds_write_b16 v96, v64 offset:6192
	v_mul_f32_e32 v64, 0xbfb8aa3b, v88
	v_exp_f32_e32 v64, v64
	v_ashrrev_i32_e32 v71, 5, v130
	v_or_b32_e32 v70, 1, v71
	v_add_f32_e32 v64, 1.0, v64
	v_rcp_f32_e32 v66, v64
	s_nop 0
	v_mul_f32_e32 v64, v88, v66
	v_mul_f32_e32 v64, v72, v64
	v_cvt_pk_bf16_f32 v64, v64, s0
	ds_write_b16 v96, v64 offset:6912
	v_mul_f32_e32 v64, 0xbfb8aa3b, v89
	v_exp_f32_e32 v64, v64
	s_nop 0
	v_add_f32_e32 v64, 1.0, v64
	v_rcp_f32_e32 v66, v64
	s_nop 0
	v_mul_f32_e32 v64, v89, v66
	v_mul_f32_e32 v64, v73, v64
	v_cvt_pk_bf16_f32 v64, v64, s0
	ds_write_b16 v96, v64 offset:7056
	v_mul_f32_e32 v64, 0xbfb8aa3b, v90
	v_exp_f32_e32 v64, v64
	s_nop 0
	v_add_f32_e32 v64, 1.0, v64
	v_rcp_f32_e32 v66, v64
	s_nop 0
	v_mul_f32_e32 v64, v90, v66
	v_mul_f32_e32 v64, v74, v64
	v_cvt_pk_bf16_f32 v64, v64, s0
	ds_write_b16 v96, v64 offset:7200
	v_mul_f32_e32 v64, 0xbfb8aa3b, v91
	v_exp_f32_e32 v64, v64
	s_nop 0
	v_add_f32_e32 v64, 1.0, v64
	v_rcp_f32_e32 v66, v64
	s_nop 0
	v_mul_f32_e32 v64, v91, v66
	v_mul_f32_e32 v64, v75, v64
	v_cvt_pk_bf16_f32 v64, v64, s0
	ds_write_b16 v96, v64 offset:7344
	v_mul_f32_e32 v64, 0xbfb8aa3b, v92
	v_exp_f32_e32 v64, v64
	s_nop 0
	v_add_f32_e32 v64, 1.0, v64
	v_rcp_f32_e32 v66, v64
	s_nop 0
	v_mul_f32_e32 v64, v92, v66
	v_mul_f32_e32 v64, v76, v64
	v_cvt_pk_bf16_f32 v64, v64, s0
	ds_write_b16 v96, v64 offset:8064
	v_mul_f32_e32 v64, 0xbfb8aa3b, v93
	v_exp_f32_e32 v64, v64
	s_nop 0
	v_add_f32_e32 v64, 1.0, v64
	v_rcp_f32_e32 v66, v64
	s_nop 0
	v_mul_f32_e32 v64, v93, v66
	v_mul_f32_e32 v64, v77, v64
	v_cvt_pk_bf16_f32 v64, v64, s0
	ds_write_b16 v96, v64 offset:8208
	v_mul_f32_e32 v64, 0xbfb8aa3b, v94
	v_exp_f32_e32 v64, v64
	s_nop 0
	v_add_f32_e32 v64, 1.0, v64
	v_rcp_f32_e32 v66, v64
	s_nop 0
	v_mul_f32_e32 v64, v94, v66
	v_mul_f32_e32 v64, v78, v64
	v_cvt_pk_bf16_f32 v64, v64, s0
	ds_write_b16 v96, v64 offset:8352
	v_mul_f32_e32 v64, 0xbfb8aa3b, v95
	v_exp_f32_e32 v64, v64
	s_nop 0
	v_add_f32_e32 v64, 1.0, v64
	v_rcp_f32_e32 v66, v64
	s_nop 0
	v_mul_f32_e32 v64, v95, v66
	v_mul_f32_e32 v64, v79, v64
	v_cvt_pk_bf16_f32 v64, v64, s0
	ds_write_b16 v96, v64 offset:8496
	v_ashrrev_i32_e32 v68, 4, v131
	s_waitcnt lgkmcnt(0)
	v_ashrrev_i32_e32 v69, 31, v68
	ds_read_b128 v[72:75], v128
	v_mad_i64_i32 v[64:65], s[0:1], v71, s23, v[68:69]
	v_lshlrev_b64 v[64:65], 10, v[64:65]
	v_lshlrev_b32_e32 v66, 6, v181
	v_lshl_add_u64 v[64:65], s[66:67], 0, v[64:65]
	v_and_b32_e32 v176, 0x200, v66
	v_lshl_add_u64 v[76:77], v[64:65], 0, v[176:177]
	v_lshlrev_b32_e32 v66, 4, v129
	v_mov_b32_e32 v67, v177
	v_lshl_add_u64 v[64:65], v[76:77], 0, v[66:67]
	s_waitcnt lgkmcnt(0)
	global_store_dwordx4 v[64:65], v[72:75], off
	ds_read_b128 v[72:75], v128 offset:2304
	v_or_b32_e32 v64, 0x100, v66
	v_mov_b32_e32 v65, v177
	v_lshl_add_u64 v[76:77], v[76:77], 0, v[64:65]
	s_waitcnt lgkmcnt(0)
	global_store_dwordx4 v[76:77], v[72:75], off
	ds_read_b128 v[72:75], v128 offset:4608
	v_mad_i64_i32 v[76:77], s[0:1], v70, s23, v[68:69]
	v_lshlrev_b64 v[76:77], 10, v[76:77]
	v_lshl_add_u64 v[76:77], s[66:67], 0, v[76:77]
	v_lshl_add_u64 v[76:77], v[76:77], 0, v[176:177]
	v_lshl_add_u64 v[78:79], v[76:77], 0, v[66:67]
	v_mul_f32_e32 v69, 0xbfb8aa3b, v48
	s_waitcnt lgkmcnt(0)
	global_store_dwordx4 v[78:79], v[72:75], off
	ds_read_b128 v[72:75], v128 offset:6912
	v_exp_f32_e32 v69, v69
	v_lshl_add_u64 v[76:77], v[76:77], 0, v[64:65]
	v_add_f32_e32 v69, 1.0, v69
	s_waitcnt lgkmcnt(0)
	global_store_dwordx4 v[76:77], v[72:75], off
	s_waitcnt lgkmcnt(0)
	s_nop 1
	v_rcp_f32_e32 v73, v69
	s_nop 0
	v_mul_f32_e32 v48, v48, v73
	v_mul_f32_e32 v32, v32, v48
	v_cvt_pk_bf16_f32 v32, v32, s0
	ds_write_b16 v96, v32
	v_mul_f32_e32 v32, 0xbfb8aa3b, v49
	v_exp_f32_e32 v32, v32
	s_nop 0
	v_add_f32_e32 v32, 1.0, v32
	v_rcp_f32_e32 v69, v32
	s_nop 0
	v_mul_f32_e32 v32, v49, v69
	v_mul_f32_e32 v32, v33, v32
	v_cvt_pk_bf16_f32 v32, v32, s0
	ds_write_b16 v96, v32 offset:144
	v_mul_f32_e32 v32, 0xbfb8aa3b, v50
	v_exp_f32_e32 v32, v32
	s_nop 0
	v_add_f32_e32 v32, 1.0, v32
	v_rcp_f32_e32 v48, v32
	s_nop 0
	v_mul_f32_e32 v32, v50, v48
	v_mul_f32_e32 v32, v34, v32
	v_cvt_pk_bf16_f32 v32, v32, s0
	ds_write_b16 v96, v32 offset:288
	v_mul_f32_e32 v32, 0xbfb8aa3b, v51
	v_exp_f32_e32 v32, v32
	s_nop 0
	v_add_f32_e32 v32, 1.0, v32
	v_rcp_f32_e32 v34, v32
	s_nop 0
	v_mul_f32_e32 v32, v51, v34
	v_mul_f32_e32 v32, v35, v32
	v_cvt_pk_bf16_f32 v32, v32, s0
	ds_write_b16 v96, v32 offset:432
	v_mul_f32_e32 v32, 0xbfb8aa3b, v52
	v_exp_f32_e32 v32, v32
	s_nop 0
	v_add_f32_e32 v32, 1.0, v32
	v_rcp_f32_e32 v34, v32
	s_nop 0
	v_mul_f32_e32 v32, v52, v34
	v_mul_f32_e32 v32, v36, v32
	v_cvt_pk_bf16_f32 v32, v32, s0
	ds_write_b16 v96, v32 offset:1152
	v_mul_f32_e32 v32, 0xbfb8aa3b, v53
	v_exp_f32_e32 v32, v32
	s_nop 0
	v_add_f32_e32 v32, 1.0, v32
	v_rcp_f32_e32 v34, v32
	s_nop 0
	v_mul_f32_e32 v32, v53, v34
	v_mul_f32_e32 v32, v37, v32
	v_cvt_pk_bf16_f32 v32, v32, s0
	ds_write_b16 v96, v32 offset:1296
	v_mul_f32_e32 v32, 0xbfb8aa3b, v54
	v_exp_f32_e32 v32, v32
	s_nop 0
	v_add_f32_e32 v32, 1.0, v32
	v_rcp_f32_e32 v34, v32
	s_nop 0
	v_mul_f32_e32 v32, v54, v34
	v_mul_f32_e32 v32, v38, v32
	v_cvt_pk_bf16_f32 v32, v32, s0
	ds_write_b16 v96, v32 offset:1440
	v_mul_f32_e32 v32, 0xbfb8aa3b, v55
	v_exp_f32_e32 v32, v32
	s_nop 0
	v_add_f32_e32 v32, 1.0, v32
	v_rcp_f32_e32 v34, v32
	s_nop 0
	v_mul_f32_e32 v32, v55, v34
	v_mul_f32_e32 v32, v39, v32
	v_cvt_pk_bf16_f32 v32, v32, s0
	ds_write_b16 v96, v32 offset:1584
	v_mul_f32_e32 v32, 0xbfb8aa3b, v56
	v_exp_f32_e32 v32, v32
	s_nop 0
	v_add_f32_e32 v32, 1.0, v32
	v_rcp_f32_e32 v34, v32
	s_nop 0
	v_mul_f32_e32 v32, v56, v34
	v_mul_f32_e32 v32, v40, v32
	v_cvt_pk_bf16_f32 v32, v32, s0
	ds_write_b16 v96, v32 offset:2304
	v_mul_f32_e32 v32, 0xbfb8aa3b, v57
	v_exp_f32_e32 v32, v32
	s_nop 0
	v_add_f32_e32 v32, 1.0, v32
	v_rcp_f32_e32 v34, v32
	s_nop 0
	v_mul_f32_e32 v32, v57, v34
	v_mul_f32_e32 v32, v41, v32
	v_cvt_pk_bf16_f32 v32, v32, s0
	ds_write_b16 v96, v32 offset:2448
	v_mul_f32_e32 v32, 0xbfb8aa3b, v58
	v_exp_f32_e32 v32, v32
	s_nop 0
	v_add_f32_e32 v32, 1.0, v32
	v_rcp_f32_e32 v34, v32
	s_nop 0
	v_mul_f32_e32 v32, v58, v34
	v_mul_f32_e32 v32, v42, v32
	v_cvt_pk_bf16_f32 v32, v32, s0
	ds_write_b16 v96, v32 offset:2592
	v_mul_f32_e32 v32, 0xbfb8aa3b, v59
	v_exp_f32_e32 v32, v32
	s_nop 0
	v_add_f32_e32 v32, 1.0, v32
	v_rcp_f32_e32 v34, v32
	s_nop 0
	v_mul_f32_e32 v32, v59, v34
	v_mul_f32_e32 v32, v43, v32
	v_cvt_pk_bf16_f32 v32, v32, s0
	ds_write_b16 v96, v32 offset:2736
	v_mul_f32_e32 v32, 0xbfb8aa3b, v60
	v_exp_f32_e32 v32, v32
	s_nop 0
	v_add_f32_e32 v32, 1.0, v32
	v_rcp_f32_e32 v34, v32
	s_nop 0
	v_mul_f32_e32 v32, v60, v34
	v_mul_f32_e32 v32, v44, v32
	v_cvt_pk_bf16_f32 v32, v32, s0
	ds_write_b16 v96, v32 offset:3456
	v_mul_f32_e32 v32, 0xbfb8aa3b, v61
	v_exp_f32_e32 v32, v32
	s_nop 0
	v_add_f32_e32 v32, 1.0, v32
	v_rcp_f32_e32 v34, v32
	s_nop 0
	v_mul_f32_e32 v32, v61, v34
	v_mul_f32_e32 v32, v45, v32
	v_cvt_pk_bf16_f32 v32, v32, s0
	ds_write_b16 v96, v32 offset:3600
	v_mul_f32_e32 v32, 0xbfb8aa3b, v62
	v_exp_f32_e32 v32, v32
	s_nop 0
	v_add_f32_e32 v32, 1.0, v32
	v_rcp_f32_e32 v34, v32
	s_nop 0
	v_mul_f32_e32 v32, v62, v34
	v_mul_f32_e32 v32, v46, v32
	v_cvt_pk_bf16_f32 v32, v32, s0
	ds_write_b16 v96, v32 offset:3744
	v_mul_f32_e32 v32, 0xbfb8aa3b, v63
	v_exp_f32_e32 v32, v32
	s_nop 0
	v_add_f32_e32 v32, 1.0, v32
	v_rcp_f32_e32 v34, v32
	s_nop 0
	v_mul_f32_e32 v32, v63, v34
	v_mul_f32_e32 v32, v47, v32
	v_cvt_pk_bf16_f32 v32, v32, s0
	ds_write_b16 v96, v32 offset:3888
	v_mul_f32_e32 v32, 0xbfb8aa3b, v16
	v_exp_f32_e32 v32, v32
	s_nop 0
	v_add_f32_e32 v32, 1.0, v32
	v_rcp_f32_e32 v34, v32
	s_nop 0
	v_mul_f32_e32 v16, v16, v34
	v_mul_f32_e32 v0, v0, v16
	v_cvt_pk_bf16_f32 v0, v0, s0
	ds_write_b16 v96, v0 offset:4608
	v_mul_f32_e32 v0, 0xbfb8aa3b, v17
	v_exp_f32_e32 v0, v0
	s_nop 0
	v_add_f32_e32 v0, 1.0, v0
	v_rcp_f32_e32 v32, v0
	s_nop 0
	v_mul_f32_e32 v0, v17, v32
	v_mul_f32_e32 v0, v1, v0
	v_cvt_pk_bf16_f32 v0, v0, s0
	ds_write_b16 v96, v0 offset:4752
	v_mul_f32_e32 v0, 0xbfb8aa3b, v18
	v_exp_f32_e32 v0, v0
	s_nop 0
	v_add_f32_e32 v0, 1.0, v0
	v_rcp_f32_e32 v16, v0
	s_nop 0
	v_mul_f32_e32 v0, v18, v16
	v_mul_f32_e32 v0, v2, v0
	v_cvt_pk_bf16_f32 v0, v0, s0
	ds_write_b16 v96, v0 offset:4896
	v_mul_f32_e32 v0, 0xbfb8aa3b, v19
	v_exp_f32_e32 v0, v0
	s_nop 0
	v_add_f32_e32 v0, 1.0, v0
	v_rcp_f32_e32 v2, v0
	s_nop 0
	v_mul_f32_e32 v0, v19, v2
	v_mul_f32_e32 v0, v3, v0
	v_cvt_pk_bf16_f32 v0, v0, s0
	ds_write_b16 v96, v0 offset:5040
	v_mul_f32_e32 v0, 0xbfb8aa3b, v20
	v_exp_f32_e32 v0, v0
	s_nop 0
	v_add_f32_e32 v0, 1.0, v0
	v_rcp_f32_e32 v2, v0
	s_nop 0
	v_mul_f32_e32 v0, v20, v2
	v_mul_f32_e32 v0, v4, v0
	v_cvt_pk_bf16_f32 v0, v0, s0
	ds_write_b16 v96, v0 offset:5760
	v_mul_f32_e32 v0, 0xbfb8aa3b, v21
	v_exp_f32_e32 v0, v0
	s_nop 0
	v_add_f32_e32 v0, 1.0, v0
	v_rcp_f32_e32 v2, v0
	s_nop 0
	v_mul_f32_e32 v0, v21, v2
	v_mul_f32_e32 v0, v5, v0
	v_cvt_pk_bf16_f32 v0, v0, s0
	ds_write_b16 v96, v0 offset:5904
	v_mul_f32_e32 v0, 0xbfb8aa3b, v22
	v_exp_f32_e32 v0, v0
	s_nop 0
	v_add_f32_e32 v0, 1.0, v0
	v_rcp_f32_e32 v2, v0
	s_nop 0
	v_mul_f32_e32 v0, v22, v2
	v_mul_f32_e32 v0, v6, v0
	v_cvt_pk_bf16_f32 v0, v0, s0
	ds_write_b16 v96, v0 offset:6048
	v_mul_f32_e32 v0, 0xbfb8aa3b, v23
	v_exp_f32_e32 v0, v0
	s_nop 0
	v_add_f32_e32 v0, 1.0, v0
	v_rcp_f32_e32 v2, v0
	s_nop 0
	v_mul_f32_e32 v0, v23, v2
	v_mul_f32_e32 v0, v7, v0
	v_cvt_pk_bf16_f32 v0, v0, s0
	ds_write_b16 v96, v0 offset:6192
	v_mul_f32_e32 v0, 0xbfb8aa3b, v24
	v_exp_f32_e32 v0, v0
	s_nop 0
	v_add_f32_e32 v0, 1.0, v0
	v_rcp_f32_e32 v2, v0
	s_nop 0
	v_mul_f32_e32 v0, v24, v2
	v_mul_f32_e32 v0, v8, v0
	v_cvt_pk_bf16_f32 v0, v0, s0
	ds_write_b16 v96, v0 offset:6912
	v_mul_f32_e32 v0, 0xbfb8aa3b, v25
	v_exp_f32_e32 v0, v0
	s_nop 0
	v_add_f32_e32 v0, 1.0, v0
	v_rcp_f32_e32 v2, v0
	s_nop 0
	v_mul_f32_e32 v0, v25, v2
	v_mul_f32_e32 v0, v9, v0
	v_cvt_pk_bf16_f32 v0, v0, s0
	ds_write_b16 v96, v0 offset:7056
	v_mul_f32_e32 v0, 0xbfb8aa3b, v26
	v_exp_f32_e32 v0, v0
	s_nop 0
	v_add_f32_e32 v0, 1.0, v0
	v_rcp_f32_e32 v2, v0
	s_nop 0
	v_mul_f32_e32 v0, v26, v2
	v_mul_f32_e32 v0, v10, v0
	v_cvt_pk_bf16_f32 v0, v0, s0
	ds_write_b16 v96, v0 offset:7200
	v_mul_f32_e32 v0, 0xbfb8aa3b, v27
	v_exp_f32_e32 v0, v0
	s_nop 0
	v_add_f32_e32 v0, 1.0, v0
	v_rcp_f32_e32 v2, v0
	s_nop 0
	v_mul_f32_e32 v0, v27, v2
	v_mul_f32_e32 v0, v11, v0
	v_cvt_pk_bf16_f32 v0, v0, s0
	ds_write_b16 v96, v0 offset:7344
	v_mul_f32_e32 v0, 0xbfb8aa3b, v28
	v_exp_f32_e32 v0, v0
	s_nop 0
	v_add_f32_e32 v0, 1.0, v0
	v_rcp_f32_e32 v2, v0
	s_nop 0
	v_mul_f32_e32 v0, v28, v2
	v_mul_f32_e32 v0, v12, v0
	v_cvt_pk_bf16_f32 v0, v0, s0
	ds_write_b16 v96, v0 offset:8064
	v_mul_f32_e32 v0, 0xbfb8aa3b, v29
	v_exp_f32_e32 v0, v0
	s_nop 0
	v_add_f32_e32 v0, 1.0, v0
	v_rcp_f32_e32 v2, v0
	s_nop 0
	v_mul_f32_e32 v0, v29, v2
	v_mul_f32_e32 v0, v13, v0
	v_cvt_pk_bf16_f32 v0, v0, s0
	ds_write_b16 v96, v0 offset:8208
	v_mul_f32_e32 v0, 0xbfb8aa3b, v30
	v_exp_f32_e32 v0, v0
	s_nop 0
	v_add_f32_e32 v0, 1.0, v0
	v_rcp_f32_e32 v2, v0
	s_nop 0
	v_mul_f32_e32 v0, v30, v2
	v_mul_f32_e32 v0, v14, v0
	v_cvt_pk_bf16_f32 v0, v0, s0
	ds_write_b16 v96, v0 offset:8352
	v_mul_f32_e32 v0, 0xbfb8aa3b, v31
	v_exp_f32_e32 v0, v0
	s_nop 0
	v_add_f32_e32 v0, 1.0, v0
	v_rcp_f32_e32 v2, v0
	s_nop 0
	v_mul_f32_e32 v0, v31, v2
	v_mul_f32_e32 v0, v15, v0
	v_cvt_pk_bf16_f32 v0, v0, s0
	ds_write_b16 v96, v0 offset:8496
	v_or_b32_e32 v4, 2, v68
	s_waitcnt lgkmcnt(0)
	v_ashrrev_i32_e32 v5, 31, v4
	ds_read_b128 v[0:3], v128
	v_mad_i64_i32 v[6:7], s[0:1], v71, s23, v[4:5]
	v_lshlrev_b64 v[6:7], 10, v[6:7]
	v_lshl_add_u64 v[6:7], s[66:67], 0, v[6:7]
	v_lshl_add_u64 v[6:7], v[6:7], 0, v[176:177]
	v_lshl_add_u64 v[8:9], v[6:7], 0, v[66:67]
	s_waitcnt lgkmcnt(0)
	global_store_dwordx4 v[8:9], v[0:3], off
	ds_read_b128 v[0:3], v128 offset:2304
	v_lshl_add_u64 v[6:7], v[6:7], 0, v[64:65]
	v_mad_i64_i32 v[4:5], s[0:1], v70, s23, v[4:5]
	v_lshlrev_b64 v[4:5], 10, v[4:5]
	s_waitcnt lgkmcnt(0)
	global_store_dwordx4 v[6:7], v[0:3], off
	ds_read_b128 v[0:3], v128 offset:4608
	v_lshl_add_u64 v[4:5], s[66:67], 0, v[4:5]
	v_lshl_add_u64 v[4:5], v[4:5], 0, v[176:177]
	v_lshl_add_u64 v[6:7], v[4:5], 0, v[66:67]
	v_lshl_add_u64 v[4:5], v[4:5], 0, v[64:65]
	s_waitcnt lgkmcnt(0)
	global_store_dwordx4 v[6:7], v[0:3], off
	ds_read_b128 v[0:3], v128 offset:6912
	v_readlane_b32 s0, v254, 11
	s_add_i32 s2, s2, s0
	s_cmp_lt_i32 s2, s3
	s_waitcnt lgkmcnt(0)
	global_store_dwordx4 v[4:5], v[0:3], off
	s_waitcnt lgkmcnt(0)
	s_barrier
	s_cbranch_scc1 .LBB0_1031

.LBB0_1086:
	s_ashr_i32 s6, s2, 31
	s_lshr_b32 s6, s6, 26
	s_add_i32 s6, s2, s6
	s_ashr_i32 s7, s6, 6
	s_lshl_b32 s7, s7, 3
	s_sub_i32 s8, s25, s7
	s_min_i32 s8, s8, 8
	s_abs_i32 s9, s8
	v_cvt_f32_u32_e32 v0, s9
	s_sub_i32 s12, 0, s9
	s_andn2_b32 s6, s6, 63
	s_sub_i32 s10, s2, s6
	v_rcp_iflag_f32_e32 v0, v0
	s_abs_i32 s6, s10
	s_xor_b32 s11, s10, s8
	s_ashr_i32 s11, s11, 31
	v_mul_f32_e32 v0, 0x4f7ffffe, v0
	v_cvt_u32_f32_e32 v0, v0
	v_mov_b32_e32 v181, v179
	v_readfirstlane_b32 s13, v0
	s_mul_i32 s12, s12, s13
	s_mul_hi_u32 s12, s13, s12
	s_add_i32 s13, s13, s12
	s_mul_hi_u32 s12, s6, s13
	s_mul_i32 s13, s12, s9
	s_sub_i32 s6, s6, s13
	s_add_i32 s14, s12, 1
	s_sub_i32 s13, s6, s9
	s_cmp_ge_u32 s6, s9
	s_cselect_b32 s12, s14, s12
	s_cselect_b32 s6, s13, s6
	s_add_i32 s13, s12, 1
	s_cmp_ge_u32 s6, s9
	s_cselect_b32 s6, s13, s12
	s_xor_b32 s6, s6, s11
	s_sub_i32 s6, s6, s11
	s_mul_i32 s8, s8, s6
	s_add_i32 s7, s7, s5
	s_sub_i32 s8, s10, s8
	v_ashrrev_i32_e32 v237, 6, v181
	s_add_i32 s7, s7, s8
	v_lshlrev_b32_e32 v0, 1, v237
	v_bfe_u32 v183, v181, 5, 1
	v_lshl_add_u32 v2, s7, 3, v0
	v_mov_b64_e32 v[0:1], s[66:67]
	v_and_b32_e32 v238, 31, v181
	v_mad_i64_i32 v[0:1], s[8:9], v2, s24, v[0:1]
	v_lshlrev_b32_e32 v176, 9, v183
	v_lshl_add_u64 v[0:1], v[0:1], 0, v[176:177]
	v_lshlrev_b32_e32 v176, 4, v238
	v_ashrrev_i32_e32 v38, 2, v181
	s_mul_i32 s8, s6, 0xb0000
	v_lshl_add_u64 v[184:185], v[0:1], 0, v[176:177]
	s_mul_hi_i32 s9, s6, 0xb0000
	s_add_u32 s8, s3, s8
	v_lshlrev_b32_e32 v0, 5, v38
	s_addc_u32 s9, s4, s9
	v_ashrrev_i32_e32 v1, 31, v0
	v_lshlrev_b32_e32 v2, 4, v181
	v_lshl_add_u64 v[0:1], v[0:1], 1, s[8:9]
	v_and_b32_e32 v176, 48, v2
	v_lshl_add_u64 v[186:187], v[0:1], 0, v[176:177]
	s_movk_i32 s8, 0x2000
	v_add_co_u32_e32 v34, vcc, s8, v186
	v_mul_u32_u24_e32 v36, 40, v238
	s_nop 0
	v_addc_co_u32_e32 v35, vcc, 0, v187, vcc
	v_lshlrev_b32_e32 v37, 4, v183
	v_lshl_add_u32 v240, v36, 1, v37
	v_add_co_u32_e32 v36, vcc, s24, v184
	s_movk_i32 s9, 0x50
	s_nop 0
	v_addc_co_u32_e32 v37, vcc, 0, v185, vcc
	v_and_b32_e32 v239, 63, v181
	v_bfe_u32 v247, v181, 4, 2
	v_lshlrev_b32_e32 v247, 1, v247
	v_mov_b32_e32 v176, 0x78
	v_lshrrev_b32_e32 v247, v247, v176
	v_and_b32_e32 v247, 3, v247
	v_and_b32_e32 v246, 3, v181
	v_xor_b32_e32 v247, v247, v246
	v_lshlrev_b32_e32 v247, 4, v247
	v_and_b32_e32 v188, 0xffffffcf, v186
	v_or_b32_e32 v188, v188, v247
	v_mov_b32_e32 v189, v187
	v_lshrrev_b32_e32 v176, 6, v181
	v_lshlrev_b32_e32 v247, 11, v176
	v_lshlrev_b32_e32 v176, 10, v176
	v_lshl_add_u64 v[188:189], v[188:189], 0, v[176:177]
	v_readfirstlane_b32 vcc_lo, v247
	v_bfe_u32 v247, v181, 4, 1
	v_lshlrev_b32_e32 v176, 9, v183
	v_lshl_add_u32 v176, v247, 8, v176
	v_lshl_add_u64 v[184:185], v[184:185], 0, v[176:177]
	v_mov_b32_e32 v176, s24
	v_lshl_add_u64 v[186:187], v[184:185], 0, v[176:177]
	v_mov_b32_e32 v176, 0x78
	v_bfe_u32 v247, v181, 2, 2
	v_lshlrev_b32_e32 v247, 1, v247
	v_lshrrev_b32_e32 v247, v247, v176
	v_and_b32_e32 v247, 3, v247
	v_bfe_u32 v246, v181, 4, 2
	v_xor_b32_e32 v247, v247, v246
	v_lshlrev_b32_e32 v247, 4, v247
	v_and_b32_e32 v246, 15, v181
	v_lshl_add_u32 v246, v246, 6, v247
	s_mov_b32 s96, 0
	s_mov_b32 m0, vcc_lo
	v_lshl_add_u64 v[248:249], v[188:189], 0, s[96:97]
	global_load_lds_dwordx4 v[248:249], off
	global_load_lds_dwordx4 v[248:249], off offset:1024
	s_mov_b32 s96, 0
	v_lshl_add_u64 v[248:249], v[184:185], 0, s[96:97]
	v_lshl_add_u64 v[250:251], v[186:187], 0, s[96:97]
	global_load_dwordx4 v[128:131], v[248:249], off
	global_load_dwordx4 v[132:135], v[248:249], off offset:256
	global_load_dwordx4 v[136:139], v[250:251], off
	global_load_dwordx4 v[140:143], v[250:251], off offset:256
	s_movk_i32 s96, 0x800
	v_lshl_add_u64 v[248:249], v[184:185], 0, s[96:97]
	v_lshl_add_u64 v[250:251], v[186:187], 0, s[96:97]
	global_load_dwordx4 v[144:147], v[248:249], off
	global_load_dwordx4 v[148:151], v[248:249], off offset:256
	global_load_dwordx4 v[152:155], v[250:251], off
	global_load_dwordx4 v[156:159], v[250:251], off offset:256
	s_movk_i32 s96, 0x2000
	s_add_i32 m0, vcc_lo, 8192
	v_lshl_add_u64 v[248:249], v[188:189], 0, s[96:97]
	global_load_lds_dwordx4 v[248:249], off
	global_load_lds_dwordx4 v[248:249], off offset:1024
	s_movk_i32 s96, 0x1000
	v_lshl_add_u64 v[248:249], v[184:185], 0, s[96:97]
	v_lshl_add_u64 v[250:251], v[186:187], 0, s[96:97]
	global_load_dwordx4 v[160:163], v[248:249], off
	global_load_dwordx4 v[164:167], v[248:249], off offset:256
	global_load_dwordx4 v[168:171], v[250:251], off
	global_load_dwordx4 v[172:175], v[250:251], off offset:256
	v_mov_b32_e32 v0, 0
	v_mov_b32_e32 v1, 0
	v_mov_b32_e32 v2, 0
	v_mov_b32_e32 v3, 0
	v_mov_b32_e32 v4, 0
	v_mov_b32_e32 v5, 0
	v_mov_b32_e32 v6, 0
	v_mov_b32_e32 v7, 0
	v_mov_b32_e32 v8, 0
	v_mov_b32_e32 v9, 0
	v_mov_b32_e32 v10, 0
	v_mov_b32_e32 v11, 0
	v_mov_b32_e32 v12, 0
	v_mov_b32_e32 v13, 0
	v_mov_b32_e32 v14, 0
	v_mov_b32_e32 v15, 0
	v_mov_b32_e32 v16, 0
	v_mov_b32_e32 v17, 0
	v_mov_b32_e32 v18, 0
	v_mov_b32_e32 v19, 0
	v_mov_b32_e32 v20, 0
	v_mov_b32_e32 v21, 0
	v_mov_b32_e32 v22, 0
	v_mov_b32_e32 v23, 0
	v_mov_b32_e32 v24, 0
	v_mov_b32_e32 v25, 0
	v_mov_b32_e32 v26, 0
	v_mov_b32_e32 v27, 0
	v_mov_b32_e32 v28, 0
	v_mov_b32_e32 v29, 0
	v_mov_b32_e32 v30, 0
	v_mov_b32_e32 v31, 0
	v_mov_b32_e32 v32, 0
	v_mov_b32_e32 v33, 0
	v_mov_b32_e32 v34, 0
	v_mov_b32_e32 v35, 0
	v_mov_b32_e32 v36, 0
	v_mov_b32_e32 v37, 0
	v_mov_b32_e32 v38, 0
	v_mov_b32_e32 v39, 0
	v_mov_b32_e32 v40, 0
	v_mov_b32_e32 v41, 0
	v_mov_b32_e32 v42, 0
	v_mov_b32_e32 v43, 0
	v_mov_b32_e32 v44, 0
	v_mov_b32_e32 v45, 0
	v_mov_b32_e32 v46, 0
	v_mov_b32_e32 v47, 0
	v_mov_b32_e32 v48, 0
	v_mov_b32_e32 v49, 0
	v_mov_b32_e32 v50, 0
	v_mov_b32_e32 v51, 0
	v_mov_b32_e32 v52, 0
	v_mov_b32_e32 v53, 0
	v_mov_b32_e32 v54, 0
	v_mov_b32_e32 v55, 0
	v_mov_b32_e32 v56, 0
	v_mov_b32_e32 v57, 0
	v_mov_b32_e32 v58, 0
	v_mov_b32_e32 v59, 0
	v_mov_b32_e32 v60, 0
	v_mov_b32_e32 v61, 0
	v_mov_b32_e32 v62, 0
	v_mov_b32_e32 v63, 0
	v_mov_b32_e32 v64, 0
	v_mov_b32_e32 v65, 0
	v_mov_b32_e32 v66, 0
	v_mov_b32_e32 v67, 0
	v_mov_b32_e32 v68, 0
	v_mov_b32_e32 v69, 0
	v_mov_b32_e32 v70, 0
	v_mov_b32_e32 v71, 0
	v_mov_b32_e32 v72, 0
	v_mov_b32_e32 v73, 0
	v_mov_b32_e32 v74, 0
	v_mov_b32_e32 v75, 0
	v_mov_b32_e32 v76, 0
	v_mov_b32_e32 v77, 0
	v_mov_b32_e32 v78, 0
	v_mov_b32_e32 v79, 0
	v_mov_b32_e32 v80, 0
	v_mov_b32_e32 v81, 0
	v_mov_b32_e32 v82, 0
	v_mov_b32_e32 v83, 0
	v_mov_b32_e32 v84, 0
	v_mov_b32_e32 v85, 0
	v_mov_b32_e32 v86, 0
	v_mov_b32_e32 v87, 0
	v_mov_b32_e32 v88, 0
	v_mov_b32_e32 v89, 0
	v_mov_b32_e32 v90, 0
	v_mov_b32_e32 v91, 0
	v_mov_b32_e32 v92, 0
	v_mov_b32_e32 v93, 0
	v_mov_b32_e32 v94, 0
	v_mov_b32_e32 v95, 0
	v_mov_b32_e32 v96, 0
	v_mov_b32_e32 v97, 0
	v_mov_b32_e32 v98, 0
	v_mov_b32_e32 v99, 0
	v_mov_b32_e32 v100, 0
	v_mov_b32_e32 v101, 0
	v_mov_b32_e32 v102, 0
	v_mov_b32_e32 v103, 0
	v_mov_b32_e32 v104, 0
	v_mov_b32_e32 v105, 0
	v_mov_b32_e32 v106, 0
	v_mov_b32_e32 v107, 0
	v_mov_b32_e32 v108, 0
	v_mov_b32_e32 v109, 0
	v_mov_b32_e32 v110, 0
	v_mov_b32_e32 v111, 0
	v_mov_b32_e32 v112, 0
	v_mov_b32_e32 v113, 0
	v_mov_b32_e32 v114, 0
	v_mov_b32_e32 v115, 0
	v_mov_b32_e32 v116, 0
	v_mov_b32_e32 v117, 0
	v_mov_b32_e32 v118, 0
	v_mov_b32_e32 v119, 0
	v_mov_b32_e32 v120, 0
	v_mov_b32_e32 v121, 0
	v_mov_b32_e32 v122, 0
	v_mov_b32_e32 v123, 0
	v_mov_b32_e32 v124, 0
	v_mov_b32_e32 v125, 0
	v_mov_b32_e32 v126, 0
	v_mov_b32_e32 v127, 0
	s_mov_b32 s8, 0
	s_waitcnt vmcnt(10)
	s_barrier
.Lg16_down_k:
	s_add_i32 s9, s8, 2
	s_lshl_b32 s96, s9, 13
	s_add_i32 m0, vcc_lo, 16384
	v_lshl_add_u64 v[248:249], v[188:189], 0, s[96:97]
	global_load_lds_dwordx4 v[248:249], off
	global_load_lds_dwordx4 v[248:249], off offset:1024
	ds_read_b128 v[196:199], v246 offset:0
	ds_read_b128 v[200:203], v246 offset:1024
	ds_read_b128 v[204:207], v246 offset:2048
	ds_read_b128 v[242:245], v246 offset:3072
	s_add_i32 s9, s8, 3
	s_min_u32 s9, s9, 87
	s_lshl_b32 s96, s9, 11
	v_lshl_add_u64 v[248:249], v[184:185], 0, s[96:97]
	v_lshl_add_u64 v[250:251], v[186:187], 0, s[96:97]
	s_waitcnt lgkmcnt(3)
	v_mfma_f32_16x16x32_bf16 v[112:115], v[128:131], v[196:199], v[112:115]
	v_mfma_f32_16x16x32_bf16 v[120:123], v[132:135], v[196:199], v[120:123]
	v_mfma_f32_16x16x32_bf16 v[48:51], v[136:139], v[196:199], v[48:51]
	v_mfma_f32_16x16x32_bf16 v[56:59], v[140:143], v[196:199], v[56:59]
	ds_read_b128 v[196:199], v246 offset:4096
	s_waitcnt lgkmcnt(3)
	v_mfma_f32_16x16x32_bf16 v[116:119], v[128:131], v[200:203], v[116:119]
	v_mfma_f32_16x16x32_bf16 v[124:127], v[132:135], v[200:203], v[124:127]
	v_mfma_f32_16x16x32_bf16 v[52:55], v[136:139], v[200:203], v[52:55]
	v_mfma_f32_16x16x32_bf16 v[60:63], v[140:143], v[200:203], v[60:63]
	ds_read_b128 v[200:203], v246 offset:5120
	s_waitcnt lgkmcnt(3)
	v_mfma_f32_16x16x32_bf16 v[96:99], v[128:131], v[204:207], v[96:99]
	v_mfma_f32_16x16x32_bf16 v[104:107], v[132:135], v[204:207], v[104:107]
	v_mfma_f32_16x16x32_bf16 v[32:35], v[136:139], v[204:207], v[32:35]
	v_mfma_f32_16x16x32_bf16 v[40:43], v[140:143], v[204:207], v[40:43]
	ds_read_b128 v[204:207], v246 offset:6144
	s_waitcnt lgkmcnt(3)
	v_mfma_f32_16x16x32_bf16 v[100:103], v[128:131], v[242:245], v[100:103]
	v_mfma_f32_16x16x32_bf16 v[108:111], v[132:135], v[242:245], v[108:111]
	v_mfma_f32_16x16x32_bf16 v[36:39], v[136:139], v[242:245], v[36:39]
	v_mfma_f32_16x16x32_bf16 v[44:47], v[140:143], v[242:245], v[44:47]
	ds_read_b128 v[242:245], v246 offset:7168
	s_waitcnt lgkmcnt(3)
	v_mfma_f32_16x16x32_bf16 v[80:83], v[128:131], v[196:199], v[80:83]
	v_mfma_f32_16x16x32_bf16 v[88:91], v[132:135], v[196:199], v[88:91]
	v_mfma_f32_16x16x32_bf16 v[16:19], v[136:139], v[196:199], v[16:19]
	v_mfma_f32_16x16x32_bf16 v[24:27], v[140:143], v[196:199], v[24:27]
	s_waitcnt lgkmcnt(2)
	v_mfma_f32_16x16x32_bf16 v[84:87], v[128:131], v[200:203], v[84:87]
	v_mfma_f32_16x16x32_bf16 v[92:95], v[132:135], v[200:203], v[92:95]
	v_mfma_f32_16x16x32_bf16 v[20:23], v[136:139], v[200:203], v[20:23]
	v_mfma_f32_16x16x32_bf16 v[28:31], v[140:143], v[200:203], v[28:31]
	s_waitcnt lgkmcnt(1)
	v_mfma_f32_16x16x32_bf16 v[64:67], v[128:131], v[204:207], v[64:67]
	v_mfma_f32_16x16x32_bf16 v[72:75], v[132:135], v[204:207], v[72:75]
	v_mfma_f32_16x16x32_bf16 v[0:3], v[136:139], v[204:207], v[0:3]
	v_mfma_f32_16x16x32_bf16 v[8:11], v[140:143], v[204:207], v[8:11]
	s_waitcnt lgkmcnt(0)
	v_mfma_f32_16x16x32_bf16 v[68:71], v[128:131], v[242:245], v[68:71]
	v_mfma_f32_16x16x32_bf16 v[76:79], v[132:135], v[242:245], v[76:79]
	v_mfma_f32_16x16x32_bf16 v[4:7], v[136:139], v[242:245], v[4:7]
	v_mfma_f32_16x16x32_bf16 v[12:15], v[140:143], v[242:245], v[12:15]
	global_load_dwordx4 v[128:131], v[248:249], off
	global_load_dwordx4 v[132:135], v[248:249], off offset:256
	global_load_dwordx4 v[136:139], v[250:251], off
	global_load_dwordx4 v[140:143], v[250:251], off offset:256
	s_waitcnt vmcnt(10)
	s_barrier
	s_add_i32 s9, s8, 3
	s_lshl_b32 s96, s9, 13
	s_mov_b32 m0, vcc_lo
	v_lshl_add_u64 v[248:249], v[188:189], 0, s[96:97]
	global_load_lds_dwordx4 v[248:249], off
	global_load_lds_dwordx4 v[248:249], off offset:1024
	ds_read_b128 v[196:199], v246 offset:8192
	ds_read_b128 v[200:203], v246 offset:9216
	ds_read_b128 v[204:207], v246 offset:10240
	ds_read_b128 v[242:245], v246 offset:11264
	s_add_i32 s9, s8, 4
	s_min_u32 s9, s9, 87
	s_lshl_b32 s96, s9, 11
	v_lshl_add_u64 v[248:249], v[184:185], 0, s[96:97]
	v_lshl_add_u64 v[250:251], v[186:187], 0, s[96:97]
	s_waitcnt lgkmcnt(3)
	v_mfma_f32_16x16x32_bf16 v[112:115], v[144:147], v[196:199], v[112:115]
	v_mfma_f32_16x16x32_bf16 v[120:123], v[148:151], v[196:199], v[120:123]
	v_mfma_f32_16x16x32_bf16 v[48:51], v[152:155], v[196:199], v[48:51]
	v_mfma_f32_16x16x32_bf16 v[56:59], v[156:159], v[196:199], v[56:59]
	ds_read_b128 v[196:199], v246 offset:12288
	s_waitcnt lgkmcnt(3)
	v_mfma_f32_16x16x32_bf16 v[116:119], v[144:147], v[200:203], v[116:119]
	v_mfma_f32_16x16x32_bf16 v[124:127], v[148:151], v[200:203], v[124:127]
	v_mfma_f32_16x16x32_bf16 v[52:55], v[152:155], v[200:203], v[52:55]
	v_mfma_f32_16x16x32_bf16 v[60:63], v[156:159], v[200:203], v[60:63]
	ds_read_b128 v[200:203], v246 offset:13312
	s_waitcnt lgkmcnt(3)
	v_mfma_f32_16x16x32_bf16 v[96:99], v[144:147], v[204:207], v[96:99]
	v_mfma_f32_16x16x32_bf16 v[104:107], v[148:151], v[204:207], v[104:107]
	v_mfma_f32_16x16x32_bf16 v[32:35], v[152:155], v[204:207], v[32:35]
	v_mfma_f32_16x16x32_bf16 v[40:43], v[156:159], v[204:207], v[40:43]
	ds_read_b128 v[204:207], v246 offset:14336
	s_waitcnt lgkmcnt(3)
	v_mfma_f32_16x16x32_bf16 v[100:103], v[144:147], v[242:245], v[100:103]
	v_mfma_f32_16x16x32_bf16 v[108:111], v[148:151], v[242:245], v[108:111]
	v_mfma_f32_16x16x32_bf16 v[36:39], v[152:155], v[242:245], v[36:39]
	v_mfma_f32_16x16x32_bf16 v[44:47], v[156:159], v[242:245], v[44:47]
	ds_read_b128 v[242:245], v246 offset:15360
	s_waitcnt lgkmcnt(3)
	v_mfma_f32_16x16x32_bf16 v[80:83], v[144:147], v[196:199], v[80:83]
	v_mfma_f32_16x16x32_bf16 v[88:91], v[148:151], v[196:199], v[88:91]
	v_mfma_f32_16x16x32_bf16 v[16:19], v[152:155], v[196:199], v[16:19]
	v_mfma_f32_16x16x32_bf16 v[24:27], v[156:159], v[196:199], v[24:27]
	s_waitcnt lgkmcnt(2)
	v_mfma_f32_16x16x32_bf16 v[84:87], v[144:147], v[200:203], v[84:87]
	v_mfma_f32_16x16x32_bf16 v[92:95], v[148:151], v[200:203], v[92:95]
	v_mfma_f32_16x16x32_bf16 v[20:23], v[152:155], v[200:203], v[20:23]
	v_mfma_f32_16x16x32_bf16 v[28:31], v[156:159], v[200:203], v[28:31]
	s_waitcnt lgkmcnt(1)
	v_mfma_f32_16x16x32_bf16 v[64:67], v[144:147], v[204:207], v[64:67]
	v_mfma_f32_16x16x32_bf16 v[72:75], v[148:151], v[204:207], v[72:75]
	v_mfma_f32_16x16x32_bf16 v[0:3], v[152:155], v[204:207], v[0:3]
	v_mfma_f32_16x16x32_bf16 v[8:11], v[156:159], v[204:207], v[8:11]
	s_waitcnt lgkmcnt(0)
	v_mfma_f32_16x16x32_bf16 v[68:71], v[144:147], v[242:245], v[68:71]
	v_mfma_f32_16x16x32_bf16 v[76:79], v[148:151], v[242:245], v[76:79]
	v_mfma_f32_16x16x32_bf16 v[4:7], v[152:155], v[242:245], v[4:7]
	v_mfma_f32_16x16x32_bf16 v[12:15], v[156:159], v[242:245], v[12:15]
	global_load_dwordx4 v[144:147], v[248:249], off
	global_load_dwordx4 v[148:151], v[248:249], off offset:256
	global_load_dwordx4 v[152:155], v[250:251], off
	global_load_dwordx4 v[156:159], v[250:251], off offset:256
	s_waitcnt vmcnt(10)
	s_barrier
	s_add_i32 s9, s8, 4
	s_lshl_b32 s96, s9, 13
	s_add_i32 m0, vcc_lo, 8192
	v_lshl_add_u64 v[248:249], v[188:189], 0, s[96:97]
	global_load_lds_dwordx4 v[248:249], off
	global_load_lds_dwordx4 v[248:249], off offset:1024
	ds_read_b128 v[196:199], v246 offset:16384
	ds_read_b128 v[200:203], v246 offset:17408
	ds_read_b128 v[204:207], v246 offset:18432
	ds_read_b128 v[242:245], v246 offset:19456
	s_add_i32 s9, s8, 5
	s_min_u32 s9, s9, 87
	s_lshl_b32 s96, s9, 11
	v_lshl_add_u64 v[248:249], v[184:185], 0, s[96:97]
	v_lshl_add_u64 v[250:251], v[186:187], 0, s[96:97]
	s_waitcnt lgkmcnt(3)
	v_mfma_f32_16x16x32_bf16 v[112:115], v[160:163], v[196:199], v[112:115]
	v_mfma_f32_16x16x32_bf16 v[120:123], v[164:167], v[196:199], v[120:123]
	v_mfma_f32_16x16x32_bf16 v[48:51], v[168:171], v[196:199], v[48:51]
	v_mfma_f32_16x16x32_bf16 v[56:59], v[172:175], v[196:199], v[56:59]
	ds_read_b128 v[196:199], v246 offset:20480
	s_waitcnt lgkmcnt(3)
	v_mfma_f32_16x16x32_bf16 v[116:119], v[160:163], v[200:203], v[116:119]
	v_mfma_f32_16x16x32_bf16 v[124:127], v[164:167], v[200:203], v[124:127]
	v_mfma_f32_16x16x32_bf16 v[52:55], v[168:171], v[200:203], v[52:55]
	v_mfma_f32_16x16x32_bf16 v[60:63], v[172:175], v[200:203], v[60:63]
	ds_read_b128 v[200:203], v246 offset:21504
	s_waitcnt lgkmcnt(3)
	v_mfma_f32_16x16x32_bf16 v[96:99], v[160:163], v[204:207], v[96:99]
	v_mfma_f32_16x16x32_bf16 v[104:107], v[164:167], v[204:207], v[104:107]
	v_mfma_f32_16x16x32_bf16 v[32:35], v[168:171], v[204:207], v[32:35]
	v_mfma_f32_16x16x32_bf16 v[40:43], v[172:175], v[204:207], v[40:43]
	ds_read_b128 v[204:207], v246 offset:22528
	s_waitcnt lgkmcnt(3)
	v_mfma_f32_16x16x32_bf16 v[100:103], v[160:163], v[242:245], v[100:103]
	v_mfma_f32_16x16x32_bf16 v[108:111], v[164:167], v[242:245], v[108:111]
	v_mfma_f32_16x16x32_bf16 v[36:39], v[168:171], v[242:245], v[36:39]
	v_mfma_f32_16x16x32_bf16 v[44:47], v[172:175], v[242:245], v[44:47]
	ds_read_b128 v[242:245], v246 offset:23552
	s_waitcnt lgkmcnt(3)
	v_mfma_f32_16x16x32_bf16 v[80:83], v[160:163], v[196:199], v[80:83]
	v_mfma_f32_16x16x32_bf16 v[88:91], v[164:167], v[196:199], v[88:91]
	v_mfma_f32_16x16x32_bf16 v[16:19], v[168:171], v[196:199], v[16:19]
	v_mfma_f32_16x16x32_bf16 v[24:27], v[172:175], v[196:199], v[24:27]
	s_waitcnt lgkmcnt(2)
	v_mfma_f32_16x16x32_bf16 v[84:87], v[160:163], v[200:203], v[84:87]
	v_mfma_f32_16x16x32_bf16 v[92:95], v[164:167], v[200:203], v[92:95]
	v_mfma_f32_16x16x32_bf16 v[20:23], v[168:171], v[200:203], v[20:23]
	v_mfma_f32_16x16x32_bf16 v[28:31], v[172:175], v[200:203], v[28:31]
	s_waitcnt lgkmcnt(1)
	v_mfma_f32_16x16x32_bf16 v[64:67], v[160:163], v[204:207], v[64:67]
	v_mfma_f32_16x16x32_bf16 v[72:75], v[164:167], v[204:207], v[72:75]
	v_mfma_f32_16x16x32_bf16 v[0:3], v[168:171], v[204:207], v[0:3]
	v_mfma_f32_16x16x32_bf16 v[8:11], v[172:175], v[204:207], v[8:11]
	s_waitcnt lgkmcnt(0)
	v_mfma_f32_16x16x32_bf16 v[68:71], v[160:163], v[242:245], v[68:71]
	v_mfma_f32_16x16x32_bf16 v[76:79], v[164:167], v[242:245], v[76:79]
	v_mfma_f32_16x16x32_bf16 v[4:7], v[168:171], v[242:245], v[4:7]
	v_mfma_f32_16x16x32_bf16 v[12:15], v[172:175], v[242:245], v[12:15]
	global_load_dwordx4 v[160:163], v[248:249], off
	global_load_dwordx4 v[164:167], v[248:249], off offset:256
	global_load_dwordx4 v[168:171], v[250:251], off
	global_load_dwordx4 v[172:175], v[250:251], off offset:256
	s_waitcnt vmcnt(10)
	s_barrier
	s_add_i32 s9, s8, 5
	s_lshl_b32 s96, s9, 13
	s_add_i32 m0, vcc_lo, 16384
	v_lshl_add_u64 v[248:249], v[188:189], 0, s[96:97]
	global_load_lds_dwordx4 v[248:249], off
	global_load_lds_dwordx4 v[248:249], off offset:1024
	ds_read_b128 v[196:199], v246 offset:0
	ds_read_b128 v[200:203], v246 offset:1024
	ds_read_b128 v[204:207], v246 offset:2048
	ds_read_b128 v[242:245], v246 offset:3072
	s_add_i32 s9, s8, 6
	s_min_u32 s9, s9, 87
	s_lshl_b32 s96, s9, 11
	v_lshl_add_u64 v[248:249], v[184:185], 0, s[96:97]
	v_lshl_add_u64 v[250:251], v[186:187], 0, s[96:97]
	s_waitcnt lgkmcnt(3)
	v_mfma_f32_16x16x32_bf16 v[112:115], v[128:131], v[196:199], v[112:115]
	v_mfma_f32_16x16x32_bf16 v[120:123], v[132:135], v[196:199], v[120:123]
	v_mfma_f32_16x16x32_bf16 v[48:51], v[136:139], v[196:199], v[48:51]
	v_mfma_f32_16x16x32_bf16 v[56:59], v[140:143], v[196:199], v[56:59]
	ds_read_b128 v[196:199], v246 offset:4096
	s_waitcnt lgkmcnt(3)
	v_mfma_f32_16x16x32_bf16 v[116:119], v[128:131], v[200:203], v[116:119]
	v_mfma_f32_16x16x32_bf16 v[124:127], v[132:135], v[200:203], v[124:127]
	v_mfma_f32_16x16x32_bf16 v[52:55], v[136:139], v[200:203], v[52:55]
	v_mfma_f32_16x16x32_bf16 v[60:63], v[140:143], v[200:203], v[60:63]
	ds_read_b128 v[200:203], v246 offset:5120
	s_waitcnt lgkmcnt(3)
	v_mfma_f32_16x16x32_bf16 v[96:99], v[128:131], v[204:207], v[96:99]
	v_mfma_f32_16x16x32_bf16 v[104:107], v[132:135], v[204:207], v[104:107]
	v_mfma_f32_16x16x32_bf16 v[32:35], v[136:139], v[204:207], v[32:35]
	v_mfma_f32_16x16x32_bf16 v[40:43], v[140:143], v[204:207], v[40:43]
	ds_read_b128 v[204:207], v246 offset:6144
	s_waitcnt lgkmcnt(3)
	v_mfma_f32_16x16x32_bf16 v[100:103], v[128:131], v[242:245], v[100:103]
	v_mfma_f32_16x16x32_bf16 v[108:111], v[132:135], v[242:245], v[108:111]
	v_mfma_f32_16x16x32_bf16 v[36:39], v[136:139], v[242:245], v[36:39]
	v_mfma_f32_16x16x32_bf16 v[44:47], v[140:143], v[242:245], v[44:47]
	ds_read_b128 v[242:245], v246 offset:7168
	s_waitcnt lgkmcnt(3)
	v_mfma_f32_16x16x32_bf16 v[80:83], v[128:131], v[196:199], v[80:83]
	v_mfma_f32_16x16x32_bf16 v[88:91], v[132:135], v[196:199], v[88:91]
	v_mfma_f32_16x16x32_bf16 v[16:19], v[136:139], v[196:199], v[16:19]
	v_mfma_f32_16x16x32_bf16 v[24:27], v[140:143], v[196:199], v[24:27]
	s_waitcnt lgkmcnt(2)
	v_mfma_f32_16x16x32_bf16 v[84:87], v[128:131], v[200:203], v[84:87]
	v_mfma_f32_16x16x32_bf16 v[92:95], v[132:135], v[200:203], v[92:95]
	v_mfma_f32_16x16x32_bf16 v[20:23], v[136:139], v[200:203], v[20:23]
	v_mfma_f32_16x16x32_bf16 v[28:31], v[140:143], v[200:203], v[28:31]
	s_waitcnt lgkmcnt(1)
	v_mfma_f32_16x16x32_bf16 v[64:67], v[128:131], v[204:207], v[64:67]
	v_mfma_f32_16x16x32_bf16 v[72:75], v[132:135], v[204:207], v[72:75]
	v_mfma_f32_16x16x32_bf16 v[0:3], v[136:139], v[204:207], v[0:3]
	v_mfma_f32_16x16x32_bf16 v[8:11], v[140:143], v[204:207], v[8:11]
	s_waitcnt lgkmcnt(0)
	v_mfma_f32_16x16x32_bf16 v[68:71], v[128:131], v[242:245], v[68:71]
	v_mfma_f32_16x16x32_bf16 v[76:79], v[132:135], v[242:245], v[76:79]
	v_mfma_f32_16x16x32_bf16 v[4:7], v[136:139], v[242:245], v[4:7]
	v_mfma_f32_16x16x32_bf16 v[12:15], v[140:143], v[242:245], v[12:15]
	global_load_dwordx4 v[128:131], v[248:249], off
	global_load_dwordx4 v[132:135], v[248:249], off offset:256
	global_load_dwordx4 v[136:139], v[250:251], off
	global_load_dwordx4 v[140:143], v[250:251], off offset:256
	s_waitcnt vmcnt(10)
	s_barrier
	s_add_i32 s9, s8, 6
	s_lshl_b32 s96, s9, 13
	s_mov_b32 m0, vcc_lo
	v_lshl_add_u64 v[248:249], v[188:189], 0, s[96:97]
	global_load_lds_dwordx4 v[248:249], off
	global_load_lds_dwordx4 v[248:249], off offset:1024
	ds_read_b128 v[196:199], v246 offset:8192
	ds_read_b128 v[200:203], v246 offset:9216
	ds_read_b128 v[204:207], v246 offset:10240
	ds_read_b128 v[242:245], v246 offset:11264
	s_add_i32 s9, s8, 7
	s_min_u32 s9, s9, 87
	s_lshl_b32 s96, s9, 11
	v_lshl_add_u64 v[248:249], v[184:185], 0, s[96:97]
	v_lshl_add_u64 v[250:251], v[186:187], 0, s[96:97]
	s_waitcnt lgkmcnt(3)
	v_mfma_f32_16x16x32_bf16 v[112:115], v[144:147], v[196:199], v[112:115]
	v_mfma_f32_16x16x32_bf16 v[120:123], v[148:151], v[196:199], v[120:123]
	v_mfma_f32_16x16x32_bf16 v[48:51], v[152:155], v[196:199], v[48:51]
	v_mfma_f32_16x16x32_bf16 v[56:59], v[156:159], v[196:199], v[56:59]
	ds_read_b128 v[196:199], v246 offset:12288
	s_waitcnt lgkmcnt(3)
	v_mfma_f32_16x16x32_bf16 v[116:119], v[144:147], v[200:203], v[116:119]
	v_mfma_f32_16x16x32_bf16 v[124:127], v[148:151], v[200:203], v[124:127]
	v_mfma_f32_16x16x32_bf16 v[52:55], v[152:155], v[200:203], v[52:55]
	v_mfma_f32_16x16x32_bf16 v[60:63], v[156:159], v[200:203], v[60:63]
	ds_read_b128 v[200:203], v246 offset:13312
	s_waitcnt lgkmcnt(3)
	v_mfma_f32_16x16x32_bf16 v[96:99], v[144:147], v[204:207], v[96:99]
	v_mfma_f32_16x16x32_bf16 v[104:107], v[148:151], v[204:207], v[104:107]
	v_mfma_f32_16x16x32_bf16 v[32:35], v[152:155], v[204:207], v[32:35]
	v_mfma_f32_16x16x32_bf16 v[40:43], v[156:159], v[204:207], v[40:43]
	ds_read_b128 v[204:207], v246 offset:14336
	s_waitcnt lgkmcnt(3)
	v_mfma_f32_16x16x32_bf16 v[100:103], v[144:147], v[242:245], v[100:103]
	v_mfma_f32_16x16x32_bf16 v[108:111], v[148:151], v[242:245], v[108:111]
	v_mfma_f32_16x16x32_bf16 v[36:39], v[152:155], v[242:245], v[36:39]
	v_mfma_f32_16x16x32_bf16 v[44:47], v[156:159], v[242:245], v[44:47]
	ds_read_b128 v[242:245], v246 offset:15360
	s_waitcnt lgkmcnt(3)
	v_mfma_f32_16x16x32_bf16 v[80:83], v[144:147], v[196:199], v[80:83]
	v_mfma_f32_16x16x32_bf16 v[88:91], v[148:151], v[196:199], v[88:91]
	v_mfma_f32_16x16x32_bf16 v[16:19], v[152:155], v[196:199], v[16:19]
	v_mfma_f32_16x16x32_bf16 v[24:27], v[156:159], v[196:199], v[24:27]
	s_waitcnt lgkmcnt(2)
	v_mfma_f32_16x16x32_bf16 v[84:87], v[144:147], v[200:203], v[84:87]
	v_mfma_f32_16x16x32_bf16 v[92:95], v[148:151], v[200:203], v[92:95]
	v_mfma_f32_16x16x32_bf16 v[20:23], v[152:155], v[200:203], v[20:23]
	v_mfma_f32_16x16x32_bf16 v[28:31], v[156:159], v[200:203], v[28:31]
	s_waitcnt lgkmcnt(1)
	v_mfma_f32_16x16x32_bf16 v[64:67], v[144:147], v[204:207], v[64:67]
	v_mfma_f32_16x16x32_bf16 v[72:75], v[148:151], v[204:207], v[72:75]
	v_mfma_f32_16x16x32_bf16 v[0:3], v[152:155], v[204:207], v[0:3]
	v_mfma_f32_16x16x32_bf16 v[8:11], v[156:159], v[204:207], v[8:11]
	s_waitcnt lgkmcnt(0)
	v_mfma_f32_16x16x32_bf16 v[68:71], v[144:147], v[242:245], v[68:71]
	v_mfma_f32_16x16x32_bf16 v[76:79], v[148:151], v[242:245], v[76:79]
	v_mfma_f32_16x16x32_bf16 v[4:7], v[152:155], v[242:245], v[4:7]
	v_mfma_f32_16x16x32_bf16 v[12:15], v[156:159], v[242:245], v[12:15]
	global_load_dwordx4 v[144:147], v[248:249], off
	global_load_dwordx4 v[148:151], v[248:249], off offset:256
	global_load_dwordx4 v[152:155], v[250:251], off
	global_load_dwordx4 v[156:159], v[250:251], off offset:256
	s_waitcnt vmcnt(10)
	s_barrier
	s_add_i32 s9, s8, 7
	s_lshl_b32 s96, s9, 13
	s_add_i32 m0, vcc_lo, 8192
	v_lshl_add_u64 v[248:249], v[188:189], 0, s[96:97]
	global_load_lds_dwordx4 v[248:249], off
	global_load_lds_dwordx4 v[248:249], off offset:1024
	ds_read_b128 v[196:199], v246 offset:16384
	ds_read_b128 v[200:203], v246 offset:17408
	ds_read_b128 v[204:207], v246 offset:18432
	ds_read_b128 v[242:245], v246 offset:19456
	s_add_i32 s9, s8, 8
	s_min_u32 s9, s9, 87
	s_lshl_b32 s96, s9, 11
	v_lshl_add_u64 v[248:249], v[184:185], 0, s[96:97]
	v_lshl_add_u64 v[250:251], v[186:187], 0, s[96:97]
	s_waitcnt lgkmcnt(3)
	v_mfma_f32_16x16x32_bf16 v[112:115], v[160:163], v[196:199], v[112:115]
	v_mfma_f32_16x16x32_bf16 v[120:123], v[164:167], v[196:199], v[120:123]
	v_mfma_f32_16x16x32_bf16 v[48:51], v[168:171], v[196:199], v[48:51]
	v_mfma_f32_16x16x32_bf16 v[56:59], v[172:175], v[196:199], v[56:59]
	ds_read_b128 v[196:199], v246 offset:20480
	s_waitcnt lgkmcnt(3)
	v_mfma_f32_16x16x32_bf16 v[116:119], v[160:163], v[200:203], v[116:119]
	v_mfma_f32_16x16x32_bf16 v[124:127], v[164:167], v[200:203], v[124:127]
	v_mfma_f32_16x16x32_bf16 v[52:55], v[168:171], v[200:203], v[52:55]
	v_mfma_f32_16x16x32_bf16 v[60:63], v[172:175], v[200:203], v[60:63]
	ds_read_b128 v[200:203], v246 offset:21504
	s_waitcnt lgkmcnt(3)
	v_mfma_f32_16x16x32_bf16 v[96:99], v[160:163], v[204:207], v[96:99]
	v_mfma_f32_16x16x32_bf16 v[104:107], v[164:167], v[204:207], v[104:107]
	v_mfma_f32_16x16x32_bf16 v[32:35], v[168:171], v[204:207], v[32:35]
	v_mfma_f32_16x16x32_bf16 v[40:43], v[172:175], v[204:207], v[40:43]
	ds_read_b128 v[204:207], v246 offset:22528
	s_waitcnt lgkmcnt(3)
	v_mfma_f32_16x16x32_bf16 v[100:103], v[160:163], v[242:245], v[100:103]
	v_mfma_f32_16x16x32_bf16 v[108:111], v[164:167], v[242:245], v[108:111]
	v_mfma_f32_16x16x32_bf16 v[36:39], v[168:171], v[242:245], v[36:39]
	v_mfma_f32_16x16x32_bf16 v[44:47], v[172:175], v[242:245], v[44:47]
	ds_read_b128 v[242:245], v246 offset:23552
	s_waitcnt lgkmcnt(3)
	v_mfma_f32_16x16x32_bf16 v[80:83], v[160:163], v[196:199], v[80:83]
	v_mfma_f32_16x16x32_bf16 v[88:91], v[164:167], v[196:199], v[88:91]
	v_mfma_f32_16x16x32_bf16 v[16:19], v[168:171], v[196:199], v[16:19]
	v_mfma_f32_16x16x32_bf16 v[24:27], v[172:175], v[196:199], v[24:27]
	s_waitcnt lgkmcnt(2)
	v_mfma_f32_16x16x32_bf16 v[84:87], v[160:163], v[200:203], v[84:87]
	v_mfma_f32_16x16x32_bf16 v[92:95], v[164:167], v[200:203], v[92:95]
	v_mfma_f32_16x16x32_bf16 v[20:23], v[168:171], v[200:203], v[20:23]
	v_mfma_f32_16x16x32_bf16 v[28:31], v[172:175], v[200:203], v[28:31]
	s_waitcnt lgkmcnt(1)
	v_mfma_f32_16x16x32_bf16 v[64:67], v[160:163], v[204:207], v[64:67]
	v_mfma_f32_16x16x32_bf16 v[72:75], v[164:167], v[204:207], v[72:75]
	v_mfma_f32_16x16x32_bf16 v[0:3], v[168:171], v[204:207], v[0:3]
	v_mfma_f32_16x16x32_bf16 v[8:11], v[172:175], v[204:207], v[8:11]
	s_waitcnt lgkmcnt(0)
	v_mfma_f32_16x16x32_bf16 v[68:71], v[160:163], v[242:245], v[68:71]
	v_mfma_f32_16x16x32_bf16 v[76:79], v[164:167], v[242:245], v[76:79]
	v_mfma_f32_16x16x32_bf16 v[4:7], v[168:171], v[242:245], v[4:7]
	v_mfma_f32_16x16x32_bf16 v[12:15], v[172:175], v[242:245], v[12:15]
	global_load_dwordx4 v[160:163], v[248:249], off
	global_load_dwordx4 v[164:167], v[248:249], off offset:256
	global_load_dwordx4 v[168:171], v[250:251], off
	global_load_dwordx4 v[172:175], v[250:251], off offset:256
	s_waitcnt vmcnt(10)
	s_barrier
	s_add_i32 s8, s8, 6
	s_cmp_lt_u32 s8, 84
	s_cbranch_scc1 .Lg16_down_k
	s_mov_b32 s96, 0xac000
	s_add_i32 m0, vcc_lo, 16384
	v_lshl_add_u64 v[248:249], v[188:189], 0, s[96:97]
	global_load_lds_dwordx4 v[248:249], off
	global_load_lds_dwordx4 v[248:249], off offset:1024
	ds_read_b128 v[196:199], v246 offset:0
	ds_read_b128 v[200:203], v246 offset:1024
	ds_read_b128 v[204:207], v246 offset:2048
	ds_read_b128 v[242:245], v246 offset:3072
	s_mov_b32 s96, 0x2b800
	v_lshl_add_u64 v[248:249], v[184:185], 0, s[96:97]
	v_lshl_add_u64 v[250:251], v[186:187], 0, s[96:97]
	s_waitcnt lgkmcnt(3)
	v_mfma_f32_16x16x32_bf16 v[112:115], v[128:131], v[196:199], v[112:115]
	v_mfma_f32_16x16x32_bf16 v[120:123], v[132:135], v[196:199], v[120:123]
	v_mfma_f32_16x16x32_bf16 v[48:51], v[136:139], v[196:199], v[48:51]
	v_mfma_f32_16x16x32_bf16 v[56:59], v[140:143], v[196:199], v[56:59]
	ds_read_b128 v[196:199], v246 offset:4096
	s_waitcnt lgkmcnt(3)
	v_mfma_f32_16x16x32_bf16 v[116:119], v[128:131], v[200:203], v[116:119]
	v_mfma_f32_16x16x32_bf16 v[124:127], v[132:135], v[200:203], v[124:127]
	v_mfma_f32_16x16x32_bf16 v[52:55], v[136:139], v[200:203], v[52:55]
	v_mfma_f32_16x16x32_bf16 v[60:63], v[140:143], v[200:203], v[60:63]
	ds_read_b128 v[200:203], v246 offset:5120
	s_waitcnt lgkmcnt(3)
	v_mfma_f32_16x16x32_bf16 v[96:99], v[128:131], v[204:207], v[96:99]
	v_mfma_f32_16x16x32_bf16 v[104:107], v[132:135], v[204:207], v[104:107]
	v_mfma_f32_16x16x32_bf16 v[32:35], v[136:139], v[204:207], v[32:35]
	v_mfma_f32_16x16x32_bf16 v[40:43], v[140:143], v[204:207], v[40:43]
	ds_read_b128 v[204:207], v246 offset:6144
	s_waitcnt lgkmcnt(3)
	v_mfma_f32_16x16x32_bf16 v[100:103], v[128:131], v[242:245], v[100:103]
	v_mfma_f32_16x16x32_bf16 v[108:111], v[132:135], v[242:245], v[108:111]
	v_mfma_f32_16x16x32_bf16 v[36:39], v[136:139], v[242:245], v[36:39]
	v_mfma_f32_16x16x32_bf16 v[44:47], v[140:143], v[242:245], v[44:47]
	ds_read_b128 v[242:245], v246 offset:7168
	s_waitcnt lgkmcnt(3)
	v_mfma_f32_16x16x32_bf16 v[80:83], v[128:131], v[196:199], v[80:83]
	v_mfma_f32_16x16x32_bf16 v[88:91], v[132:135], v[196:199], v[88:91]
	v_mfma_f32_16x16x32_bf16 v[16:19], v[136:139], v[196:199], v[16:19]
	v_mfma_f32_16x16x32_bf16 v[24:27], v[140:143], v[196:199], v[24:27]
	s_waitcnt lgkmcnt(2)
	v_mfma_f32_16x16x32_bf16 v[84:87], v[128:131], v[200:203], v[84:87]
	v_mfma_f32_16x16x32_bf16 v[92:95], v[132:135], v[200:203], v[92:95]
	v_mfma_f32_16x16x32_bf16 v[20:23], v[136:139], v[200:203], v[20:23]
	v_mfma_f32_16x16x32_bf16 v[28:31], v[140:143], v[200:203], v[28:31]
	s_waitcnt lgkmcnt(1)
	v_mfma_f32_16x16x32_bf16 v[64:67], v[128:131], v[204:207], v[64:67]
	v_mfma_f32_16x16x32_bf16 v[72:75], v[132:135], v[204:207], v[72:75]
	v_mfma_f32_16x16x32_bf16 v[0:3], v[136:139], v[204:207], v[0:3]
	v_mfma_f32_16x16x32_bf16 v[8:11], v[140:143], v[204:207], v[8:11]
	s_waitcnt lgkmcnt(0)
	v_mfma_f32_16x16x32_bf16 v[68:71], v[128:131], v[242:245], v[68:71]
	v_mfma_f32_16x16x32_bf16 v[76:79], v[132:135], v[242:245], v[76:79]
	v_mfma_f32_16x16x32_bf16 v[4:7], v[136:139], v[242:245], v[4:7]
	v_mfma_f32_16x16x32_bf16 v[12:15], v[140:143], v[242:245], v[12:15]
	global_load_dwordx4 v[128:131], v[248:249], off
	global_load_dwordx4 v[132:135], v[248:249], off offset:256
	global_load_dwordx4 v[136:139], v[250:251], off
	global_load_dwordx4 v[140:143], v[250:251], off offset:256
	s_waitcnt vmcnt(10)
	s_barrier
	s_mov_b32 s96, 0xae000
	s_mov_b32 m0, vcc_lo
	v_lshl_add_u64 v[248:249], v[188:189], 0, s[96:97]
	global_load_lds_dwordx4 v[248:249], off
	global_load_lds_dwordx4 v[248:249], off offset:1024
	ds_read_b128 v[196:199], v246 offset:8192
	ds_read_b128 v[200:203], v246 offset:9216
	ds_read_b128 v[204:207], v246 offset:10240
	ds_read_b128 v[242:245], v246 offset:11264
	s_waitcnt lgkmcnt(3)
	v_mfma_f32_16x16x32_bf16 v[112:115], v[144:147], v[196:199], v[112:115]
	v_mfma_f32_16x16x32_bf16 v[120:123], v[148:151], v[196:199], v[120:123]
	v_mfma_f32_16x16x32_bf16 v[48:51], v[152:155], v[196:199], v[48:51]
	v_mfma_f32_16x16x32_bf16 v[56:59], v[156:159], v[196:199], v[56:59]
	ds_read_b128 v[196:199], v246 offset:12288
	s_waitcnt lgkmcnt(3)
	v_mfma_f32_16x16x32_bf16 v[116:119], v[144:147], v[200:203], v[116:119]
	v_mfma_f32_16x16x32_bf16 v[124:127], v[148:151], v[200:203], v[124:127]
	v_mfma_f32_16x16x32_bf16 v[52:55], v[152:155], v[200:203], v[52:55]
	v_mfma_f32_16x16x32_bf16 v[60:63], v[156:159], v[200:203], v[60:63]
	ds_read_b128 v[200:203], v246 offset:13312
	s_waitcnt lgkmcnt(3)
	v_mfma_f32_16x16x32_bf16 v[96:99], v[144:147], v[204:207], v[96:99]
	v_mfma_f32_16x16x32_bf16 v[104:107], v[148:151], v[204:207], v[104:107]
	v_mfma_f32_16x16x32_bf16 v[32:35], v[152:155], v[204:207], v[32:35]
	v_mfma_f32_16x16x32_bf16 v[40:43], v[156:159], v[204:207], v[40:43]
	ds_read_b128 v[204:207], v246 offset:14336
	s_waitcnt lgkmcnt(3)
	v_mfma_f32_16x16x32_bf16 v[100:103], v[144:147], v[242:245], v[100:103]
	v_mfma_f32_16x16x32_bf16 v[108:111], v[148:151], v[242:245], v[108:111]
	v_mfma_f32_16x16x32_bf16 v[36:39], v[152:155], v[242:245], v[36:39]
	v_mfma_f32_16x16x32_bf16 v[44:47], v[156:159], v[242:245], v[44:47]
	ds_read_b128 v[242:245], v246 offset:15360
	s_waitcnt lgkmcnt(3)
	v_mfma_f32_16x16x32_bf16 v[80:83], v[144:147], v[196:199], v[80:83]
	v_mfma_f32_16x16x32_bf16 v[88:91], v[148:151], v[196:199], v[88:91]
	v_mfma_f32_16x16x32_bf16 v[16:19], v[152:155], v[196:199], v[16:19]
	v_mfma_f32_16x16x32_bf16 v[24:27], v[156:159], v[196:199], v[24:27]
	s_waitcnt lgkmcnt(2)
	v_mfma_f32_16x16x32_bf16 v[84:87], v[144:147], v[200:203], v[84:87]
	v_mfma_f32_16x16x32_bf16 v[92:95], v[148:151], v[200:203], v[92:95]
	v_mfma_f32_16x16x32_bf16 v[20:23], v[152:155], v[200:203], v[20:23]
	v_mfma_f32_16x16x32_bf16 v[28:31], v[156:159], v[200:203], v[28:31]
	s_waitcnt lgkmcnt(1)
	v_mfma_f32_16x16x32_bf16 v[64:67], v[144:147], v[204:207], v[64:67]
	v_mfma_f32_16x16x32_bf16 v[72:75], v[148:151], v[204:207], v[72:75]
	v_mfma_f32_16x16x32_bf16 v[0:3], v[152:155], v[204:207], v[0:3]
	v_mfma_f32_16x16x32_bf16 v[8:11], v[156:159], v[204:207], v[8:11]
	s_waitcnt lgkmcnt(0)
	v_mfma_f32_16x16x32_bf16 v[68:71], v[144:147], v[242:245], v[68:71]
	v_mfma_f32_16x16x32_bf16 v[76:79], v[148:151], v[242:245], v[76:79]
	v_mfma_f32_16x16x32_bf16 v[4:7], v[152:155], v[242:245], v[4:7]
	v_mfma_f32_16x16x32_bf16 v[12:15], v[156:159], v[242:245], v[12:15]
	s_waitcnt vmcnt(6)
	s_barrier
	ds_read_b128 v[196:199], v246 offset:16384
	ds_read_b128 v[200:203], v246 offset:17408
	ds_read_b128 v[204:207], v246 offset:18432
	ds_read_b128 v[242:245], v246 offset:19456
	s_waitcnt lgkmcnt(3)
	v_mfma_f32_16x16x32_bf16 v[112:115], v[160:163], v[196:199], v[112:115]
	v_mfma_f32_16x16x32_bf16 v[120:123], v[164:167], v[196:199], v[120:123]
	v_mfma_f32_16x16x32_bf16 v[48:51], v[168:171], v[196:199], v[48:51]
	v_mfma_f32_16x16x32_bf16 v[56:59], v[172:175], v[196:199], v[56:59]
	ds_read_b128 v[196:199], v246 offset:20480
	s_waitcnt lgkmcnt(3)
	v_mfma_f32_16x16x32_bf16 v[116:119], v[160:163], v[200:203], v[116:119]
	v_mfma_f32_16x16x32_bf16 v[124:127], v[164:167], v[200:203], v[124:127]
	v_mfma_f32_16x16x32_bf16 v[52:55], v[168:171], v[200:203], v[52:55]
	v_mfma_f32_16x16x32_bf16 v[60:63], v[172:175], v[200:203], v[60:63]
	ds_read_b128 v[200:203], v246 offset:21504
	s_waitcnt lgkmcnt(3)
	v_mfma_f32_16x16x32_bf16 v[96:99], v[160:163], v[204:207], v[96:99]
	v_mfma_f32_16x16x32_bf16 v[104:107], v[164:167], v[204:207], v[104:107]
	v_mfma_f32_16x16x32_bf16 v[32:35], v[168:171], v[204:207], v[32:35]
	v_mfma_f32_16x16x32_bf16 v[40:43], v[172:175], v[204:207], v[40:43]
	ds_read_b128 v[204:207], v246 offset:22528
	s_waitcnt lgkmcnt(3)
	v_mfma_f32_16x16x32_bf16 v[100:103], v[160:163], v[242:245], v[100:103]
	v_mfma_f32_16x16x32_bf16 v[108:111], v[164:167], v[242:245], v[108:111]
	v_mfma_f32_16x16x32_bf16 v[36:39], v[168:171], v[242:245], v[36:39]
	v_mfma_f32_16x16x32_bf16 v[44:47], v[172:175], v[242:245], v[44:47]
	ds_read_b128 v[242:245], v246 offset:23552
	s_waitcnt lgkmcnt(3)
	v_mfma_f32_16x16x32_bf16 v[80:83], v[160:163], v[196:199], v[80:83]
	v_mfma_f32_16x16x32_bf16 v[88:91], v[164:167], v[196:199], v[88:91]
	v_mfma_f32_16x16x32_bf16 v[16:19], v[168:171], v[196:199], v[16:19]
	v_mfma_f32_16x16x32_bf16 v[24:27], v[172:175], v[196:199], v[24:27]
	s_waitcnt lgkmcnt(2)
	v_mfma_f32_16x16x32_bf16 v[84:87], v[160:163], v[200:203], v[84:87]
	v_mfma_f32_16x16x32_bf16 v[92:95], v[164:167], v[200:203], v[92:95]
	v_mfma_f32_16x16x32_bf16 v[20:23], v[168:171], v[200:203], v[20:23]
	v_mfma_f32_16x16x32_bf16 v[28:31], v[172:175], v[200:203], v[28:31]
	s_waitcnt lgkmcnt(1)
	v_mfma_f32_16x16x32_bf16 v[64:67], v[160:163], v[204:207], v[64:67]
	v_mfma_f32_16x16x32_bf16 v[72:75], v[164:167], v[204:207], v[72:75]
	v_mfma_f32_16x16x32_bf16 v[0:3], v[168:171], v[204:207], v[0:3]
	v_mfma_f32_16x16x32_bf16 v[8:11], v[172:175], v[204:207], v[8:11]
	s_waitcnt lgkmcnt(0)
	v_mfma_f32_16x16x32_bf16 v[68:71], v[160:163], v[242:245], v[68:71]
	v_mfma_f32_16x16x32_bf16 v[76:79], v[164:167], v[242:245], v[76:79]
	v_mfma_f32_16x16x32_bf16 v[4:7], v[168:171], v[242:245], v[4:7]
	v_mfma_f32_16x16x32_bf16 v[12:15], v[172:175], v[242:245], v[12:15]
	s_waitcnt vmcnt(0)
	s_barrier
	ds_read_b128 v[196:199], v246 offset:0
	ds_read_b128 v[200:203], v246 offset:1024
	ds_read_b128 v[204:207], v246 offset:2048
	ds_read_b128 v[242:245], v246 offset:3072
	s_waitcnt lgkmcnt(3)
	v_mfma_f32_16x16x32_bf16 v[112:115], v[128:131], v[196:199], v[112:115]
	v_mfma_f32_16x16x32_bf16 v[120:123], v[132:135], v[196:199], v[120:123]
	v_mfma_f32_16x16x32_bf16 v[48:51], v[136:139], v[196:199], v[48:51]
	v_mfma_f32_16x16x32_bf16 v[56:59], v[140:143], v[196:199], v[56:59]
	ds_read_b128 v[196:199], v246 offset:4096
	s_waitcnt lgkmcnt(3)
	v_mfma_f32_16x16x32_bf16 v[116:119], v[128:131], v[200:203], v[116:119]
	v_mfma_f32_16x16x32_bf16 v[124:127], v[132:135], v[200:203], v[124:127]
	v_mfma_f32_16x16x32_bf16 v[52:55], v[136:139], v[200:203], v[52:55]
	v_mfma_f32_16x16x32_bf16 v[60:63], v[140:143], v[200:203], v[60:63]
	ds_read_b128 v[200:203], v246 offset:5120
	s_waitcnt lgkmcnt(3)
	v_mfma_f32_16x16x32_bf16 v[96:99], v[128:131], v[204:207], v[96:99]
	v_mfma_f32_16x16x32_bf16 v[104:107], v[132:135], v[204:207], v[104:107]
	v_mfma_f32_16x16x32_bf16 v[32:35], v[136:139], v[204:207], v[32:35]
	v_mfma_f32_16x16x32_bf16 v[40:43], v[140:143], v[204:207], v[40:43]
	ds_read_b128 v[204:207], v246 offset:6144
	s_waitcnt lgkmcnt(3)
	v_mfma_f32_16x16x32_bf16 v[100:103], v[128:131], v[242:245], v[100:103]
	v_mfma_f32_16x16x32_bf16 v[108:111], v[132:135], v[242:245], v[108:111]
	v_mfma_f32_16x16x32_bf16 v[36:39], v[136:139], v[242:245], v[36:39]
	v_mfma_f32_16x16x32_bf16 v[44:47], v[140:143], v[242:245], v[44:47]
	ds_read_b128 v[242:245], v246 offset:7168
	v_permlane16_swap_b32_e32 v112, v116
	v_permlane16_swap_b32_e32 v113, v117
	v_permlane16_swap_b32_e32 v114, v118
	v_permlane16_swap_b32_e32 v115, v119
	v_permlane16_swap_b32_e32 v120, v124
	v_permlane16_swap_b32_e32 v121, v125
	v_permlane16_swap_b32_e32 v122, v126
	v_permlane16_swap_b32_e32 v123, v127
	v_permlane16_swap_b32_e32 v48, v52
	v_permlane16_swap_b32_e32 v49, v53
	v_permlane16_swap_b32_e32 v50, v54
	v_permlane16_swap_b32_e32 v51, v55
	v_permlane16_swap_b32_e32 v56, v60
	v_permlane16_swap_b32_e32 v57, v61
	v_permlane16_swap_b32_e32 v58, v62
	v_permlane16_swap_b32_e32 v59, v63
	v_permlane32_swap_b32_e32 v112, v116
	v_permlane32_swap_b32_e32 v113, v117
	v_permlane32_swap_b32_e32 v114, v118
	v_permlane32_swap_b32_e32 v115, v119
	v_permlane32_swap_b32_e32 v120, v124
	v_permlane32_swap_b32_e32 v121, v125
	v_permlane32_swap_b32_e32 v122, v126
	v_permlane32_swap_b32_e32 v123, v127
	v_permlane32_swap_b32_e32 v48, v52
	v_permlane32_swap_b32_e32 v49, v53
	v_permlane32_swap_b32_e32 v50, v54
	v_permlane32_swap_b32_e32 v51, v55
	v_permlane32_swap_b32_e32 v56, v60
	v_permlane32_swap_b32_e32 v57, v61
	v_permlane32_swap_b32_e32 v58, v62
	v_permlane32_swap_b32_e32 v59, v63
	s_waitcnt lgkmcnt(3)
	v_mfma_f32_16x16x32_bf16 v[80:83], v[128:131], v[196:199], v[80:83]
	v_mfma_f32_16x16x32_bf16 v[88:91], v[132:135], v[196:199], v[88:91]
	v_mfma_f32_16x16x32_bf16 v[16:19], v[136:139], v[196:199], v[16:19]
	v_mfma_f32_16x16x32_bf16 v[24:27], v[140:143], v[196:199], v[24:27]
	s_waitcnt lgkmcnt(2)
	v_mfma_f32_16x16x32_bf16 v[84:87], v[128:131], v[200:203], v[84:87]
	v_mfma_f32_16x16x32_bf16 v[92:95], v[132:135], v[200:203], v[92:95]
	v_mfma_f32_16x16x32_bf16 v[20:23], v[136:139], v[200:203], v[20:23]
	v_mfma_f32_16x16x32_bf16 v[28:31], v[140:143], v[200:203], v[28:31]
	v_permlane16_swap_b32_e32 v96, v100
	v_permlane16_swap_b32_e32 v97, v101
	v_permlane16_swap_b32_e32 v98, v102
	v_permlane16_swap_b32_e32 v99, v103
	v_permlane16_swap_b32_e32 v104, v108
	v_permlane16_swap_b32_e32 v105, v109
	v_permlane16_swap_b32_e32 v106, v110
	v_permlane16_swap_b32_e32 v107, v111
	v_permlane16_swap_b32_e32 v32, v36
	v_permlane16_swap_b32_e32 v33, v37
	v_permlane16_swap_b32_e32 v34, v38
	v_permlane16_swap_b32_e32 v35, v39
	v_permlane16_swap_b32_e32 v40, v44
	v_permlane16_swap_b32_e32 v41, v45
	v_permlane16_swap_b32_e32 v42, v46
	v_permlane16_swap_b32_e32 v43, v47
	v_permlane32_swap_b32_e32 v96, v100
	v_permlane32_swap_b32_e32 v97, v101
	v_permlane32_swap_b32_e32 v98, v102
	v_permlane32_swap_b32_e32 v99, v103
	v_permlane32_swap_b32_e32 v104, v108
	v_permlane32_swap_b32_e32 v105, v109
	v_permlane32_swap_b32_e32 v106, v110
	v_permlane32_swap_b32_e32 v107, v111
	v_permlane32_swap_b32_e32 v32, v36
	v_permlane32_swap_b32_e32 v33, v37
	v_permlane32_swap_b32_e32 v34, v38
	v_permlane32_swap_b32_e32 v35, v39
	v_permlane32_swap_b32_e32 v40, v44
	v_permlane32_swap_b32_e32 v41, v45
	v_permlane32_swap_b32_e32 v42, v46
	v_permlane32_swap_b32_e32 v43, v47
	s_waitcnt lgkmcnt(1)
	v_mfma_f32_16x16x32_bf16 v[64:67], v[128:131], v[204:207], v[64:67]
	v_mfma_f32_16x16x32_bf16 v[72:75], v[132:135], v[204:207], v[72:75]
	v_mfma_f32_16x16x32_bf16 v[0:3], v[136:139], v[204:207], v[0:3]
	v_mfma_f32_16x16x32_bf16 v[8:11], v[140:143], v[204:207], v[8:11]
	s_waitcnt lgkmcnt(0)
	v_mfma_f32_16x16x32_bf16 v[68:71], v[128:131], v[242:245], v[68:71]
	v_mfma_f32_16x16x32_bf16 v[76:79], v[132:135], v[242:245], v[76:79]
	v_mfma_f32_16x16x32_bf16 v[4:7], v[136:139], v[242:245], v[4:7]
	v_mfma_f32_16x16x32_bf16 v[12:15], v[140:143], v[242:245], v[12:15]
	v_permlane16_swap_b32_e32 v80, v84
	v_permlane16_swap_b32_e32 v81, v85
	v_permlane16_swap_b32_e32 v82, v86
	v_permlane16_swap_b32_e32 v83, v87
	v_permlane16_swap_b32_e32 v88, v92
	v_permlane16_swap_b32_e32 v89, v93
	v_permlane16_swap_b32_e32 v90, v94
	v_permlane16_swap_b32_e32 v91, v95
	v_permlane16_swap_b32_e32 v16, v20
	v_permlane16_swap_b32_e32 v17, v21
	v_permlane16_swap_b32_e32 v18, v22
	v_permlane16_swap_b32_e32 v19, v23
	v_permlane16_swap_b32_e32 v24, v28
	v_permlane16_swap_b32_e32 v25, v29
	v_permlane16_swap_b32_e32 v26, v30
	v_permlane16_swap_b32_e32 v27, v31
	v_permlane32_swap_b32_e32 v80, v84
	v_permlane32_swap_b32_e32 v81, v85
	v_permlane32_swap_b32_e32 v82, v86
	v_permlane32_swap_b32_e32 v83, v87
	v_permlane32_swap_b32_e32 v88, v92
	v_permlane32_swap_b32_e32 v89, v93
	v_permlane32_swap_b32_e32 v90, v94
	v_permlane32_swap_b32_e32 v91, v95
	v_permlane32_swap_b32_e32 v16, v20
	v_permlane32_swap_b32_e32 v17, v21
	v_permlane32_swap_b32_e32 v18, v22
	v_permlane32_swap_b32_e32 v19, v23
	v_permlane32_swap_b32_e32 v24, v28
	v_permlane32_swap_b32_e32 v25, v29
	v_permlane32_swap_b32_e32 v26, v30
	v_permlane32_swap_b32_e32 v27, v31
	s_barrier
	s_nop 7
	v_permlane16_swap_b32_e32 v64, v68
	v_permlane16_swap_b32_e32 v65, v69
	v_permlane16_swap_b32_e32 v66, v70
	v_permlane16_swap_b32_e32 v67, v71
	v_permlane16_swap_b32_e32 v72, v76
	v_permlane16_swap_b32_e32 v73, v77
	v_permlane16_swap_b32_e32 v74, v78
	v_permlane16_swap_b32_e32 v75, v79
	v_permlane16_swap_b32_e32 v0, v4
	v_permlane16_swap_b32_e32 v1, v5
	v_permlane16_swap_b32_e32 v2, v6
	v_permlane16_swap_b32_e32 v3, v7
	v_permlane16_swap_b32_e32 v8, v12
	v_permlane16_swap_b32_e32 v9, v13
	v_permlane16_swap_b32_e32 v10, v14
	v_permlane16_swap_b32_e32 v11, v15
	v_permlane32_swap_b32_e32 v64, v68
	v_permlane32_swap_b32_e32 v65, v69
	v_permlane32_swap_b32_e32 v66, v70
	v_permlane32_swap_b32_e32 v67, v71
	v_permlane32_swap_b32_e32 v72, v76
	v_permlane32_swap_b32_e32 v73, v77
	v_permlane32_swap_b32_e32 v74, v78
	v_permlane32_swap_b32_e32 v75, v79
	v_permlane32_swap_b32_e32 v0, v4
	v_permlane32_swap_b32_e32 v1, v5
	v_permlane32_swap_b32_e32 v2, v6
	v_permlane32_swap_b32_e32 v3, v7
	v_permlane32_swap_b32_e32 v8, v12
	v_permlane32_swap_b32_e32 v9, v13
	v_permlane32_swap_b32_e32 v10, v14
	v_permlane32_swap_b32_e32 v11, v15
	s_waitcnt vmcnt(0)
	s_movk_i32 s8, 0x2400
	s_waitcnt vmcnt(0)
	v_and_b32_e32 v132, 0xffffffc0, v181
	v_mul_lo_u32 v129, v237, s8
	v_lshlrev_b32_e32 v130, 2, v238
	v_lshl_add_u32 v156, s7, 8, v132
	v_mul_u32_u24_e32 v132, 0x110, v183
	v_or_b32_e32 v131, v129, v130
	v_lshlrev_b32_e32 v132, 2, v132
	v_add_u32_e32 v131, v131, v132
	v_add3_u32 v132, v129, v132, v130
	v_readlane_b32 s8, v253, 36
	v_lshlrev_b32_e32 v128, 2, v181
	v_add_u32_e32 v133, 0x800, v131
	v_add_u32_e32 v134, 0x800, v132
	v_lshrrev_b32_e32 v155, 4, v239
	v_readlane_b32 s12, v253, 40
	v_readlane_b32 s13, v253, 41
	v_readlane_b32 s14, v253, 42
	v_readlane_b32 s15, v253, 43
	v_readlane_b32 s16, v253, 44
	v_readlane_b32 s17, v253, 45
	v_readlane_b32 s18, v253, 46
	v_readlane_b32 s19, v253, 47
	v_and_b32_e32 v128, 60, v128
	ds_write2_b32 v131, v112, v113 offset1:68
	ds_write2_b32 v132, v96, v97 offset0:32 offset1:100
	ds_write2_b32 v131, v114, v115 offset0:136 offset1:204
	ds_write2_b32 v132, v98, v99 offset0:168 offset1:236
	ds_write2_b32 v133, v116, v117 offset0:32 offset1:100
	ds_write2_b32 v134, v100, v101 offset0:64 offset1:132
	ds_write2_b32 v133, v118, v119 offset0:168 offset1:236
	v_or_b32_e32 v100, v156, v155
	v_readlane_b32 s20, v253, 48
	v_readlane_b32 s21, v253, 49
	v_readlane_b32 s22, v253, 50
	v_readlane_b32 s23, v253, 51
	s_mov_b64 s[12:13], s[16:17]
	v_lshl_or_b32 v144, v128, 2, v129
	v_lshl_or_b32 v128, s6, 7, v128
	s_movk_i32 s6, 0x110
	v_cmp_gt_i32_e32 vcc, s39, v100
	v_add_u32_e32 v96, 0xffff8000, v100
	v_ashrrev_i32_e32 v97, 31, v100
	s_mov_b64 s[14:15], s[18:19]
	v_mad_u32_u24 v130, v155, s6, v144
	v_cndmask_b32_e32 v97, 0, v97, vcc
	v_cndmask_b32_e32 v96, v96, v100, vcc
	v_mov_b32_e32 v144, s63
	v_mov_b32_e32 v145, s15
	v_mov_b32_e32 v146, s62
	v_mov_b32_e32 v147, s14
	v_min_i32_e32 v100, 0x8000, v100
	v_add_u32_e32 v135, 0xa00, v132
	v_add_u32_e32 v136, 0x1000, v131
	v_add_u32_e32 v137, 0x1000, v132
	v_add_u32_e32 v138, 0x1200, v131
	v_add_u32_e32 v139, 0x1200, v132
	v_add_u32_e32 v140, 0x1800, v131
	v_add_u32_e32 v141, 0x1800, v132
	v_add_u32_e32 v142, 0x1a00, v131
	v_add_u32_e32 v143, 0x1c00, v132
	v_ashrrev_i32_e32 v129, 31, v128
	v_cndmask_b32_e32 v99, v144, v145, vcc
	v_cndmask_b32_e32 v98, v146, v147, vcc
	v_lshlrev_b64 v[96:97], 12, v[96:97]
	v_ashrrev_i32_e32 v100, 12, v100
	ds_write2_b32 v135, v102, v103 offset0:72 offset1:140
	ds_write2_b32 v136, v120, v121 offset0:64 offset1:132
	ds_write2_b32 v137, v104, v105 offset0:96 offset1:164
	ds_write2_b32 v138, v122, v123 offset0:72 offset1:140
	ds_write2_b32 v139, v106, v107 offset0:104 offset1:172
	ds_write2_b32 v140, v124, v125 offset0:96 offset1:164
	ds_write2_b32 v141, v108, v109 offset0:128 offset1:196
	ds_write2_b32 v142, v126, v127 offset0:104 offset1:172
	ds_write2_b32 v143, v110, v111 offset0:8 offset1:76
	v_lshl_add_u64 v[98:99], v[98:99], 0, v[96:97]
	v_lshlrev_b64 v[96:97], 2, v[128:129]
	v_mul_hi_i32_i24_e32 v101, 0x6000, v100
	v_mul_i32_i24_e32 v100, 0x6000, v100
	s_waitcnt lgkmcnt(0)
	v_lshl_add_u64 v[98:99], v[98:99], 0, v[96:97]
	v_lshl_add_u64 v[100:101], s[0:1], 0, v[100:101]
	v_lshl_add_u64 v[100:101], v[100:101], 0, v[96:97]
	ds_read_b128 v[102:105], v130
	global_load_dwordx4 v[106:109], v[98:99], off
	global_load_dwordx4 v[110:113], v[100:101], off
	v_or_b32_e32 v148, 4, v155
	v_or_b32_e32 v149, 8, v155
	v_or_b32_e32 v150, 12, v155
	v_or_b32_e32 v151, 16, v155
	v_or_b32_e32 v152, 20, v155
	v_or_b32_e32 v153, 24, v155
	v_or_b32_e32 v154, 28, v155
	v_or_b32_e32 v157, v156, v154
	v_readlane_b32 s6, v254, 11
	s_add_i32 s2, s2, s6
	s_cmp_lt_i32 s2, s26
	v_readlane_b32 s9, v253, 37
	v_readlane_b32 s10, v253, 38
	v_readlane_b32 s11, v253, 39
	s_mov_b64 s[16:17], s[20:21]
	s_mov_b64 s[18:19], s[22:23]
	s_waitcnt vmcnt(0) lgkmcnt(0)
	v_pk_fma_f32 v[102:103], v[102:103], v[110:111], v[106:107]
	v_pk_fma_f32 v[104:105], v[104:105], v[112:113], v[108:109]
	v_or_b32_e32 v106, v156, v148
	global_store_dwordx4 v[98:99], v[102:105], off
	v_cmp_gt_i32_e32 vcc, s39, v106
	s_nop 0
	v_ashrrev_i32_e32 v102, 31, v106
	v_add_u32_e32 v104, 0xffff8000, v106
	v_cndmask_b32_e32 v103, 0, v102, vcc
	v_cndmask_b32_e32 v102, v104, v106, vcc
	v_cndmask_b32_e32 v105, v144, v145, vcc
	v_cndmask_b32_e32 v104, v146, v147, vcc
	v_lshlrev_b64 v[102:103], 12, v[102:103]
	v_lshl_add_u64 v[102:103], v[104:105], 0, v[102:103]
	v_min_i32_e32 v104, 0x8000, v106
	v_ashrrev_i32_e32 v104, 12, v104
	v_mul_hi_i32_i24_e32 v105, 0x6000, v104
	v_mul_i32_i24_e32 v104, 0x6000, v104
	v_lshl_add_u64 v[102:103], v[102:103], 0, v[96:97]
	v_lshl_add_u64 v[104:105], s[0:1], 0, v[104:105]
	v_lshl_add_u64 v[104:105], v[104:105], 0, v[96:97]
	ds_read_b128 v[106:109], v130 offset:1088
	global_load_dwordx4 v[110:113], v[102:103], off
	global_load_dwordx4 v[114:117], v[104:105], off
	s_waitcnt vmcnt(0) lgkmcnt(0)
	v_pk_fma_f32 v[106:107], v[106:107], v[114:115], v[110:111]
	v_pk_fma_f32 v[108:109], v[108:109], v[116:117], v[112:113]
	v_or_b32_e32 v110, v156, v149
	global_store_dwordx4 v[102:103], v[106:109], off
	v_cmp_gt_i32_e32 vcc, s39, v110
	s_nop 0
	v_ashrrev_i32_e32 v106, 31, v110
	v_add_u32_e32 v108, 0xffff8000, v110
	v_cndmask_b32_e32 v107, 0, v106, vcc
	v_cndmask_b32_e32 v106, v108, v110, vcc
	v_cndmask_b32_e32 v109, v144, v145, vcc
	v_cndmask_b32_e32 v108, v146, v147, vcc
	v_lshlrev_b64 v[106:107], 12, v[106:107]
	v_lshl_add_u64 v[106:107], v[108:109], 0, v[106:107]
	v_min_i32_e32 v108, 0x8000, v110
	v_ashrrev_i32_e32 v108, 12, v108
	v_mul_hi_i32_i24_e32 v109, 0x6000, v108
	v_mul_i32_i24_e32 v108, 0x6000, v108
	v_lshl_add_u64 v[106:107], v[106:107], 0, v[96:97]
	v_lshl_add_u64 v[108:109], s[0:1], 0, v[108:109]
	v_lshl_add_u64 v[108:109], v[108:109], 0, v[96:97]
	ds_read_b128 v[110:113], v130 offset:2176
	global_load_dwordx4 v[114:117], v[106:107], off
	global_load_dwordx4 v[118:121], v[108:109], off
	s_waitcnt vmcnt(0) lgkmcnt(0)
	v_pk_fma_f32 v[110:111], v[110:111], v[118:119], v[114:115]
	v_pk_fma_f32 v[112:113], v[112:113], v[120:121], v[116:117]
	v_or_b32_e32 v114, v156, v150
	global_store_dwordx4 v[106:107], v[110:113], off
	v_cmp_gt_i32_e32 vcc, s39, v114
	s_nop 0
	v_ashrrev_i32_e32 v110, 31, v114
	v_add_u32_e32 v112, 0xffff8000, v114
	v_cndmask_b32_e32 v111, 0, v110, vcc
	v_cndmask_b32_e32 v110, v112, v114, vcc
	v_cndmask_b32_e32 v113, v144, v145, vcc
	v_cndmask_b32_e32 v112, v146, v147, vcc
	v_lshlrev_b64 v[110:111], 12, v[110:111]
	v_lshl_add_u64 v[110:111], v[112:113], 0, v[110:111]
	v_min_i32_e32 v112, 0x8000, v114
	v_ashrrev_i32_e32 v112, 12, v112
	v_mul_hi_i32_i24_e32 v113, 0x6000, v112
	v_mul_i32_i24_e32 v112, 0x6000, v112
	v_lshl_add_u64 v[110:111], v[110:111], 0, v[96:97]
	v_lshl_add_u64 v[112:113], s[0:1], 0, v[112:113]
	v_lshl_add_u64 v[112:113], v[112:113], 0, v[96:97]
	ds_read_b128 v[114:117], v130 offset:3264
	global_load_dwordx4 v[118:121], v[110:111], off
	global_load_dwordx4 v[122:125], v[112:113], off
	s_waitcnt vmcnt(0) lgkmcnt(0)
	v_pk_fma_f32 v[114:115], v[114:115], v[122:123], v[118:119]
	v_pk_fma_f32 v[116:117], v[116:117], v[124:125], v[120:121]
	v_or_b32_e32 v118, v156, v151
	global_store_dwordx4 v[110:111], v[114:117], off
	v_cmp_gt_i32_e32 vcc, s39, v118
	s_nop 0
	v_ashrrev_i32_e32 v114, 31, v118
	v_add_u32_e32 v116, 0xffff8000, v118
	v_cndmask_b32_e32 v115, 0, v114, vcc
	v_cndmask_b32_e32 v114, v116, v118, vcc
	v_cndmask_b32_e32 v117, v144, v145, vcc
	v_cndmask_b32_e32 v116, v146, v147, vcc
	v_lshlrev_b64 v[114:115], 12, v[114:115]
	v_lshl_add_u64 v[114:115], v[116:117], 0, v[114:115]
	v_min_i32_e32 v116, 0x8000, v118
	v_ashrrev_i32_e32 v116, 12, v116
	v_mul_hi_i32_i24_e32 v117, 0x6000, v116
	v_mul_i32_i24_e32 v116, 0x6000, v116
	v_lshl_add_u64 v[114:115], v[114:115], 0, v[96:97]
	v_lshl_add_u64 v[116:117], s[0:1], 0, v[116:117]
	v_lshl_add_u64 v[116:117], v[116:117], 0, v[96:97]
	ds_read_b128 v[118:121], v130 offset:4352
	global_load_dwordx4 v[122:125], v[114:115], off
	global_load_dwordx4 v[126:129], v[116:117], off
	s_waitcnt vmcnt(0) lgkmcnt(0)
	v_pk_fma_f32 v[118:119], v[118:119], v[126:127], v[122:123]
	v_pk_fma_f32 v[120:121], v[120:121], v[128:129], v[124:125]
	v_or_b32_e32 v122, v156, v152
	global_store_dwordx4 v[114:115], v[118:121], off
	v_cmp_gt_i32_e32 vcc, s39, v122
	s_nop 0
	v_ashrrev_i32_e32 v118, 31, v122
	v_add_u32_e32 v120, 0xffff8000, v122
	v_cndmask_b32_e32 v119, 0, v118, vcc
	v_cndmask_b32_e32 v118, v120, v122, vcc
	v_cndmask_b32_e32 v121, v144, v145, vcc
	v_cndmask_b32_e32 v120, v146, v147, vcc
	v_lshlrev_b64 v[118:119], 12, v[118:119]
	v_lshl_add_u64 v[118:119], v[120:121], 0, v[118:119]
	v_min_i32_e32 v120, 0x8000, v122
	v_ashrrev_i32_e32 v120, 12, v120
	v_mul_hi_i32_i24_e32 v121, 0x6000, v120
	v_mul_i32_i24_e32 v120, 0x6000, v120
	v_lshl_add_u64 v[118:119], v[118:119], 0, v[96:97]
	v_lshl_add_u64 v[120:121], s[0:1], 0, v[120:121]
	v_lshl_add_u64 v[120:121], v[120:121], 0, v[96:97]
	ds_read_b128 v[122:125], v130 offset:5440
	global_load_dwordx4 v[126:129], v[118:119], off
	global_load_dwordx4 v[158:161], v[120:121], off
	s_waitcnt vmcnt(0) lgkmcnt(0)
	v_pk_fma_f32 v[122:123], v[122:123], v[158:159], v[126:127]
	v_pk_fma_f32 v[124:125], v[124:125], v[160:161], v[128:129]
	v_or_b32_e32 v126, v156, v153
	global_store_dwordx4 v[118:119], v[122:125], off
	v_cmp_gt_i32_e32 vcc, s39, v126
	s_nop 0
	v_ashrrev_i32_e32 v122, 31, v126
	v_add_u32_e32 v124, 0xffff8000, v126
	v_cndmask_b32_e32 v123, 0, v122, vcc
	v_cndmask_b32_e32 v122, v124, v126, vcc
	v_cndmask_b32_e32 v125, v144, v145, vcc
	v_cndmask_b32_e32 v124, v146, v147, vcc
	v_lshlrev_b64 v[122:123], 12, v[122:123]
	v_lshl_add_u64 v[122:123], v[124:125], 0, v[122:123]
	v_min_i32_e32 v124, 0x8000, v126
	v_ashrrev_i32_e32 v124, 12, v124
	v_mul_hi_i32_i24_e32 v125, 0x6000, v124
	v_mul_i32_i24_e32 v124, 0x6000, v124
	v_lshl_add_u64 v[122:123], v[122:123], 0, v[96:97]
	v_lshl_add_u64 v[124:125], s[0:1], 0, v[124:125]
	v_lshl_add_u64 v[124:125], v[124:125], 0, v[96:97]
	ds_read_b128 v[126:129], v130 offset:6528
	global_load_dwordx4 v[158:161], v[122:123], off
	global_load_dwordx4 v[162:165], v[124:125], off
	v_cmp_gt_i32_e32 vcc, s39, v157
	s_waitcnt vmcnt(0) lgkmcnt(0)
	v_pk_fma_f32 v[126:127], v[126:127], v[162:163], v[158:159]
	v_pk_fma_f32 v[128:129], v[128:129], v[164:165], v[160:161]
	global_store_dwordx4 v[122:123], v[126:129], off
	ds_read_b128 v[158:161], v130 offset:7616
	s_nop 0
	v_ashrrev_i32_e32 v126, 31, v157
	v_add_u32_e32 v128, 0xffff8000, v157
	v_cndmask_b32_e32 v127, 0, v126, vcc
	v_cndmask_b32_e32 v126, v128, v157, vcc
	v_cndmask_b32_e32 v129, v144, v145, vcc
	v_cndmask_b32_e32 v128, v146, v147, vcc
	v_lshlrev_b64 v[126:127], 12, v[126:127]
	v_lshl_add_u64 v[126:127], v[128:129], 0, v[126:127]
	v_min_i32_e32 v128, 0x8000, v157
	v_ashrrev_i32_e32 v128, 12, v128
	v_mul_hi_i32_i24_e32 v129, 0x6000, v128
	v_mul_i32_i24_e32 v128, 0x6000, v128
	v_lshl_add_u64 v[126:127], v[126:127], 0, v[96:97]
	v_lshl_add_u64 v[128:129], s[0:1], 0, v[128:129]
	v_lshl_add_u64 v[128:129], v[128:129], 0, v[96:97]
	global_load_dwordx4 v[162:165], v[126:127], off
	global_load_dwordx4 v[166:169], v[128:129], off
	s_waitcnt vmcnt(0) lgkmcnt(0)
	v_pk_fma_f32 v[158:159], v[158:159], v[166:167], v[162:163]
	v_pk_fma_f32 v[160:161], v[160:161], v[168:169], v[164:165]
	global_store_dwordx4 v[126:127], v[158:161], off
	s_waitcnt lgkmcnt(0)
	ds_write2_b32 v131, v80, v81 offset1:68
	ds_write2_b32 v132, v64, v65 offset0:32 offset1:100
	ds_write2_b32 v131, v82, v83 offset0:136 offset1:204
	ds_write2_b32 v132, v66, v67 offset0:168 offset1:236
	ds_write2_b32 v133, v84, v85 offset0:32 offset1:100
	ds_write2_b32 v134, v68, v69 offset0:64 offset1:132
	ds_write2_b32 v133, v86, v87 offset0:168 offset1:236
	ds_write2_b32 v135, v70, v71 offset0:72 offset1:140
	ds_write2_b32 v136, v88, v89 offset0:64 offset1:132
	ds_write2_b32 v137, v72, v73 offset0:96 offset1:164
	ds_write2_b32 v138, v90, v91 offset0:72 offset1:140
	ds_write2_b32 v139, v74, v75 offset0:104 offset1:172
	ds_write2_b32 v140, v92, v93 offset0:96 offset1:164
	ds_write2_b32 v141, v76, v77 offset0:128 offset1:196
	ds_write2_b32 v142, v94, v95 offset0:104 offset1:172
	ds_write2_b32 v143, v78, v79 offset0:8 offset1:76
	s_waitcnt lgkmcnt(0)
	ds_read_b128 v[64:67], v130
	global_load_dwordx4 v[68:71], v[98:99], off offset:256
	global_load_dwordx4 v[72:75], v[100:101], off offset:256
	s_waitcnt vmcnt(0) lgkmcnt(0)
	v_pk_fma_f32 v[64:65], v[64:65], v[72:73], v[68:69]
	v_pk_fma_f32 v[66:67], v[66:67], v[74:75], v[70:71]
	global_store_dwordx4 v[98:99], v[64:67], off offset:256
	ds_read_b128 v[64:67], v130 offset:1088
	global_load_dwordx4 v[68:71], v[102:103], off offset:256
	global_load_dwordx4 v[72:75], v[104:105], off offset:256
	s_waitcnt vmcnt(0) lgkmcnt(0)
	v_pk_fma_f32 v[64:65], v[64:65], v[72:73], v[68:69]
	v_pk_fma_f32 v[66:67], v[66:67], v[74:75], v[70:71]
	global_store_dwordx4 v[102:103], v[64:67], off offset:256
	ds_read_b128 v[64:67], v130 offset:2176
	global_load_dwordx4 v[68:71], v[106:107], off offset:256
	global_load_dwordx4 v[72:75], v[108:109], off offset:256
	s_waitcnt vmcnt(0) lgkmcnt(0)
	v_pk_fma_f32 v[64:65], v[64:65], v[72:73], v[68:69]
	v_pk_fma_f32 v[66:67], v[66:67], v[74:75], v[70:71]
	global_store_dwordx4 v[106:107], v[64:67], off offset:256
	ds_read_b128 v[64:67], v130 offset:3264
	global_load_dwordx4 v[68:71], v[110:111], off offset:256
	global_load_dwordx4 v[72:75], v[112:113], off offset:256
	s_waitcnt vmcnt(0) lgkmcnt(0)
	v_pk_fma_f32 v[64:65], v[64:65], v[72:73], v[68:69]
	v_pk_fma_f32 v[66:67], v[66:67], v[74:75], v[70:71]
	global_store_dwordx4 v[110:111], v[64:67], off offset:256
	ds_read_b128 v[64:67], v130 offset:4352
	global_load_dwordx4 v[68:71], v[114:115], off offset:256
	global_load_dwordx4 v[72:75], v[116:117], off offset:256
	s_waitcnt vmcnt(0) lgkmcnt(0)
	v_pk_fma_f32 v[64:65], v[64:65], v[72:73], v[68:69]
	v_pk_fma_f32 v[66:67], v[66:67], v[74:75], v[70:71]
	global_store_dwordx4 v[114:115], v[64:67], off offset:256
	ds_read_b128 v[64:67], v130 offset:5440
	global_load_dwordx4 v[68:71], v[118:119], off offset:256
	global_load_dwordx4 v[72:75], v[120:121], off offset:256
	s_waitcnt vmcnt(0) lgkmcnt(0)
	v_pk_fma_f32 v[64:65], v[64:65], v[72:73], v[68:69]
	v_pk_fma_f32 v[66:67], v[66:67], v[74:75], v[70:71]
	global_store_dwordx4 v[118:119], v[64:67], off offset:256
	ds_read_b128 v[64:67], v130 offset:6528
	global_load_dwordx4 v[68:71], v[122:123], off offset:256
	global_load_dwordx4 v[72:75], v[124:125], off offset:256
	s_waitcnt vmcnt(0) lgkmcnt(0)
	v_pk_fma_f32 v[64:65], v[64:65], v[72:73], v[68:69]
	v_pk_fma_f32 v[66:67], v[66:67], v[74:75], v[70:71]
	global_store_dwordx4 v[122:123], v[64:67], off offset:256
	ds_read_b128 v[64:67], v130 offset:7616
	global_load_dwordx4 v[68:71], v[126:127], off offset:256
	global_load_dwordx4 v[72:75], v[128:129], off offset:256
	s_waitcnt vmcnt(0) lgkmcnt(0)
	v_pk_fma_f32 v[64:65], v[64:65], v[72:73], v[68:69]
	v_pk_fma_f32 v[66:67], v[66:67], v[74:75], v[70:71]
	global_store_dwordx4 v[126:127], v[64:67], off offset:256
	s_waitcnt lgkmcnt(0)
	ds_write2_b32 v131, v48, v49 offset1:68
	ds_write2_b32 v132, v32, v33 offset0:32 offset1:100
	ds_write2_b32 v131, v50, v51 offset0:136 offset1:204
	ds_write2_b32 v132, v34, v35 offset0:168 offset1:236
	ds_write2_b32 v133, v52, v53 offset0:32 offset1:100
	ds_write2_b32 v134, v36, v37 offset0:64 offset1:132
	ds_write2_b32 v133, v54, v55 offset0:168 offset1:236
	ds_write2_b32 v135, v38, v39 offset0:72 offset1:140
	ds_write2_b32 v136, v56, v57 offset0:64 offset1:132
	ds_write2_b32 v137, v40, v41 offset0:96 offset1:164
	ds_write2_b32 v138, v58, v59 offset0:72 offset1:140
	ds_write2_b32 v139, v42, v43 offset0:104 offset1:172
	ds_write2_b32 v140, v60, v61 offset0:96 offset1:164
	ds_write2_b32 v141, v44, v45 offset0:128 offset1:196
	ds_write2_b32 v142, v62, v63 offset0:104 offset1:172
	ds_write2_b32 v143, v46, v47 offset0:8 offset1:76
	v_or_b32_e32 v64, 32, v156
	v_or_b32_e32 v36, v64, v155
	v_cmp_gt_i32_e32 vcc, s39, v36
	v_ashrrev_i32_e32 v32, 31, v36
	v_add_u32_e32 v34, 0xffff8000, v36
	v_cndmask_b32_e32 v33, 0, v32, vcc
	v_cndmask_b32_e32 v32, v34, v36, vcc
	v_cndmask_b32_e32 v35, v144, v145, vcc
	v_cndmask_b32_e32 v34, v146, v147, vcc
	v_lshlrev_b64 v[32:33], 12, v[32:33]
	v_lshl_add_u64 v[32:33], v[34:35], 0, v[32:33]
	v_min_i32_e32 v34, 0x8000, v36
	v_ashrrev_i32_e32 v34, 12, v34
	v_mul_hi_i32_i24_e32 v35, 0x6000, v34
	v_mul_i32_i24_e32 v34, 0x6000, v34
	s_waitcnt lgkmcnt(0)
	v_lshl_add_u64 v[32:33], v[32:33], 0, v[96:97]
	v_lshl_add_u64 v[34:35], s[0:1], 0, v[34:35]
	v_lshl_add_u64 v[34:35], v[34:35], 0, v[96:97]
	ds_read_b128 v[36:39], v130
	global_load_dwordx4 v[40:43], v[32:33], off
	global_load_dwordx4 v[44:47], v[34:35], off
	s_waitcnt vmcnt(0) lgkmcnt(0)
	v_pk_fma_f32 v[36:37], v[36:37], v[44:45], v[40:41]
	v_pk_fma_f32 v[38:39], v[38:39], v[46:47], v[42:43]
	v_or_b32_e32 v40, v64, v148
	global_store_dwordx4 v[32:33], v[36:39], off
	v_cmp_gt_i32_e32 vcc, s39, v40
	s_nop 0
	v_ashrrev_i32_e32 v36, 31, v40
	v_add_u32_e32 v38, 0xffff8000, v40
	v_cndmask_b32_e32 v37, 0, v36, vcc
	v_cndmask_b32_e32 v36, v38, v40, vcc
	v_cndmask_b32_e32 v39, v144, v145, vcc
	v_cndmask_b32_e32 v38, v146, v147, vcc
	v_lshlrev_b64 v[36:37], 12, v[36:37]
	v_lshl_add_u64 v[36:37], v[38:39], 0, v[36:37]
	v_min_i32_e32 v38, 0x8000, v40
	v_ashrrev_i32_e32 v38, 12, v38
	v_mul_hi_i32_i24_e32 v39, 0x6000, v38
	v_mul_i32_i24_e32 v38, 0x6000, v38
	v_lshl_add_u64 v[36:37], v[36:37], 0, v[96:97]
	v_lshl_add_u64 v[38:39], s[0:1], 0, v[38:39]
	v_lshl_add_u64 v[38:39], v[38:39], 0, v[96:97]
	ds_read_b128 v[40:43], v130 offset:1088
	global_load_dwordx4 v[44:47], v[36:37], off
	global_load_dwordx4 v[48:51], v[38:39], off
	s_waitcnt vmcnt(0) lgkmcnt(0)
	v_pk_fma_f32 v[40:41], v[40:41], v[48:49], v[44:45]
	v_pk_fma_f32 v[42:43], v[42:43], v[50:51], v[46:47]
	v_or_b32_e32 v44, v64, v149
	global_store_dwordx4 v[36:37], v[40:43], off
	v_cmp_gt_i32_e32 vcc, s39, v44
	s_nop 0
	v_ashrrev_i32_e32 v40, 31, v44
	v_add_u32_e32 v42, 0xffff8000, v44
	v_cndmask_b32_e32 v41, 0, v40, vcc
	v_cndmask_b32_e32 v40, v42, v44, vcc
	v_cndmask_b32_e32 v43, v144, v145, vcc
	v_cndmask_b32_e32 v42, v146, v147, vcc
	v_lshlrev_b64 v[40:41], 12, v[40:41]
	v_lshl_add_u64 v[40:41], v[42:43], 0, v[40:41]
	v_min_i32_e32 v42, 0x8000, v44
	v_ashrrev_i32_e32 v42, 12, v42
	v_mul_hi_i32_i24_e32 v43, 0x6000, v42
	v_mul_i32_i24_e32 v42, 0x6000, v42
	v_lshl_add_u64 v[40:41], v[40:41], 0, v[96:97]
	v_lshl_add_u64 v[42:43], s[0:1], 0, v[42:43]
	v_lshl_add_u64 v[42:43], v[42:43], 0, v[96:97]
	ds_read_b128 v[44:47], v130 offset:2176
	global_load_dwordx4 v[48:51], v[40:41], off
	global_load_dwordx4 v[52:55], v[42:43], off
	s_waitcnt vmcnt(0) lgkmcnt(0)
	v_pk_fma_f32 v[44:45], v[44:45], v[52:53], v[48:49]
	v_pk_fma_f32 v[46:47], v[46:47], v[54:55], v[50:51]
	v_or_b32_e32 v48, v64, v150
	global_store_dwordx4 v[40:41], v[44:47], off
	v_cmp_gt_i32_e32 vcc, s39, v48
	s_nop 0
	v_ashrrev_i32_e32 v44, 31, v48
	v_add_u32_e32 v46, 0xffff8000, v48
	v_cndmask_b32_e32 v45, 0, v44, vcc
	v_cndmask_b32_e32 v44, v46, v48, vcc
	v_cndmask_b32_e32 v47, v144, v145, vcc
	v_cndmask_b32_e32 v46, v146, v147, vcc
	v_lshlrev_b64 v[44:45], 12, v[44:45]
	v_lshl_add_u64 v[44:45], v[46:47], 0, v[44:45]
	v_min_i32_e32 v46, 0x8000, v48
	v_ashrrev_i32_e32 v46, 12, v46
	v_mul_hi_i32_i24_e32 v47, 0x6000, v46
	v_mul_i32_i24_e32 v46, 0x6000, v46
	v_lshl_add_u64 v[44:45], v[44:45], 0, v[96:97]
	v_lshl_add_u64 v[46:47], s[0:1], 0, v[46:47]
	v_lshl_add_u64 v[46:47], v[46:47], 0, v[96:97]
	ds_read_b128 v[48:51], v130 offset:3264
	global_load_dwordx4 v[52:55], v[44:45], off
	global_load_dwordx4 v[56:59], v[46:47], off
	s_waitcnt vmcnt(0) lgkmcnt(0)
	v_pk_fma_f32 v[48:49], v[48:49], v[56:57], v[52:53]
	v_pk_fma_f32 v[50:51], v[50:51], v[58:59], v[54:55]
	v_or_b32_e32 v52, v64, v151
	global_store_dwordx4 v[44:45], v[48:51], off
	v_cmp_gt_i32_e32 vcc, s39, v52
	s_nop 0
	v_ashrrev_i32_e32 v48, 31, v52
	v_add_u32_e32 v50, 0xffff8000, v52
	v_cndmask_b32_e32 v49, 0, v48, vcc
	v_cndmask_b32_e32 v48, v50, v52, vcc
	v_cndmask_b32_e32 v51, v144, v145, vcc
	v_cndmask_b32_e32 v50, v146, v147, vcc
	v_lshlrev_b64 v[48:49], 12, v[48:49]
	v_lshl_add_u64 v[48:49], v[50:51], 0, v[48:49]
	v_min_i32_e32 v50, 0x8000, v52
	v_ashrrev_i32_e32 v50, 12, v50
	v_mul_hi_i32_i24_e32 v51, 0x6000, v50
	v_mul_i32_i24_e32 v50, 0x6000, v50
	v_lshl_add_u64 v[48:49], v[48:49], 0, v[96:97]
	v_lshl_add_u64 v[50:51], s[0:1], 0, v[50:51]
	v_lshl_add_u64 v[50:51], v[50:51], 0, v[96:97]
	ds_read_b128 v[52:55], v130 offset:4352
	global_load_dwordx4 v[56:59], v[48:49], off
	global_load_dwordx4 v[60:63], v[50:51], off
	s_waitcnt vmcnt(0) lgkmcnt(0)
	v_pk_fma_f32 v[52:53], v[52:53], v[60:61], v[56:57]
	v_pk_fma_f32 v[54:55], v[54:55], v[62:63], v[58:59]
	v_or_b32_e32 v56, v64, v152
	global_store_dwordx4 v[48:49], v[52:55], off
	v_cmp_gt_i32_e32 vcc, s39, v56
	s_nop 0
	v_ashrrev_i32_e32 v52, 31, v56
	v_add_u32_e32 v54, 0xffff8000, v56
	v_cndmask_b32_e32 v53, 0, v52, vcc
	v_cndmask_b32_e32 v52, v54, v56, vcc
	v_cndmask_b32_e32 v55, v144, v145, vcc
	v_cndmask_b32_e32 v54, v146, v147, vcc
	v_lshlrev_b64 v[52:53], 12, v[52:53]
	v_lshl_add_u64 v[52:53], v[54:55], 0, v[52:53]
	v_min_i32_e32 v54, 0x8000, v56
	v_ashrrev_i32_e32 v54, 12, v54
	v_mul_hi_i32_i24_e32 v55, 0x6000, v54
	v_mul_i32_i24_e32 v54, 0x6000, v54
	v_lshl_add_u64 v[52:53], v[52:53], 0, v[96:97]
	v_lshl_add_u64 v[54:55], s[0:1], 0, v[54:55]
	v_lshl_add_u64 v[54:55], v[54:55], 0, v[96:97]
	ds_read_b128 v[56:59], v130 offset:5440
	global_load_dwordx4 v[60:63], v[52:53], off
	global_load_dwordx4 v[66:69], v[54:55], off
	s_waitcnt vmcnt(0) lgkmcnt(0)
	v_pk_fma_f32 v[56:57], v[56:57], v[66:67], v[60:61]
	v_pk_fma_f32 v[58:59], v[58:59], v[68:69], v[62:63]
	v_or_b32_e32 v60, v64, v153
	global_store_dwordx4 v[52:53], v[56:59], off
	v_cmp_gt_i32_e32 vcc, s39, v60
	v_or_b32_e32 v64, v64, v154
	v_ashrrev_i32_e32 v56, 31, v60
	v_add_u32_e32 v58, 0xffff8000, v60
	v_cndmask_b32_e32 v57, 0, v56, vcc
	v_cndmask_b32_e32 v56, v58, v60, vcc
	v_cndmask_b32_e32 v59, v144, v145, vcc
	v_cndmask_b32_e32 v58, v146, v147, vcc
	v_lshlrev_b64 v[56:57], 12, v[56:57]
	v_lshl_add_u64 v[56:57], v[58:59], 0, v[56:57]
	v_min_i32_e32 v58, 0x8000, v60
	v_ashrrev_i32_e32 v58, 12, v58
	v_mul_hi_i32_i24_e32 v59, 0x6000, v58
	v_mul_i32_i24_e32 v58, 0x6000, v58
	v_lshl_add_u64 v[56:57], v[56:57], 0, v[96:97]
	v_lshl_add_u64 v[58:59], s[0:1], 0, v[58:59]
	v_lshl_add_u64 v[58:59], v[58:59], 0, v[96:97]
	ds_read_b128 v[60:63], v130 offset:6528
	global_load_dwordx4 v[66:69], v[56:57], off
	global_load_dwordx4 v[70:73], v[58:59], off
	v_cmp_gt_i32_e32 vcc, s39, v64
	s_waitcnt vmcnt(0) lgkmcnt(0)
	v_pk_fma_f32 v[60:61], v[60:61], v[70:71], v[66:67]
	v_pk_fma_f32 v[62:63], v[62:63], v[72:73], v[68:69]
	global_store_dwordx4 v[56:57], v[60:63], off
	s_nop 1
	v_ashrrev_i32_e32 v60, 31, v64
	v_add_u32_e32 v62, 0xffff8000, v64
	v_cndmask_b32_e32 v61, 0, v60, vcc
	v_cndmask_b32_e32 v60, v62, v64, vcc
	v_cndmask_b32_e32 v63, v144, v145, vcc
	v_cndmask_b32_e32 v62, v146, v147, vcc
	v_lshlrev_b64 v[60:61], 12, v[60:61]
	v_lshl_add_u64 v[60:61], v[62:63], 0, v[60:61]
	v_min_i32_e32 v62, 0x8000, v64
	v_ashrrev_i32_e32 v62, 12, v62
	v_mul_hi_i32_i24_e32 v63, 0x6000, v62
	v_mul_i32_i24_e32 v62, 0x6000, v62
	v_lshl_add_u64 v[60:61], v[60:61], 0, v[96:97]
	v_lshl_add_u64 v[62:63], s[0:1], 0, v[62:63]
	v_lshl_add_u64 v[62:63], v[62:63], 0, v[96:97]
	ds_read_b128 v[64:67], v130 offset:7616
	global_load_dwordx4 v[68:71], v[60:61], off
	global_load_dwordx4 v[72:75], v[62:63], off
	s_waitcnt vmcnt(0) lgkmcnt(0)
	v_pk_fma_f32 v[64:65], v[64:65], v[72:73], v[68:69]
	v_pk_fma_f32 v[66:67], v[66:67], v[74:75], v[70:71]
	global_store_dwordx4 v[60:61], v[64:67], off
	s_waitcnt lgkmcnt(0)
	ds_write2_b32 v131, v16, v17 offset1:68
	ds_write2_b32 v132, v0, v1 offset0:32 offset1:100
	ds_write2_b32 v131, v18, v19 offset0:136 offset1:204
	ds_write2_b32 v132, v2, v3 offset0:168 offset1:236
	ds_write2_b32 v133, v20, v21 offset0:32 offset1:100
	ds_write2_b32 v134, v4, v5 offset0:64 offset1:132
	ds_write2_b32 v133, v22, v23 offset0:168 offset1:236
	ds_write2_b32 v135, v6, v7 offset0:72 offset1:140
	ds_write2_b32 v136, v24, v25 offset0:64 offset1:132
	ds_write2_b32 v137, v8, v9 offset0:96 offset1:164
	ds_write2_b32 v138, v26, v27 offset0:72 offset1:140
	ds_write2_b32 v139, v10, v11 offset0:104 offset1:172
	ds_write2_b32 v140, v28, v29 offset0:96 offset1:164
	ds_write2_b32 v141, v12, v13 offset0:128 offset1:196
	ds_write2_b32 v142, v30, v31 offset0:104 offset1:172
	ds_write2_b32 v143, v14, v15 offset0:8 offset1:76
	s_waitcnt lgkmcnt(0)
	ds_read_b128 v[0:3], v130
	global_load_dwordx4 v[4:7], v[32:33], off offset:256
	global_load_dwordx4 v[8:11], v[34:35], off offset:256
	s_waitcnt vmcnt(0) lgkmcnt(0)
	v_pk_fma_f32 v[0:1], v[0:1], v[8:9], v[4:5]
	v_pk_fma_f32 v[2:3], v[2:3], v[10:11], v[6:7]
	global_store_dwordx4 v[32:33], v[0:3], off offset:256
	ds_read_b128 v[0:3], v130 offset:1088
	global_load_dwordx4 v[4:7], v[36:37], off offset:256
	global_load_dwordx4 v[8:11], v[38:39], off offset:256
	s_waitcnt vmcnt(0) lgkmcnt(0)
	v_pk_fma_f32 v[0:1], v[0:1], v[8:9], v[4:5]
	v_pk_fma_f32 v[2:3], v[2:3], v[10:11], v[6:7]
	global_store_dwordx4 v[36:37], v[0:3], off offset:256
	ds_read_b128 v[0:3], v130 offset:2176
	global_load_dwordx4 v[4:7], v[40:41], off offset:256
	global_load_dwordx4 v[8:11], v[42:43], off offset:256
	s_waitcnt vmcnt(0) lgkmcnt(0)
	v_pk_fma_f32 v[0:1], v[0:1], v[8:9], v[4:5]
	v_pk_fma_f32 v[2:3], v[2:3], v[10:11], v[6:7]
	global_store_dwordx4 v[40:41], v[0:3], off offset:256
	ds_read_b128 v[0:3], v130 offset:3264
	global_load_dwordx4 v[4:7], v[44:45], off offset:256
	global_load_dwordx4 v[8:11], v[46:47], off offset:256
	s_waitcnt vmcnt(0) lgkmcnt(0)
	v_pk_fma_f32 v[0:1], v[0:1], v[8:9], v[4:5]
	v_pk_fma_f32 v[2:3], v[2:3], v[10:11], v[6:7]
	global_store_dwordx4 v[44:45], v[0:3], off offset:256
	ds_read_b128 v[0:3], v130 offset:4352
	global_load_dwordx4 v[4:7], v[48:49], off offset:256
	global_load_dwordx4 v[8:11], v[50:51], off offset:256
	s_waitcnt vmcnt(0) lgkmcnt(0)
	v_pk_fma_f32 v[0:1], v[0:1], v[8:9], v[4:5]
	v_pk_fma_f32 v[2:3], v[2:3], v[10:11], v[6:7]
	global_store_dwordx4 v[48:49], v[0:3], off offset:256
	ds_read_b128 v[0:3], v130 offset:5440
	global_load_dwordx4 v[4:7], v[52:53], off offset:256
	global_load_dwordx4 v[8:11], v[54:55], off offset:256
	s_waitcnt vmcnt(0) lgkmcnt(0)
	v_pk_fma_f32 v[0:1], v[0:1], v[8:9], v[4:5]
	v_pk_fma_f32 v[2:3], v[2:3], v[10:11], v[6:7]
	global_store_dwordx4 v[52:53], v[0:3], off offset:256
	ds_read_b128 v[0:3], v130 offset:6528
	global_load_dwordx4 v[4:7], v[56:57], off offset:256
	global_load_dwordx4 v[8:11], v[58:59], off offset:256
	s_waitcnt vmcnt(0) lgkmcnt(0)
	v_pk_fma_f32 v[0:1], v[0:1], v[8:9], v[4:5]
	v_pk_fma_f32 v[2:3], v[2:3], v[10:11], v[6:7]
	global_store_dwordx4 v[56:57], v[0:3], off offset:256
	ds_read_b128 v[0:3], v130 offset:7616
	global_load_dwordx4 v[4:7], v[60:61], off offset:256
	global_load_dwordx4 v[8:11], v[62:63], off offset:256
	s_waitcnt vmcnt(0) lgkmcnt(0)
	v_pk_fma_f32 v[0:1], v[0:1], v[8:9], v[4:5]
	v_pk_fma_f32 v[2:3], v[2:3], v[10:11], v[6:7]
	global_store_dwordx4 v[60:61], v[0:3], off offset:256
	s_waitcnt lgkmcnt(0)
	s_barrier
	s_cbranch_scc1 .LBB0_1086
